# added: first K-iteration peeled with SrcC=0 (no 128-mov accumulator zero-init per unit) on all 8 GEMM phases, on top of rstd-in-LDS
# speedup vs baseline: 1.0120x; 1.0102x over previous
; #define PG8_STAGE(bufoff, gbase, voff) do { _Pragma("unroll") for (int _i = 0; _i < 2; ++_i) \
;         __builtin_amdgcn_global_load_lds((const unsigned*)((const char*)(gbase) + (voff)[_i]), (LAS unsigned*)(lds + (bufoff) + ldsw + _i * 8192), 16, 0, 0); } while (0)
; #define PG8_LDA(dst, b, h) do { _Pragma("unroll") for (int m = 0; m < 4; ++m) _Pragma("unroll") for (int k = 0; k < 2; ++k) dst[m][k] = *(const LAS bf16x8*)(lds + PG8_SA(b, h) + aoff + m * 2048 + k * 1024); } while (0)
; #define PG8_LDB(dst, b, h) do { _Pragma("unroll") for (int n = 0; n < 2; ++n) _Pragma("unroll") for (int k = 0; k < 2; ++k) dst[n][k] = *(const LAS bf16x8*)(lds + PG8_SB(b, h) + boff + n * 2048 + k * 1024); } while (0)
; #define PG8_WAIT_L(n) asm volatile("s_waitcnt lgkmcnt(" #n ")" ::: "memory")
; template <class Epi>
; __device__ __forceinline__ void gemm_phase(LAS unsigned char* lds, const Gemm g, const StaticOrder& S, const Epi& E) {
;     ...
;         const bool has_next = S.next(ui + 1, nxt);
;         const char* nA = has_next ? (const char*)g.A + (size_t)nxt.pm * tstepA : cA; const char* nB = has_next ? (const char*)g.Bt + (size_t)nxt.pn * tstepB : cB;
;         for (int t = 0; t < nt; t += 2) {
;             const bool last = (t == nt - 2);
;             const char* a1 = cA + (size_t)(t + 1) * kstep;
;             const char* a2 = last ? nA : cA + (size_t)(t + 2) * kstep; const char* b2 = last ? nB : cB + (size_t)(t + 2) * kstep;
;             const char* a3 = a2 + kstep; const char* b3 = b2 + kstep;
;             if (last) E.pre(cur, wr, fr, epre);
;             PG8_LDB(B0, 0, 0); PG8_SCHED; PG8_LDA(At, 0, 0); PG8_STAGE(PG8_SA(1, 1), a1 + hstepA, voffA);
;             PG8_WAIT_L(8); PG8_BAR; PG8_WAIT_L(0); PG8_MMA(0, 0, At, B0); PG8_BAR; PG8_SCHED;
;             PG8_LDB(B1, 0, 1); PG8_STAGE(PG8_SB(0, 0), b2, voffB);
;             PG8_BAR; PG8_WAIT_L(0); PG8_MMA(0, 1, At, B1); PG8_BAR;
;             PG8_LDA(At, 0, 1); PG8_STAGE(PG8_SA(0, 0), a2, voffA);
;             PG8_BAR; PG8_WAIT_L(0); PG8_MMA(1, 0, At, B0); PG8_BAR; PG8_SCHED;
;     ...
;         for (int a = 0; a < 2; ++a)
; #pragma unroll
;             for (int b = 0; b < 2; ++b)
; #pragma unroll
;                 for (int m = 0; m < 4; ++m)
; #pragma unroll
;                     for (int n = 0; n < 2; ++n) acc[a][b][m][n] = (f32x4){0.f, 0.f, 0.f, 0.f};
;         cur = nxt; cA = nA; cB = nB; ++ui;
.LBB0_204:
	s_ashr_i32 s13, s12, 31
	v_cmp_lt_i64_e32 vcc, s[14:15], v[142:143]
	s_lshl_b64 s[14:15], s[12:13], 19
	s_add_u32 s14, s76, s14
	s_addc_u32 s15, s77, s15
	s_and_b64 s[16:17], vcc, exec
	s_cselect_b32 s13, s15, s21
	s_cselect_b32 s19, s14, s20
	s_ashr_i32 s11, s10, 31
	s_lshl_b64 s[16:17], s[10:11], 19
	s_add_u32 s16, s74, s16
	s_addc_u32 s17, s75, s17
	s_and_b64 s[24:25], vcc, exec
	s_cselect_b32 s11, s17, s23
	s_cselect_b32 s44, s16, s22
	s_add_u32 s20, s20, 0x40080
	s_addc_u32 s21, s21, 0
	s_add_u32 s45, s22, 0x100
	s_addc_u32 s46, s23, 0
	s_mov_b32 s47, -2
	s_waitcnt lgkmcnt(0)
	ds_read_b128 v[146:149], v170
	ds_read_b128 v[154:157], v170 offset:1024
	ds_read_b128 v[158:161], v170 offset:2048
	ds_read_b128 v[162:165], v170 offset:3072
	s_add_u32 s22, s20, 0xfffc0080
	s_addc_u32 s23, s21, -1
	s_cmp_eq_u32 s47, 12
	s_cselect_b32 s25, s13, s23
	s_cselect_b32 s24, s19, s22
	s_cselect_b32 s23, s11, s46
	s_cselect_b32 s22, s44, s45
	v_lshl_add_u64 v[150:151], s[20:21], 0, v[138:139]
	s_add_i32 m0, s30, 0xc000
	s_waitcnt vmcnt(0)
	ds_read_b128 v[174:177], v171
	ds_read_b128 v[178:181], v171 offset:1024
	ds_read_b128 v[182:185], v171 offset:2048
	ds_read_b128 v[186:189], v171 offset:3072
	ds_read_b128 v[190:193], v171 offset:4096
	ds_read_b128 v[194:197], v171 offset:5120
	ds_read_b128 v[198:201], v171 offset:6144
	ds_read_b128 v[202:205], v171 offset:7168
	global_load_lds_dwordx4 v[150:151], off
	v_lshl_add_u64 v[150:151], s[20:21], 0, v[140:141]
	s_add_i32 m0, s30, 0xe000
	s_nop 0
	global_load_lds_dwordx4 v[150:151], off
	s_waitcnt lgkmcnt(8)
	s_barrier
	s_waitcnt lgkmcnt(0)
	s_setprio 1
	s_waitcnt lgkmcnt(0)
	v_mfma_f32_16x16x32_bf16 v[76:79], v[146:149], v[174:177], 0
	v_mfma_f32_16x16x32_bf16 v[64:67], v[158:161], v[174:177], 0
	v_mfma_f32_16x16x32_bf16 v[60:63], v[146:149], v[182:185], 0
	v_mfma_f32_16x16x32_bf16 v[56:59], v[158:161], v[182:185], 0
	v_mfma_f32_16x16x32_bf16 v[48:51], v[146:149], v[190:193], 0
	v_mfma_f32_16x16x32_bf16 v[40:43], v[158:161], v[190:193], 0
	v_mfma_f32_16x16x32_bf16 v[36:39], v[146:149], v[198:201], 0
	v_mfma_f32_16x16x32_bf16 v[32:35], v[158:161], v[198:201], 0
	v_mfma_f32_16x16x32_bf16 v[76:79], v[154:157], v[178:181], v[76:79]
	v_mfma_f32_16x16x32_bf16 v[64:67], v[162:165], v[178:181], v[64:67]
	v_mfma_f32_16x16x32_bf16 v[60:63], v[154:157], v[186:189], v[60:63]
	v_mfma_f32_16x16x32_bf16 v[56:59], v[162:165], v[186:189], v[56:59]
	v_mfma_f32_16x16x32_bf16 v[48:51], v[154:157], v[194:197], v[48:51]
	v_mfma_f32_16x16x32_bf16 v[40:43], v[162:165], v[194:197], v[40:43]
	v_mfma_f32_16x16x32_bf16 v[36:39], v[154:157], v[202:205], v[36:39]
	v_mfma_f32_16x16x32_bf16 v[32:35], v[162:165], v[202:205], v[32:35]
	s_setprio 0
	s_barrier
	s_add_i32 s48, s39, s27
	v_lshl_add_u64 v[150:151], s[22:23], 0, v[132:133]
	s_mov_b32 m0, s48
	ds_read_b128 v[206:209], v172
	ds_read_b128 v[210:213], v172 offset:1024
	ds_read_b128 v[214:217], v172 offset:2048
	ds_read_b128 v[218:221], v172 offset:3072
	global_load_lds_dwordx4 v[150:151], off
	v_lshl_add_u64 v[166:167], s[22:23], 0, v[128:129]
	s_add_i32 m0, s48, 0x2000
	s_nop 0
	global_load_lds_dwordx4 v[166:167], off
	s_barrier
	s_waitcnt lgkmcnt(0)
	s_setprio 1
	s_waitcnt lgkmcnt(0)
	v_mfma_f32_16x16x32_bf16 v[124:127], v[206:209], v[174:177], 0
	v_mfma_f32_16x16x32_bf16 v[120:123], v[214:217], v[174:177], 0
	v_mfma_f32_16x16x32_bf16 v[116:119], v[206:209], v[182:185], 0
	v_mfma_f32_16x16x32_bf16 v[112:115], v[214:217], v[182:185], 0
	v_mfma_f32_16x16x32_bf16 v[108:111], v[206:209], v[190:193], 0
	v_mfma_f32_16x16x32_bf16 v[104:107], v[214:217], v[190:193], 0
	v_mfma_f32_16x16x32_bf16 v[100:103], v[206:209], v[198:201], 0
	v_mfma_f32_16x16x32_bf16 v[96:99], v[214:217], v[198:201], 0
	v_mfma_f32_16x16x32_bf16 v[124:127], v[210:213], v[178:181], v[124:127]
	v_mfma_f32_16x16x32_bf16 v[120:123], v[218:221], v[178:181], v[120:123]
	v_mfma_f32_16x16x32_bf16 v[116:119], v[210:213], v[186:189], v[116:119]
	v_mfma_f32_16x16x32_bf16 v[112:115], v[218:221], v[186:189], v[112:115]
	v_mfma_f32_16x16x32_bf16 v[108:111], v[210:213], v[194:197], v[108:111]
	v_mfma_f32_16x16x32_bf16 v[104:107], v[218:221], v[194:197], v[104:107]
	v_mfma_f32_16x16x32_bf16 v[100:103], v[210:213], v[202:205], v[100:103]
	v_mfma_f32_16x16x32_bf16 v[96:99], v[218:221], v[202:205], v[96:99]
	s_setprio 0
	s_mov_b32 m0, s30
	v_lshl_add_u64 v[222:223], s[24:25], 0, v[134:135]
	s_barrier
	ds_read_b128 v[174:177], v171 offset:16384
	ds_read_b128 v[178:181], v171 offset:17408
	ds_read_b128 v[182:185], v171 offset:18432
	ds_read_b128 v[186:189], v171 offset:19456
	ds_read_b128 v[190:193], v171 offset:20480
	ds_read_b128 v[194:197], v171 offset:21504
	ds_read_b128 v[198:201], v171 offset:22528
	ds_read_b128 v[202:205], v171 offset:23552
	global_load_lds_dwordx4 v[222:223], off
	v_lshl_add_u64 v[224:225], s[24:25], 0, v[130:131]
	s_mov_b32 m0, s31
	s_nop 0
	global_load_lds_dwordx4 v[224:225], off
	s_barrier
	s_waitcnt lgkmcnt(0)
	s_setprio 1
	s_waitcnt lgkmcnt(0)
	v_mfma_f32_16x16x32_bf16 v[28:31], v[146:149], v[174:177], 0
	v_mfma_f32_16x16x32_bf16 v[24:27], v[158:161], v[174:177], 0
	v_mfma_f32_16x16x32_bf16 v[20:23], v[146:149], v[182:185], 0
	v_mfma_f32_16x16x32_bf16 v[16:19], v[158:161], v[182:185], 0
	v_mfma_f32_16x16x32_bf16 v[12:15], v[146:149], v[190:193], 0
	v_mfma_f32_16x16x32_bf16 v[8:11], v[158:161], v[190:193], 0
	v_mfma_f32_16x16x32_bf16 v[4:7], v[146:149], v[198:201], 0
	v_mfma_f32_16x16x32_bf16 v[0:3], v[158:161], v[198:201], 0
	v_mfma_f32_16x16x32_bf16 v[28:31], v[154:157], v[178:181], v[28:31]
	v_mfma_f32_16x16x32_bf16 v[24:27], v[162:165], v[178:181], v[24:27]
	v_mfma_f32_16x16x32_bf16 v[20:23], v[154:157], v[186:189], v[20:23]
	v_mfma_f32_16x16x32_bf16 v[16:19], v[162:165], v[186:189], v[16:19]
	v_mfma_f32_16x16x32_bf16 v[12:15], v[154:157], v[194:197], v[12:15]
	v_mfma_f32_16x16x32_bf16 v[8:11], v[162:165], v[194:197], v[8:11]
	v_mfma_f32_16x16x32_bf16 v[4:7], v[154:157], v[202:205], v[4:7]
	v_mfma_f32_16x16x32_bf16 v[0:3], v[162:165], v[202:205], v[0:3]
	s_setprio 0
	s_barrier
; #define PG8_STAGE(bufoff, gbase, voff) do { _Pragma("unroll") for (int _i = 0; _i < 2; ++_i) \
;         __builtin_amdgcn_global_load_lds((const unsigned*)((const char*)(gbase) + (voff)[_i]), (LAS unsigned*)(lds + (bufoff) + ldsw + _i * 8192), 16, 0, 0); } while (0)
; #define PG8_LDA(dst, b, h) do { _Pragma("unroll") for (int m = 0; m < 4; ++m) _Pragma("unroll") for (int k = 0; k < 2; ++k) dst[m][k] = *(const LAS bf16x8*)(lds + PG8_SA(b, h) + aoff + m * 2048 + k * 1024); } while (0)
; #define PG8_LDB(dst, b, h) do { _Pragma("unroll") for (int n = 0; n < 2; ++n) _Pragma("unroll") for (int k = 0; k < 2; ++k) dst[n][k] = *(const LAS bf16x8*)(lds + PG8_SB(b, h) + boff + n * 2048 + k * 1024); } while (0)
; #define PG8_MMA(ai, bj, At, Bt) do { __builtin_amdgcn_s_setprio(1); _Pragma("unroll") for (int m = 0; m < 4; ++m) _Pragma("unroll") for (int n = 0; n < 2; ++n) _Pragma("unroll") for (int k = 0; k < 2; ++k) \
;         acc[ai][bj][m][n] = __builtin_amdgcn_mfma_f32_16x16x32_bf16(Bt[n][k], At[m][k], acc[ai][bj][m][n], 0, 0, 0); __builtin_amdgcn_s_setprio(0); } while (0)
; #define PG8_WAIT_V(n) asm volatile("s_waitcnt vmcnt(" #n ")" ::: "memory")
; #define PG8_WAIT_L(n) asm volatile("s_waitcnt lgkmcnt(" #n ")" ::: "memory")
; #define PG8_BAR __builtin_amdgcn_s_barrier()
; #define PG8_SCHED __builtin_amdgcn_sched_barrier(0)
; template <class Epi>
; __device__ __forceinline__ void gemm_phase(LAS unsigned char* lds, const Gemm g, const StaticOrder& S, const Epi& E) {
;     ...
;             PG8_STAGE(PG8_SB(0, 1), b2 + hstepB, voffB);
;             PG8_WAIT_V(6); PG8_BAR; PG8_MMA(1, 1, At, B1); PG8_BAR;
;             PG8_LDB(B0, 1, 0); PG8_SCHED; PG8_LDA(At, 1, 0); PG8_STAGE(PG8_SA(0, 1), a2 + hstepA, voffA);
;             PG8_WAIT_L(8); PG8_BAR; PG8_WAIT_L(0); PG8_MMA(0, 0, At, B0); PG8_BAR; PG8_SCHED;
;             PG8_LDB(B1, 1, 1); PG8_STAGE(PG8_SB(1, 0), b3, voffB);
	s_add_u32 s48, s22, 0x40000
	s_addc_u32 s49, s23, 0
	s_add_i32 s50, s40, s27
	v_lshl_add_u64 v[146:147], s[48:49], 0, v[132:133]
	s_mov_b32 m0, s50
	s_nop 0
	global_load_lds_dwordx4 v[146:147], off
	v_lshl_add_u64 v[146:147], s[48:49], 0, v[128:129]
	s_add_i32 m0, s50, 0x2000
	s_nop 0
	global_load_lds_dwordx4 v[146:147], off
	s_waitcnt vmcnt(6)
	s_barrier
	s_setprio 1
	v_mfma_f32_16x16x32_bf16 v[92:95], v[206:209], v[174:177], 0
	v_mfma_f32_16x16x32_bf16 v[88:91], v[214:217], v[174:177], 0
	v_mfma_f32_16x16x32_bf16 v[84:87], v[206:209], v[182:185], 0
	v_mfma_f32_16x16x32_bf16 v[80:83], v[214:217], v[182:185], 0
	v_mfma_f32_16x16x32_bf16 v[72:75], v[206:209], v[190:193], 0
	v_mfma_f32_16x16x32_bf16 v[68:71], v[214:217], v[190:193], 0
	v_mfma_f32_16x16x32_bf16 v[52:55], v[206:209], v[198:201], 0
	v_mfma_f32_16x16x32_bf16 v[44:47], v[214:217], v[198:201], 0
	v_mfma_f32_16x16x32_bf16 v[92:95], v[210:213], v[178:181], v[92:95]
	v_mfma_f32_16x16x32_bf16 v[88:91], v[218:221], v[178:181], v[88:91]
	v_mfma_f32_16x16x32_bf16 v[84:87], v[210:213], v[186:189], v[84:87]
	v_mfma_f32_16x16x32_bf16 v[80:83], v[218:221], v[186:189], v[80:83]
	v_mfma_f32_16x16x32_bf16 v[72:75], v[210:213], v[194:197], v[72:75]
	v_mfma_f32_16x16x32_bf16 v[68:71], v[218:221], v[194:197], v[68:71]
	v_mfma_f32_16x16x32_bf16 v[52:55], v[210:213], v[202:205], v[52:55]
	v_mfma_f32_16x16x32_bf16 v[44:47], v[218:221], v[202:205], v[44:47]
	s_setprio 0
	s_add_i32 s48, 0, 0x18000
	v_add_u32_e32 v162, s48, v168
	s_barrier
	ds_read_b128 v[146:149], v162
	ds_read_b128 v[154:157], v162 offset:1024
	ds_read_b128 v[158:161], v162 offset:2048
	ds_read_b128 v[162:165], v162 offset:3072
	s_add_u32 s24, s24, 0x40000
	s_addc_u32 s25, s25, 0
	s_mov_b32 m0, s33
	v_lshl_add_u64 v[206:207], s[24:25], 0, v[134:135]
	ds_read_b128 v[174:177], v171 offset:32768
	ds_read_b128 v[178:181], v171 offset:33792
	ds_read_b128 v[182:185], v171 offset:34816
	ds_read_b128 v[186:189], v171 offset:35840
	ds_read_b128 v[190:193], v171 offset:36864
	ds_read_b128 v[194:197], v171 offset:37888
	ds_read_b128 v[198:201], v171 offset:38912
	ds_read_b128 v[202:205], v171 offset:39936
	global_load_lds_dwordx4 v[206:207], off
	v_lshl_add_u64 v[206:207], s[24:25], 0, v[130:131]
	s_mov_b32 m0, s34
	s_nop 0
	global_load_lds_dwordx4 v[206:207], off
	s_waitcnt lgkmcnt(8)
	s_barrier
	s_waitcnt lgkmcnt(0)
	s_setprio 1
	s_waitcnt lgkmcnt(0)
	v_mfma_f32_16x16x32_bf16 v[76:79], v[146:149], v[174:177], v[76:79]
	v_mfma_f32_16x16x32_bf16 v[64:67], v[158:161], v[174:177], v[64:67]
	v_mfma_f32_16x16x32_bf16 v[60:63], v[146:149], v[182:185], v[60:63]
	v_mfma_f32_16x16x32_bf16 v[56:59], v[158:161], v[182:185], v[56:59]
	v_mfma_f32_16x16x32_bf16 v[48:51], v[146:149], v[190:193], v[48:51]
	v_mfma_f32_16x16x32_bf16 v[40:43], v[158:161], v[190:193], v[40:43]
	v_mfma_f32_16x16x32_bf16 v[36:39], v[146:149], v[198:201], v[36:39]
	v_mfma_f32_16x16x32_bf16 v[32:35], v[158:161], v[198:201], v[32:35]
	v_mfma_f32_16x16x32_bf16 v[76:79], v[154:157], v[178:181], v[76:79]
	v_mfma_f32_16x16x32_bf16 v[64:67], v[162:165], v[178:181], v[64:67]
	v_mfma_f32_16x16x32_bf16 v[60:63], v[154:157], v[186:189], v[60:63]
	v_mfma_f32_16x16x32_bf16 v[56:59], v[162:165], v[186:189], v[56:59]
	v_mfma_f32_16x16x32_bf16 v[48:51], v[154:157], v[194:197], v[48:51]
	v_mfma_f32_16x16x32_bf16 v[40:43], v[162:165], v[194:197], v[40:43]
	v_mfma_f32_16x16x32_bf16 v[36:39], v[154:157], v[202:205], v[36:39]
	v_mfma_f32_16x16x32_bf16 v[32:35], v[162:165], v[202:205], v[32:35]
	s_setprio 0
	s_barrier
	s_add_i32 s24, 0, 0x1c000
	s_add_i32 s25, s48, s27
	v_add_u32_e32 v218, s24, v168
	v_lshl_add_u64 v[150:151], v[150:151], 0, s[6:7]
	s_mov_b32 m0, s25
	ds_read_b128 v[206:209], v218
	ds_read_b128 v[210:213], v218 offset:1024
	ds_read_b128 v[214:217], v218 offset:2048
	ds_read_b128 v[218:221], v218 offset:3072
	global_load_lds_dwordx4 v[150:151], off
	v_lshl_add_u64 v[150:151], v[166:167], 0, s[6:7]
	s_add_i32 m0, s25, 0x2000
	s_nop 0
	global_load_lds_dwordx4 v[150:151], off
	s_barrier
; #define PG8_STAGE(bufoff, gbase, voff) do { _Pragma("unroll") for (int _i = 0; _i < 2; ++_i) \
;         __builtin_amdgcn_global_load_lds((const unsigned*)((const char*)(gbase) + (voff)[_i]), (LAS unsigned*)(lds + (bufoff) + ldsw + _i * 8192), 16, 0, 0); } while (0)
; #define PG8_LDA(dst, b, h) do { _Pragma("unroll") for (int m = 0; m < 4; ++m) _Pragma("unroll") for (int k = 0; k < 2; ++k) dst[m][k] = *(const LAS bf16x8*)(lds + PG8_SA(b, h) + aoff + m * 2048 + k * 1024); } while (0)
; #define PG8_MMA(ai, bj, At, Bt) do { __builtin_amdgcn_s_setprio(1); _Pragma("unroll") for (int m = 0; m < 4; ++m) _Pragma("unroll") for (int n = 0; n < 2; ++n) _Pragma("unroll") for (int k = 0; k < 2; ++k) \
;         acc[ai][bj][m][n] = __builtin_amdgcn_mfma_f32_16x16x32_bf16(Bt[n][k], At[m][k], acc[ai][bj][m][n], 0, 0, 0); __builtin_amdgcn_s_setprio(0); } while (0)
; #define PG8_WAIT_V(n) asm volatile("s_waitcnt vmcnt(" #n ")" ::: "memory")
; #define PG8_WAIT_L(n) asm volatile("s_waitcnt lgkmcnt(" #n ")" ::: "memory")
; #define PG8_BAR __builtin_amdgcn_s_barrier()
; #define PG8_SCHED __builtin_amdgcn_sched_barrier(0)
; template <class Epi>
; __device__ __forceinline__ void gemm_phase(LAS unsigned char* lds, const Gemm g, const StaticOrder& S, const Epi& E) {
;     ...
;             PG8_BAR; PG8_WAIT_L(0); PG8_MMA(0, 1, At, B1); PG8_BAR;
;             PG8_LDA(At, 1, 1); PG8_STAGE(PG8_SA(1, 0), a3, voffA);
;             PG8_BAR; PG8_WAIT_L(0); PG8_MMA(1, 0, At, B0); PG8_BAR; PG8_SCHED;
;             PG8_STAGE(PG8_SB(1, 1), b3 + hstepB, voffB);
;             PG8_WAIT_V(6); PG8_BAR; PG8_MMA(1, 1, At, B1); PG8_BAR;
	s_waitcnt lgkmcnt(0)
	s_setprio 1
	s_waitcnt lgkmcnt(0)
	v_mfma_f32_16x16x32_bf16 v[124:127], v[206:209], v[174:177], v[124:127]
	v_mfma_f32_16x16x32_bf16 v[120:123], v[214:217], v[174:177], v[120:123]
	v_mfma_f32_16x16x32_bf16 v[116:119], v[206:209], v[182:185], v[116:119]
	v_mfma_f32_16x16x32_bf16 v[112:115], v[214:217], v[182:185], v[112:115]
	v_mfma_f32_16x16x32_bf16 v[108:111], v[206:209], v[190:193], v[108:111]
	v_mfma_f32_16x16x32_bf16 v[104:107], v[214:217], v[190:193], v[104:107]
	v_mfma_f32_16x16x32_bf16 v[100:103], v[206:209], v[198:201], v[100:103]
	v_mfma_f32_16x16x32_bf16 v[96:99], v[214:217], v[198:201], v[96:99]
	v_mfma_f32_16x16x32_bf16 v[124:127], v[210:213], v[178:181], v[124:127]
	v_mfma_f32_16x16x32_bf16 v[120:123], v[218:221], v[178:181], v[120:123]
	v_mfma_f32_16x16x32_bf16 v[116:119], v[210:213], v[186:189], v[116:119]
	v_mfma_f32_16x16x32_bf16 v[112:115], v[218:221], v[186:189], v[112:115]
	v_mfma_f32_16x16x32_bf16 v[108:111], v[210:213], v[194:197], v[108:111]
	v_mfma_f32_16x16x32_bf16 v[104:107], v[218:221], v[194:197], v[104:107]
	v_mfma_f32_16x16x32_bf16 v[100:103], v[210:213], v[202:205], v[100:103]
	v_mfma_f32_16x16x32_bf16 v[96:99], v[218:221], v[202:205], v[96:99]
	s_setprio 0
	s_mov_b32 m0, s36
	v_lshl_add_u64 v[150:151], v[222:223], 0, s[6:7]
	s_barrier
	ds_read_b128 v[174:177], v171 offset:49152
	ds_read_b128 v[178:181], v171 offset:50176
	ds_read_b128 v[182:185], v171 offset:51200
	ds_read_b128 v[186:189], v171 offset:52224
	ds_read_b128 v[190:193], v171 offset:53248
	ds_read_b128 v[194:197], v171 offset:54272
	ds_read_b128 v[198:201], v171 offset:55296
	ds_read_b128 v[202:205], v171 offset:56320
	global_load_lds_dwordx4 v[150:151], off
	v_lshl_add_u64 v[150:151], v[224:225], 0, s[6:7]
	s_mov_b32 m0, s37
	s_nop 0
	global_load_lds_dwordx4 v[150:151], off
	s_barrier
	s_waitcnt lgkmcnt(0)
	s_setprio 1
	s_waitcnt lgkmcnt(0)
	v_mfma_f32_16x16x32_bf16 v[28:31], v[146:149], v[174:177], v[28:31]
	v_mfma_f32_16x16x32_bf16 v[24:27], v[158:161], v[174:177], v[24:27]
	v_mfma_f32_16x16x32_bf16 v[20:23], v[146:149], v[182:185], v[20:23]
	v_mfma_f32_16x16x32_bf16 v[16:19], v[158:161], v[182:185], v[16:19]
	v_mfma_f32_16x16x32_bf16 v[12:15], v[146:149], v[190:193], v[12:15]
	v_mfma_f32_16x16x32_bf16 v[8:11], v[158:161], v[190:193], v[8:11]
	v_mfma_f32_16x16x32_bf16 v[4:7], v[146:149], v[198:201], v[4:7]
	v_mfma_f32_16x16x32_bf16 v[0:3], v[158:161], v[198:201], v[0:3]
	v_mfma_f32_16x16x32_bf16 v[28:31], v[154:157], v[178:181], v[28:31]
	v_mfma_f32_16x16x32_bf16 v[24:27], v[162:165], v[178:181], v[24:27]
	v_mfma_f32_16x16x32_bf16 v[20:23], v[154:157], v[186:189], v[20:23]
	v_mfma_f32_16x16x32_bf16 v[16:19], v[162:165], v[186:189], v[16:19]
	v_mfma_f32_16x16x32_bf16 v[12:15], v[154:157], v[194:197], v[12:15]
	v_mfma_f32_16x16x32_bf16 v[8:11], v[162:165], v[194:197], v[8:11]
	v_mfma_f32_16x16x32_bf16 v[4:7], v[154:157], v[202:205], v[4:7]
	v_mfma_f32_16x16x32_bf16 v[0:3], v[162:165], v[202:205], v[0:3]
	s_setprio 0
	s_barrier
	s_add_u32 s22, s22, 0x40080
	s_addc_u32 s23, s23, 0
	s_add_i32 s24, s24, s27
	v_lshl_add_u64 v[146:147], s[22:23], 0, v[132:133]
	s_mov_b32 m0, s24
	s_nop 0
	global_load_lds_dwordx4 v[146:147], off
	v_lshl_add_u64 v[146:147], s[22:23], 0, v[128:129]
	s_add_i32 m0, s24, 0x2000
	s_nop 0
	global_load_lds_dwordx4 v[146:147], off
	s_waitcnt vmcnt(6)
	s_barrier
	s_setprio 1
	v_mfma_f32_16x16x32_bf16 v[92:95], v[206:209], v[174:177], v[92:95]
	v_mfma_f32_16x16x32_bf16 v[88:91], v[214:217], v[174:177], v[88:91]
	v_mfma_f32_16x16x32_bf16 v[84:87], v[206:209], v[182:185], v[84:87]
	v_mfma_f32_16x16x32_bf16 v[80:83], v[214:217], v[182:185], v[80:83]
	v_mfma_f32_16x16x32_bf16 v[72:75], v[206:209], v[190:193], v[72:75]
	v_mfma_f32_16x16x32_bf16 v[68:71], v[214:217], v[190:193], v[68:71]
	v_mfma_f32_16x16x32_bf16 v[52:55], v[206:209], v[198:201], v[52:55]
	v_mfma_f32_16x16x32_bf16 v[44:47], v[214:217], v[198:201], v[44:47]
	v_mfma_f32_16x16x32_bf16 v[92:95], v[210:213], v[178:181], v[92:95]
	v_mfma_f32_16x16x32_bf16 v[88:91], v[218:221], v[178:181], v[88:91]
	v_mfma_f32_16x16x32_bf16 v[84:87], v[210:213], v[186:189], v[84:87]
	v_mfma_f32_16x16x32_bf16 v[80:83], v[218:221], v[186:189], v[80:83]
	v_mfma_f32_16x16x32_bf16 v[72:75], v[210:213], v[194:197], v[72:75]
	v_mfma_f32_16x16x32_bf16 v[68:71], v[218:221], v[194:197], v[68:71]
	v_mfma_f32_16x16x32_bf16 v[52:55], v[210:213], v[202:205], v[52:55]
	v_mfma_f32_16x16x32_bf16 v[44:47], v[218:221], v[202:205], v[44:47]
	s_setprio 0
	s_add_i32 s47, s47, 2
	s_add_u32 s20, s20, 0x100
	s_addc_u32 s21, s21, 0
	s_add_u32 s45, s45, 0x100
	s_addc_u32 s46, s46, 0
	s_cmp_gt_u32 s47, 13
	s_barrier

; #define PG8_STAGE(bufoff, gbase, voff) do { _Pragma("unroll") for (int _i = 0; _i < 2; ++_i) \
;         __builtin_amdgcn_global_load_lds((const unsigned*)((const char*)(gbase) + (voff)[_i]), (LAS unsigned*)(lds + (bufoff) + ldsw + _i * 8192), 16, 0, 0); } while (0)
; #define PG8_LDA(dst, b, h) do { _Pragma("unroll") for (int m = 0; m < 4; ++m) _Pragma("unroll") for (int k = 0; k < 2; ++k) dst[m][k] = *(const LAS bf16x8*)(lds + PG8_SA(b, h) + aoff + m * 2048 + k * 1024); } while (0)
; #define PG8_LDB(dst, b, h) do { _Pragma("unroll") for (int n = 0; n < 2; ++n) _Pragma("unroll") for (int k = 0; k < 2; ++k) dst[n][k] = *(const LAS bf16x8*)(lds + PG8_SB(b, h) + boff + n * 2048 + k * 1024); } while (0)
; #define PG8_WAIT_L(n) asm volatile("s_waitcnt lgkmcnt(" #n ")" ::: "memory")
; template <class Epi>
; __device__ __forceinline__ void gemm_phase(LAS unsigned char* lds, const Gemm g, const StaticOrder& S, const Epi& E) {
;     ...
;         const bool has_next = S.next(ui + 1, nxt);
;         const char* nA = has_next ? (const char*)g.A + (size_t)nxt.pm * tstepA : cA; const char* nB = has_next ? (const char*)g.Bt + (size_t)nxt.pn * tstepB : cB;
;         for (int t = 0; t < nt; t += 2) {
;             const bool last = (t == nt - 2);
;             const char* a1 = cA + (size_t)(t + 1) * kstep;
;             const char* a2 = last ? nA : cA + (size_t)(t + 2) * kstep; const char* b2 = last ? nB : cB + (size_t)(t + 2) * kstep;
;             const char* a3 = a2 + kstep; const char* b3 = b2 + kstep;
;             if (last) E.pre(cur, wr, fr, epre);
;             PG8_LDB(B0, 0, 0); PG8_SCHED; PG8_LDA(At, 0, 0); PG8_STAGE(PG8_SA(1, 1), a1 + hstepA, voffA);
;             PG8_WAIT_L(8); PG8_BAR; PG8_WAIT_L(0); PG8_MMA(0, 0, At, B0); PG8_BAR; PG8_SCHED;
;             PG8_LDB(B1, 0, 1); PG8_STAGE(PG8_SB(0, 0), b2, voffB);
;             PG8_BAR; PG8_WAIT_L(0); PG8_MMA(0, 1, At, B1); PG8_BAR;
;             PG8_LDA(At, 0, 1); PG8_STAGE(PG8_SA(0, 0), a2, voffA);
;             PG8_BAR; PG8_WAIT_L(0); PG8_MMA(1, 0, At, B0); PG8_BAR; PG8_SCHED;
;     ...
;         for (int a = 0; a < 2; ++a)
; #pragma unroll
;             for (int b = 0; b < 2; ++b)
; #pragma unroll
;                 for (int m = 0; m < 4; ++m)
; #pragma unroll
;                     for (int n = 0; n < 2; ++n) acc[a][b][m][n] = (f32x4){0.f, 0.f, 0.f, 0.f};
;         cur = nxt; cA = nA; cB = nB; ++ui;
.LBB0_683:
	s_ashr_i32 s17, s16, 31
	s_lshl_b64 s[20:21], s[16:17], 20
	s_add_u32 s20, s29, s20
	s_addc_u32 s21, s30, s21
	s_and_b64 s[4:5], s[4:5], exec
	s_cselect_b32 s17, s21, s23
	s_cselect_b32 s45, s20, s22
	s_add_u32 s4, s24, 0x140080
	s_addc_u32 s5, s25, 0
	s_add_u32 s46, s22, 0x100
	s_addc_u32 s47, s23, 0
	s_mov_b32 s48, -2
	s_waitcnt lgkmcnt(0)
	ds_read_b128 v[128:131], v191
	ds_read_b128 v[132:135], v191 offset:1024
	ds_read_b128 v[136:139], v191 offset:2048
	ds_read_b128 v[140:143], v191 offset:3072
	s_add_u32 s22, s4, 0xffec0080
	s_addc_u32 s23, s5, -1
	s_cmp_eq_u32 s48, 28
	s_cselect_b32 s25, s19, s23
	s_cselect_b32 s24, s18, s22
	s_cselect_b32 s23, s17, s47
	s_cselect_b32 s22, s45, s46
	v_lshl_add_u64 v[186:187], s[4:5], 0, v[162:163]
	s_add_i32 m0, s11, 0xc000
	ds_read_b128 v[144:147], v192
	ds_read_b128 v[148:151], v192 offset:1024
	ds_read_b128 v[170:173], v192 offset:2048
	ds_read_b128 v[174:177], v192 offset:3072
	ds_read_b128 v[178:181], v192 offset:4096
	ds_read_b128 v[182:185], v192 offset:5120
	ds_read_b128 v[196:199], v192 offset:6144
	ds_read_b128 v[200:203], v192 offset:7168
	global_load_lds_dwordx4 v[186:187], off
	v_lshl_add_u64 v[186:187], s[4:5], 0, v[164:165]
	s_add_i32 m0, s11, 0xe000
	s_nop 0
	global_load_lds_dwordx4 v[186:187], off
	s_waitcnt lgkmcnt(8)
	s_barrier
	s_waitcnt lgkmcnt(0)
	s_setprio 1
	s_waitcnt lgkmcnt(0)
	v_mfma_f32_16x16x32_bf16 v[124:127], v[128:131], v[144:147], 0
	v_mfma_f32_16x16x32_bf16 v[120:123], v[136:139], v[144:147], 0
	v_mfma_f32_16x16x32_bf16 v[108:111], v[128:131], v[170:173], 0
	v_mfma_f32_16x16x32_bf16 v[104:107], v[136:139], v[170:173], 0
	v_mfma_f32_16x16x32_bf16 v[92:95], v[128:131], v[178:181], 0
	v_mfma_f32_16x16x32_bf16 v[88:91], v[136:139], v[178:181], 0
	v_mfma_f32_16x16x32_bf16 v[76:79], v[128:131], v[196:199], 0
	v_mfma_f32_16x16x32_bf16 v[72:75], v[136:139], v[196:199], 0
	v_mfma_f32_16x16x32_bf16 v[124:127], v[132:135], v[148:151], v[124:127]
	v_mfma_f32_16x16x32_bf16 v[120:123], v[140:143], v[148:151], v[120:123]
	v_mfma_f32_16x16x32_bf16 v[108:111], v[132:135], v[174:177], v[108:111]
	v_mfma_f32_16x16x32_bf16 v[104:107], v[140:143], v[174:177], v[104:107]
	v_mfma_f32_16x16x32_bf16 v[92:95], v[132:135], v[182:185], v[92:95]
	v_mfma_f32_16x16x32_bf16 v[88:91], v[140:143], v[182:185], v[88:91]
	v_mfma_f32_16x16x32_bf16 v[76:79], v[132:135], v[200:203], v[76:79]
	v_mfma_f32_16x16x32_bf16 v[72:75], v[140:143], v[200:203], v[72:75]
	s_setprio 0
	s_barrier
	s_add_i32 s49, s42, s31
	v_lshl_add_u64 v[186:187], s[22:23], 0, v[156:157]
	s_mov_b32 m0, s49
	ds_read_b128 v[204:207], v193
	ds_read_b128 v[208:211], v193 offset:1024
	ds_read_b128 v[212:215], v193 offset:2048
	ds_read_b128 v[216:219], v193 offset:3072
	global_load_lds_dwordx4 v[186:187], off
	v_lshl_add_u64 v[220:221], s[22:23], 0, v[160:161]
	s_add_i32 m0, s49, 0x2000
	s_nop 0
	global_load_lds_dwordx4 v[220:221], off
	s_barrier
	s_waitcnt lgkmcnt(0)
	s_setprio 1
	s_waitcnt lgkmcnt(0)
	v_mfma_f32_16x16x32_bf16 v[116:119], v[204:207], v[144:147], 0
	v_mfma_f32_16x16x32_bf16 v[112:115], v[212:215], v[144:147], 0
	v_mfma_f32_16x16x32_bf16 v[100:103], v[204:207], v[170:173], 0
	v_mfma_f32_16x16x32_bf16 v[96:99], v[212:215], v[170:173], 0
	v_mfma_f32_16x16x32_bf16 v[84:87], v[204:207], v[178:181], 0
	v_mfma_f32_16x16x32_bf16 v[80:83], v[212:215], v[178:181], 0
	v_mfma_f32_16x16x32_bf16 v[68:71], v[204:207], v[196:199], 0
	v_mfma_f32_16x16x32_bf16 v[64:67], v[212:215], v[196:199], 0
	v_mfma_f32_16x16x32_bf16 v[116:119], v[208:211], v[148:151], v[116:119]
	v_mfma_f32_16x16x32_bf16 v[112:115], v[216:219], v[148:151], v[112:115]
	v_mfma_f32_16x16x32_bf16 v[100:103], v[208:211], v[174:177], v[100:103]
	v_mfma_f32_16x16x32_bf16 v[96:99], v[216:219], v[174:177], v[96:99]
	v_mfma_f32_16x16x32_bf16 v[84:87], v[208:211], v[182:185], v[84:87]
	v_mfma_f32_16x16x32_bf16 v[80:83], v[216:219], v[182:185], v[80:83]
	v_mfma_f32_16x16x32_bf16 v[68:71], v[208:211], v[200:203], v[68:71]
	v_mfma_f32_16x16x32_bf16 v[64:67], v[216:219], v[200:203], v[64:67]
	s_setprio 0
	s_mov_b32 m0, s11
	v_lshl_add_u64 v[222:223], s[24:25], 0, v[154:155]
	s_barrier
	ds_read_b128 v[144:147], v192 offset:16384
	ds_read_b128 v[148:151], v192 offset:17408
	ds_read_b128 v[170:173], v192 offset:18432
	ds_read_b128 v[174:177], v192 offset:19456
	ds_read_b128 v[178:181], v192 offset:20480
	ds_read_b128 v[182:185], v192 offset:21504
	ds_read_b128 v[196:199], v192 offset:22528
	ds_read_b128 v[200:203], v192 offset:23552
	global_load_lds_dwordx4 v[222:223], off
	v_lshl_add_u64 v[224:225], s[24:25], 0, v[158:159]
	s_mov_b32 m0, s34
	s_nop 0
	global_load_lds_dwordx4 v[224:225], off
	s_barrier
	s_waitcnt lgkmcnt(0)
	s_setprio 1
	s_waitcnt lgkmcnt(0)
	v_mfma_f32_16x16x32_bf16 v[60:63], v[128:131], v[144:147], 0
	v_mfma_f32_16x16x32_bf16 v[56:59], v[136:139], v[144:147], 0
	v_mfma_f32_16x16x32_bf16 v[44:47], v[128:131], v[170:173], 0
	v_mfma_f32_16x16x32_bf16 v[40:43], v[136:139], v[170:173], 0
	v_mfma_f32_16x16x32_bf16 v[28:31], v[128:131], v[178:181], 0
	v_mfma_f32_16x16x32_bf16 v[24:27], v[136:139], v[178:181], 0
	v_mfma_f32_16x16x32_bf16 v[12:15], v[128:131], v[196:199], 0
	v_mfma_f32_16x16x32_bf16 v[8:11], v[136:139], v[196:199], 0
	v_mfma_f32_16x16x32_bf16 v[60:63], v[132:135], v[148:151], v[60:63]
	v_mfma_f32_16x16x32_bf16 v[56:59], v[140:143], v[148:151], v[56:59]
	v_mfma_f32_16x16x32_bf16 v[44:47], v[132:135], v[174:177], v[44:47]
	v_mfma_f32_16x16x32_bf16 v[40:43], v[140:143], v[174:177], v[40:43]
	v_mfma_f32_16x16x32_bf16 v[28:31], v[132:135], v[182:185], v[28:31]
	v_mfma_f32_16x16x32_bf16 v[24:27], v[140:143], v[182:185], v[24:27]
	v_mfma_f32_16x16x32_bf16 v[12:15], v[132:135], v[200:203], v[12:15]
	v_mfma_f32_16x16x32_bf16 v[8:11], v[140:143], v[200:203], v[8:11]
	s_setprio 0
	s_barrier
; #define PG8_STAGE(bufoff, gbase, voff) do { _Pragma("unroll") for (int _i = 0; _i < 2; ++_i) \
;         __builtin_amdgcn_global_load_lds((const unsigned*)((const char*)(gbase) + (voff)[_i]), (LAS unsigned*)(lds + (bufoff) + ldsw + _i * 8192), 16, 0, 0); } while (0)
; #define PG8_LDA(dst, b, h) do { _Pragma("unroll") for (int m = 0; m < 4; ++m) _Pragma("unroll") for (int k = 0; k < 2; ++k) dst[m][k] = *(const LAS bf16x8*)(lds + PG8_SA(b, h) + aoff + m * 2048 + k * 1024); } while (0)
; #define PG8_LDB(dst, b, h) do { _Pragma("unroll") for (int n = 0; n < 2; ++n) _Pragma("unroll") for (int k = 0; k < 2; ++k) dst[n][k] = *(const LAS bf16x8*)(lds + PG8_SB(b, h) + boff + n * 2048 + k * 1024); } while (0)
; #define PG8_MMA(ai, bj, At, Bt) do { __builtin_amdgcn_s_setprio(1); _Pragma("unroll") for (int m = 0; m < 4; ++m) _Pragma("unroll") for (int n = 0; n < 2; ++n) _Pragma("unroll") for (int k = 0; k < 2; ++k) \
;         acc[ai][bj][m][n] = __builtin_amdgcn_mfma_f32_16x16x32_bf16(Bt[n][k], At[m][k], acc[ai][bj][m][n], 0, 0, 0); __builtin_amdgcn_s_setprio(0); } while (0)
; #define PG8_WAIT_V(n) asm volatile("s_waitcnt vmcnt(" #n ")" ::: "memory")
; #define PG8_WAIT_L(n) asm volatile("s_waitcnt lgkmcnt(" #n ")" ::: "memory")
; #define PG8_BAR __builtin_amdgcn_s_barrier()
; #define PG8_SCHED __builtin_amdgcn_sched_barrier(0)
; template <class Epi>
; __device__ __forceinline__ void gemm_phase(LAS unsigned char* lds, const Gemm g, const StaticOrder& S, const Epi& E) {
;     ...
;             PG8_STAGE(PG8_SB(0, 1), b2 + hstepB, voffB);
;             PG8_WAIT_V(6); PG8_BAR; PG8_MMA(1, 1, At, B1); PG8_BAR;
;             PG8_LDB(B0, 1, 0); PG8_SCHED; PG8_LDA(At, 1, 0); PG8_STAGE(PG8_SA(0, 1), a2 + hstepA, voffA);
;             PG8_WAIT_L(8); PG8_BAR; PG8_WAIT_L(0); PG8_MMA(0, 0, At, B0); PG8_BAR; PG8_SCHED;
;             PG8_LDB(B1, 1, 1); PG8_STAGE(PG8_SB(1, 0), b3, voffB);
	s_add_u32 s50, s22, 0x80000
	s_addc_u32 s51, s23, 0
	s_add_i32 s49, s43, s31
	v_lshl_add_u64 v[128:129], s[50:51], 0, v[156:157]
	s_mov_b32 m0, s49
	s_nop 0
	global_load_lds_dwordx4 v[128:129], off
	v_lshl_add_u64 v[128:129], s[50:51], 0, v[160:161]
	s_add_i32 m0, s49, 0x2000
	s_nop 0
	global_load_lds_dwordx4 v[128:129], off
	s_waitcnt vmcnt(6)
	s_barrier
	s_setprio 1
	v_mfma_f32_16x16x32_bf16 v[52:55], v[204:207], v[144:147], 0
	v_mfma_f32_16x16x32_bf16 v[48:51], v[212:215], v[144:147], 0
	v_mfma_f32_16x16x32_bf16 v[36:39], v[204:207], v[170:173], 0
	v_mfma_f32_16x16x32_bf16 v[32:35], v[212:215], v[170:173], 0
	v_mfma_f32_16x16x32_bf16 v[20:23], v[204:207], v[178:181], 0
	v_mfma_f32_16x16x32_bf16 v[16:19], v[212:215], v[178:181], 0
	v_mfma_f32_16x16x32_bf16 v[4:7], v[204:207], v[196:199], 0
	v_mfma_f32_16x16x32_bf16 v[0:3], v[212:215], v[196:199], 0
	v_mfma_f32_16x16x32_bf16 v[52:55], v[208:211], v[148:151], v[52:55]
	v_mfma_f32_16x16x32_bf16 v[48:51], v[216:219], v[148:151], v[48:51]
	v_mfma_f32_16x16x32_bf16 v[36:39], v[208:211], v[174:177], v[36:39]
	v_mfma_f32_16x16x32_bf16 v[32:35], v[216:219], v[174:177], v[32:35]
	v_mfma_f32_16x16x32_bf16 v[20:23], v[208:211], v[182:185], v[20:23]
	v_mfma_f32_16x16x32_bf16 v[16:19], v[216:219], v[182:185], v[16:19]
	v_mfma_f32_16x16x32_bf16 v[4:7], v[208:211], v[200:203], v[4:7]
	v_mfma_f32_16x16x32_bf16 v[0:3], v[216:219], v[200:203], v[0:3]
	s_setprio 0
	s_add_i32 s49, 0, 0x18000
	v_add_u32_e32 v140, s49, v189
	s_barrier
	ds_read_b128 v[128:131], v140
	ds_read_b128 v[132:135], v140 offset:1024
	ds_read_b128 v[136:139], v140 offset:2048
	ds_read_b128 v[140:143], v140 offset:3072
	s_add_u32 s24, s24, 0x140000
	s_addc_u32 s25, s25, 0
	s_mov_b32 m0, s35
	v_lshl_add_u64 v[204:205], s[24:25], 0, v[154:155]
	ds_read_b128 v[144:147], v192 offset:32768
	ds_read_b128 v[148:151], v192 offset:33792
	ds_read_b128 v[170:173], v192 offset:34816
	ds_read_b128 v[174:177], v192 offset:35840
	ds_read_b128 v[178:181], v192 offset:36864
	ds_read_b128 v[182:185], v192 offset:37888
	ds_read_b128 v[196:199], v192 offset:38912
	ds_read_b128 v[200:203], v192 offset:39936
	global_load_lds_dwordx4 v[204:205], off
	v_lshl_add_u64 v[204:205], s[24:25], 0, v[158:159]
	s_mov_b32 m0, s36
	s_nop 0
	global_load_lds_dwordx4 v[204:205], off
	s_waitcnt lgkmcnt(8)
	s_barrier
	s_waitcnt lgkmcnt(0)
	s_setprio 1
	s_waitcnt lgkmcnt(0)
	v_mfma_f32_16x16x32_bf16 v[124:127], v[128:131], v[144:147], v[124:127]
	v_mfma_f32_16x16x32_bf16 v[120:123], v[136:139], v[144:147], v[120:123]
	v_mfma_f32_16x16x32_bf16 v[108:111], v[128:131], v[170:173], v[108:111]
	v_mfma_f32_16x16x32_bf16 v[104:107], v[136:139], v[170:173], v[104:107]
	v_mfma_f32_16x16x32_bf16 v[92:95], v[128:131], v[178:181], v[92:95]
	v_mfma_f32_16x16x32_bf16 v[88:91], v[136:139], v[178:181], v[88:91]
	v_mfma_f32_16x16x32_bf16 v[76:79], v[128:131], v[196:199], v[76:79]
	v_mfma_f32_16x16x32_bf16 v[72:75], v[136:139], v[196:199], v[72:75]
	v_mfma_f32_16x16x32_bf16 v[124:127], v[132:135], v[148:151], v[124:127]
	v_mfma_f32_16x16x32_bf16 v[120:123], v[140:143], v[148:151], v[120:123]
	v_mfma_f32_16x16x32_bf16 v[108:111], v[132:135], v[174:177], v[108:111]
	v_mfma_f32_16x16x32_bf16 v[104:107], v[140:143], v[174:177], v[104:107]
	v_mfma_f32_16x16x32_bf16 v[92:95], v[132:135], v[182:185], v[92:95]
	v_mfma_f32_16x16x32_bf16 v[88:91], v[140:143], v[182:185], v[88:91]
	v_mfma_f32_16x16x32_bf16 v[76:79], v[132:135], v[200:203], v[76:79]
	v_mfma_f32_16x16x32_bf16 v[72:75], v[140:143], v[200:203], v[72:75]
	s_setprio 0
	s_barrier
	s_add_i32 s24, 0, 0x1c000
	s_add_i32 s25, s49, s31
	v_add_u32_e32 v195, s24, v189
	v_lshl_add_u64 v[186:187], v[186:187], 0, s[14:15]
	s_mov_b32 m0, s25
	ds_read_b128 v[204:207], v195
	ds_read_b128 v[208:211], v195 offset:1024
	ds_read_b128 v[212:215], v195 offset:2048
	ds_read_b128 v[216:219], v195 offset:3072
	global_load_lds_dwordx4 v[186:187], off
	v_lshl_add_u64 v[186:187], v[220:221], 0, s[14:15]
	s_add_i32 m0, s25, 0x2000
	s_nop 0
	global_load_lds_dwordx4 v[186:187], off
	s_barrier
; #define PG8_STAGE(bufoff, gbase, voff) do { _Pragma("unroll") for (int _i = 0; _i < 2; ++_i) \
;         __builtin_amdgcn_global_load_lds((const unsigned*)((const char*)(gbase) + (voff)[_i]), (LAS unsigned*)(lds + (bufoff) + ldsw + _i * 8192), 16, 0, 0); } while (0)
; #define PG8_LDA(dst, b, h) do { _Pragma("unroll") for (int m = 0; m < 4; ++m) _Pragma("unroll") for (int k = 0; k < 2; ++k) dst[m][k] = *(const LAS bf16x8*)(lds + PG8_SA(b, h) + aoff + m * 2048 + k * 1024); } while (0)
; #define PG8_MMA(ai, bj, At, Bt) do { __builtin_amdgcn_s_setprio(1); _Pragma("unroll") for (int m = 0; m < 4; ++m) _Pragma("unroll") for (int n = 0; n < 2; ++n) _Pragma("unroll") for (int k = 0; k < 2; ++k) \
;         acc[ai][bj][m][n] = __builtin_amdgcn_mfma_f32_16x16x32_bf16(Bt[n][k], At[m][k], acc[ai][bj][m][n], 0, 0, 0); __builtin_amdgcn_s_setprio(0); } while (0)
; #define PG8_WAIT_V(n) asm volatile("s_waitcnt vmcnt(" #n ")" ::: "memory")
; #define PG8_WAIT_L(n) asm volatile("s_waitcnt lgkmcnt(" #n ")" ::: "memory")
; #define PG8_BAR __builtin_amdgcn_s_barrier()
; #define PG8_SCHED __builtin_amdgcn_sched_barrier(0)
; template <class Epi>
; __device__ __forceinline__ void gemm_phase(LAS unsigned char* lds, const Gemm g, const StaticOrder& S, const Epi& E) {
;     ...
;             PG8_BAR; PG8_WAIT_L(0); PG8_MMA(0, 1, At, B1); PG8_BAR;
;             PG8_LDA(At, 1, 1); PG8_STAGE(PG8_SA(1, 0), a3, voffA);
;             PG8_BAR; PG8_WAIT_L(0); PG8_MMA(1, 0, At, B0); PG8_BAR; PG8_SCHED;
;             PG8_STAGE(PG8_SB(1, 1), b3 + hstepB, voffB);
;             PG8_WAIT_V(6); PG8_BAR; PG8_MMA(1, 1, At, B1); PG8_BAR;
	s_waitcnt lgkmcnt(0)
	s_setprio 1
	s_waitcnt lgkmcnt(0)
	v_mfma_f32_16x16x32_bf16 v[116:119], v[204:207], v[144:147], v[116:119]
	v_mfma_f32_16x16x32_bf16 v[112:115], v[212:215], v[144:147], v[112:115]
	v_mfma_f32_16x16x32_bf16 v[100:103], v[204:207], v[170:173], v[100:103]
	v_mfma_f32_16x16x32_bf16 v[96:99], v[212:215], v[170:173], v[96:99]
	v_mfma_f32_16x16x32_bf16 v[84:87], v[204:207], v[178:181], v[84:87]
	v_mfma_f32_16x16x32_bf16 v[80:83], v[212:215], v[178:181], v[80:83]
	v_mfma_f32_16x16x32_bf16 v[68:71], v[204:207], v[196:199], v[68:71]
	v_mfma_f32_16x16x32_bf16 v[64:67], v[212:215], v[196:199], v[64:67]
	v_mfma_f32_16x16x32_bf16 v[116:119], v[208:211], v[148:151], v[116:119]
	v_mfma_f32_16x16x32_bf16 v[112:115], v[216:219], v[148:151], v[112:115]
	v_mfma_f32_16x16x32_bf16 v[100:103], v[208:211], v[174:177], v[100:103]
	v_mfma_f32_16x16x32_bf16 v[96:99], v[216:219], v[174:177], v[96:99]
	v_mfma_f32_16x16x32_bf16 v[84:87], v[208:211], v[182:185], v[84:87]
	v_mfma_f32_16x16x32_bf16 v[80:83], v[216:219], v[182:185], v[80:83]
	v_mfma_f32_16x16x32_bf16 v[68:71], v[208:211], v[200:203], v[68:71]
	v_mfma_f32_16x16x32_bf16 v[64:67], v[216:219], v[200:203], v[64:67]
	s_setprio 0
	s_mov_b32 m0, s38
	v_lshl_add_u64 v[186:187], v[222:223], 0, s[14:15]
	s_barrier
	ds_read_b128 v[144:147], v192 offset:49152
	ds_read_b128 v[148:151], v192 offset:50176
	ds_read_b128 v[170:173], v192 offset:51200
	ds_read_b128 v[174:177], v192 offset:52224
	ds_read_b128 v[178:181], v192 offset:53248
	ds_read_b128 v[182:185], v192 offset:54272
	ds_read_b128 v[196:199], v192 offset:55296
	ds_read_b128 v[200:203], v192 offset:56320
	global_load_lds_dwordx4 v[186:187], off
	v_lshl_add_u64 v[186:187], v[224:225], 0, s[14:15]
	s_mov_b32 m0, s39
	s_nop 0
	global_load_lds_dwordx4 v[186:187], off
	s_barrier
	s_waitcnt lgkmcnt(0)
	s_setprio 1
	s_waitcnt lgkmcnt(0)
	v_mfma_f32_16x16x32_bf16 v[60:63], v[128:131], v[144:147], v[60:63]
	v_mfma_f32_16x16x32_bf16 v[56:59], v[136:139], v[144:147], v[56:59]
	v_mfma_f32_16x16x32_bf16 v[44:47], v[128:131], v[170:173], v[44:47]
	v_mfma_f32_16x16x32_bf16 v[40:43], v[136:139], v[170:173], v[40:43]
	v_mfma_f32_16x16x32_bf16 v[28:31], v[128:131], v[178:181], v[28:31]
	v_mfma_f32_16x16x32_bf16 v[24:27], v[136:139], v[178:181], v[24:27]
	v_mfma_f32_16x16x32_bf16 v[12:15], v[128:131], v[196:199], v[12:15]
	v_mfma_f32_16x16x32_bf16 v[8:11], v[136:139], v[196:199], v[8:11]
	v_mfma_f32_16x16x32_bf16 v[60:63], v[132:135], v[148:151], v[60:63]
	v_mfma_f32_16x16x32_bf16 v[56:59], v[140:143], v[148:151], v[56:59]
	v_mfma_f32_16x16x32_bf16 v[44:47], v[132:135], v[174:177], v[44:47]
	v_mfma_f32_16x16x32_bf16 v[40:43], v[140:143], v[174:177], v[40:43]
	v_mfma_f32_16x16x32_bf16 v[28:31], v[132:135], v[182:185], v[28:31]
	v_mfma_f32_16x16x32_bf16 v[24:27], v[140:143], v[182:185], v[24:27]
	v_mfma_f32_16x16x32_bf16 v[12:15], v[132:135], v[200:203], v[12:15]
	v_mfma_f32_16x16x32_bf16 v[8:11], v[140:143], v[200:203], v[8:11]
	s_setprio 0
	s_barrier
	s_add_u32 s22, s22, 0x80080
	s_addc_u32 s23, s23, 0
	s_add_i32 s24, s24, s31
	v_lshl_add_u64 v[128:129], s[22:23], 0, v[156:157]
	s_mov_b32 m0, s24
	s_nop 0
	global_load_lds_dwordx4 v[128:129], off
	v_lshl_add_u64 v[128:129], s[22:23], 0, v[160:161]
	s_add_i32 m0, s24, 0x2000
	s_nop 0
	global_load_lds_dwordx4 v[128:129], off
	s_waitcnt vmcnt(6)
	s_barrier
	s_setprio 1
	v_mfma_f32_16x16x32_bf16 v[52:55], v[204:207], v[144:147], v[52:55]
	v_mfma_f32_16x16x32_bf16 v[48:51], v[212:215], v[144:147], v[48:51]
	v_mfma_f32_16x16x32_bf16 v[36:39], v[204:207], v[170:173], v[36:39]
	v_mfma_f32_16x16x32_bf16 v[32:35], v[212:215], v[170:173], v[32:35]
	v_mfma_f32_16x16x32_bf16 v[20:23], v[204:207], v[178:181], v[20:23]
	v_mfma_f32_16x16x32_bf16 v[16:19], v[212:215], v[178:181], v[16:19]
	v_mfma_f32_16x16x32_bf16 v[4:7], v[204:207], v[196:199], v[4:7]
	v_mfma_f32_16x16x32_bf16 v[0:3], v[212:215], v[196:199], v[0:3]
	v_mfma_f32_16x16x32_bf16 v[52:55], v[208:211], v[148:151], v[52:55]
	v_mfma_f32_16x16x32_bf16 v[48:51], v[216:219], v[148:151], v[48:51]
	v_mfma_f32_16x16x32_bf16 v[36:39], v[208:211], v[174:177], v[36:39]
	v_mfma_f32_16x16x32_bf16 v[32:35], v[216:219], v[174:177], v[32:35]
	v_mfma_f32_16x16x32_bf16 v[20:23], v[208:211], v[182:185], v[20:23]
	v_mfma_f32_16x16x32_bf16 v[16:19], v[216:219], v[182:185], v[16:19]
	v_mfma_f32_16x16x32_bf16 v[4:7], v[208:211], v[200:203], v[4:7]
	v_mfma_f32_16x16x32_bf16 v[0:3], v[216:219], v[200:203], v[0:3]
	s_setprio 0
	s_add_i32 s48, s48, 2
	s_add_u32 s4, s4, 0x100
	s_addc_u32 s5, s5, 0
	s_add_u32 s46, s46, 0x100
	s_addc_u32 s47, s47, 0
	s_cmp_gt_u32 s48, 29
	s_barrier

; #define PG8_STAGE(bufoff, gbase, voff) do { _Pragma("unroll") for (int _i = 0; _i < 2; ++_i) \
;         __builtin_amdgcn_global_load_lds((const unsigned*)((const char*)(gbase) + (voff)[_i]), (LAS unsigned*)(lds + (bufoff) + ldsw + _i * 8192), 16, 0, 0); } while (0)
; #define PG8_LDA(dst, b, h) do { _Pragma("unroll") for (int m = 0; m < 4; ++m) _Pragma("unroll") for (int k = 0; k < 2; ++k) dst[m][k] = *(const LAS bf16x8*)(lds + PG8_SA(b, h) + aoff + m * 2048 + k * 1024); } while (0)
; #define PG8_LDB(dst, b, h) do { _Pragma("unroll") for (int n = 0; n < 2; ++n) _Pragma("unroll") for (int k = 0; k < 2; ++k) dst[n][k] = *(const LAS bf16x8*)(lds + PG8_SB(b, h) + boff + n * 2048 + k * 1024); } while (0)
; #define PG8_WAIT_L(n) asm volatile("s_waitcnt lgkmcnt(" #n ")" ::: "memory")
; template <class Epi>
; __device__ __forceinline__ void gemm_phase(LAS unsigned char* lds, const Gemm g, const StaticOrder& S, const Epi& E) {
;     ...
;         const bool has_next = S.next(ui + 1, nxt);
;         const char* nA = has_next ? (const char*)g.A + (size_t)nxt.pm * tstepA : cA; const char* nB = has_next ? (const char*)g.Bt + (size_t)nxt.pn * tstepB : cB;
;         for (int t = 0; t < nt; t += 2) {
;             const bool last = (t == nt - 2);
;             const char* a1 = cA + (size_t)(t + 1) * kstep;
;             const char* a2 = last ? nA : cA + (size_t)(t + 2) * kstep; const char* b2 = last ? nB : cB + (size_t)(t + 2) * kstep;
;             const char* a3 = a2 + kstep; const char* b3 = b2 + kstep;
;             if (last) E.pre(cur, wr, fr, epre);
;             PG8_LDB(B0, 0, 0); PG8_SCHED; PG8_LDA(At, 0, 0); PG8_STAGE(PG8_SA(1, 1), a1 + hstepA, voffA);
;             PG8_WAIT_L(8); PG8_BAR; PG8_WAIT_L(0); PG8_MMA(0, 0, At, B0); PG8_BAR; PG8_SCHED;
;             PG8_LDB(B1, 0, 1); PG8_STAGE(PG8_SB(0, 0), b2, voffB);
;             PG8_BAR; PG8_WAIT_L(0); PG8_MMA(0, 1, At, B1); PG8_BAR;
;             PG8_LDA(At, 0, 1); PG8_STAGE(PG8_SA(0, 0), a2, voffA);
;             PG8_BAR; PG8_WAIT_L(0); PG8_MMA(1, 0, At, B0); PG8_BAR; PG8_SCHED;
;     ...
;         for (int a = 0; a < 2; ++a)
; #pragma unroll
;             for (int b = 0; b < 2; ++b)
; #pragma unroll
;                 for (int m = 0; m < 4; ++m)
; #pragma unroll
;                     for (int n = 0; n < 2; ++n) acc[a][b][m][n] = (f32x4){0.f, 0.f, 0.f, 0.f};
;         cur = nxt; cA = nA; cB = nB; ++ui;
.LBB0_769:
	s_ashr_i32 s13, s12, 31
	v_cmp_lt_i64_e32 vcc, s[14:15], v[142:143]
	s_lshl_b64 s[14:15], s[12:13], 19
	s_add_u32 s14, s76, s14
	s_addc_u32 s15, s77, s15
	s_and_b64 s[16:17], vcc, exec
	s_cselect_b32 s13, s15, s21
	s_cselect_b32 s41, s14, s20
	s_ashr_i32 s11, s10, 31
	s_lshl_b64 s[16:17], s[10:11], 19
	s_add_u32 s16, s27, s16
	s_addc_u32 s17, s28, s17
	s_and_b64 s[24:25], vcc, exec
	s_cselect_b32 s11, s17, s23
	s_cselect_b32 s42, s16, s22
	s_add_u32 s20, s20, 0x40080
	s_addc_u32 s21, s21, 0
	s_add_u32 s43, s22, 0x100
	s_addc_u32 s44, s23, 0
	s_mov_b32 s45, -2
	ds_read_b128 v[146:149], v177
	ds_read_b128 v[154:157], v177 offset:1024
	ds_read_b128 v[158:161], v177 offset:2048
	ds_read_b128 v[162:165], v177 offset:3072
	s_add_u32 s22, s20, 0xfffc0080
	s_addc_u32 s23, s21, -1
	s_cmp_eq_u32 s45, 12
	s_cselect_b32 s25, s13, s23
	s_cselect_b32 s24, s41, s22
	s_cselect_b32 s23, s11, s44
	s_cselect_b32 s22, s42, s43
	v_lshl_add_u64 v[150:151], s[20:21], 0, v[138:139]
	s_add_i32 m0, s19, 0xc000
	ds_read_b128 v[166:169], v178
	ds_read_b128 v[170:173], v178 offset:1024
	ds_read_b128 v[182:185], v178 offset:2048
	ds_read_b128 v[186:189], v178 offset:3072
	ds_read_b128 v[190:193], v178 offset:4096
	ds_read_b128 v[194:197], v178 offset:5120
	ds_read_b128 v[198:201], v178 offset:6144
	ds_read_b128 v[202:205], v178 offset:7168
	global_load_lds_dwordx4 v[150:151], off
	v_lshl_add_u64 v[150:151], s[20:21], 0, v[140:141]
	s_add_i32 m0, s19, 0xe000
	s_nop 0
	global_load_lds_dwordx4 v[150:151], off
	s_waitcnt lgkmcnt(8)
	s_barrier
	s_waitcnt lgkmcnt(0)
	s_setprio 1
	s_waitcnt lgkmcnt(0)
	v_mfma_f32_16x16x32_bf16 v[124:127], v[146:149], v[166:169], 0
	v_mfma_f32_16x16x32_bf16 v[120:123], v[158:161], v[166:169], 0
	v_mfma_f32_16x16x32_bf16 v[108:111], v[146:149], v[182:185], 0
	v_mfma_f32_16x16x32_bf16 v[104:107], v[158:161], v[182:185], 0
	v_mfma_f32_16x16x32_bf16 v[92:95], v[146:149], v[190:193], 0
	v_mfma_f32_16x16x32_bf16 v[88:91], v[158:161], v[190:193], 0
	v_mfma_f32_16x16x32_bf16 v[76:79], v[146:149], v[198:201], 0
	v_mfma_f32_16x16x32_bf16 v[72:75], v[158:161], v[198:201], 0
	v_mfma_f32_16x16x32_bf16 v[124:127], v[154:157], v[170:173], v[124:127]
	v_mfma_f32_16x16x32_bf16 v[120:123], v[162:165], v[170:173], v[120:123]
	v_mfma_f32_16x16x32_bf16 v[108:111], v[154:157], v[186:189], v[108:111]
	v_mfma_f32_16x16x32_bf16 v[104:107], v[162:165], v[186:189], v[104:107]
	v_mfma_f32_16x16x32_bf16 v[92:95], v[154:157], v[194:197], v[92:95]
	v_mfma_f32_16x16x32_bf16 v[88:91], v[162:165], v[194:197], v[88:91]
	v_mfma_f32_16x16x32_bf16 v[76:79], v[154:157], v[202:205], v[76:79]
	v_mfma_f32_16x16x32_bf16 v[72:75], v[162:165], v[202:205], v[72:75]
	s_setprio 0
	s_barrier
	s_add_i32 s46, s7, s29
	v_lshl_add_u64 v[150:151], s[22:23], 0, v[130:131]
	s_mov_b32 m0, s46
	ds_read_b128 v[206:209], v179
	ds_read_b128 v[210:213], v179 offset:1024
	ds_read_b128 v[214:217], v179 offset:2048
	ds_read_b128 v[218:221], v179 offset:3072
	global_load_lds_dwordx4 v[150:151], off
	v_lshl_add_u64 v[222:223], s[22:23], 0, v[134:135]
	s_add_i32 m0, s46, 0x2000
	s_nop 0
	global_load_lds_dwordx4 v[222:223], off
	s_barrier
	s_waitcnt lgkmcnt(0)
	s_setprio 1
	s_waitcnt lgkmcnt(0)
	v_mfma_f32_16x16x32_bf16 v[116:119], v[206:209], v[166:169], 0
	v_mfma_f32_16x16x32_bf16 v[112:115], v[214:217], v[166:169], 0
	v_mfma_f32_16x16x32_bf16 v[100:103], v[206:209], v[182:185], 0
	v_mfma_f32_16x16x32_bf16 v[96:99], v[214:217], v[182:185], 0
	v_mfma_f32_16x16x32_bf16 v[84:87], v[206:209], v[190:193], 0
	v_mfma_f32_16x16x32_bf16 v[80:83], v[214:217], v[190:193], 0
	v_mfma_f32_16x16x32_bf16 v[68:71], v[206:209], v[198:201], 0
	v_mfma_f32_16x16x32_bf16 v[64:67], v[214:217], v[198:201], 0
	v_mfma_f32_16x16x32_bf16 v[116:119], v[210:213], v[170:173], v[116:119]
	v_mfma_f32_16x16x32_bf16 v[112:115], v[218:221], v[170:173], v[112:115]
	v_mfma_f32_16x16x32_bf16 v[100:103], v[210:213], v[186:189], v[100:103]
	v_mfma_f32_16x16x32_bf16 v[96:99], v[218:221], v[186:189], v[96:99]
	v_mfma_f32_16x16x32_bf16 v[84:87], v[210:213], v[194:197], v[84:87]
	v_mfma_f32_16x16x32_bf16 v[80:83], v[218:221], v[194:197], v[80:83]
	v_mfma_f32_16x16x32_bf16 v[68:71], v[210:213], v[202:205], v[68:71]
	v_mfma_f32_16x16x32_bf16 v[64:67], v[218:221], v[202:205], v[64:67]
	s_setprio 0
	s_mov_b32 m0, s19
	v_lshl_add_u64 v[224:225], s[24:25], 0, v[128:129]
	s_barrier
	ds_read_b128 v[166:169], v178 offset:16384
	ds_read_b128 v[170:173], v178 offset:17408
	ds_read_b128 v[182:185], v178 offset:18432
	ds_read_b128 v[186:189], v178 offset:19456
	ds_read_b128 v[190:193], v178 offset:20480
	ds_read_b128 v[194:197], v178 offset:21504
	ds_read_b128 v[198:201], v178 offset:22528
	ds_read_b128 v[202:205], v178 offset:23552
	global_load_lds_dwordx4 v[224:225], off
	v_lshl_add_u64 v[226:227], s[24:25], 0, v[132:133]
	s_mov_b32 m0, s30
	s_nop 0
	global_load_lds_dwordx4 v[226:227], off
	s_barrier
	s_waitcnt lgkmcnt(0)
	s_setprio 1
	s_waitcnt lgkmcnt(0)
	v_mfma_f32_16x16x32_bf16 v[60:63], v[146:149], v[166:169], 0
	v_mfma_f32_16x16x32_bf16 v[56:59], v[158:161], v[166:169], 0
	v_mfma_f32_16x16x32_bf16 v[44:47], v[146:149], v[182:185], 0
	v_mfma_f32_16x16x32_bf16 v[40:43], v[158:161], v[182:185], 0
	v_mfma_f32_16x16x32_bf16 v[28:31], v[146:149], v[190:193], 0
	v_mfma_f32_16x16x32_bf16 v[24:27], v[158:161], v[190:193], 0
	v_mfma_f32_16x16x32_bf16 v[12:15], v[146:149], v[198:201], 0
	v_mfma_f32_16x16x32_bf16 v[8:11], v[158:161], v[198:201], 0
	v_mfma_f32_16x16x32_bf16 v[60:63], v[154:157], v[170:173], v[60:63]
	v_mfma_f32_16x16x32_bf16 v[56:59], v[162:165], v[170:173], v[56:59]
	v_mfma_f32_16x16x32_bf16 v[44:47], v[154:157], v[186:189], v[44:47]
	v_mfma_f32_16x16x32_bf16 v[40:43], v[162:165], v[186:189], v[40:43]
	v_mfma_f32_16x16x32_bf16 v[28:31], v[154:157], v[194:197], v[28:31]
	v_mfma_f32_16x16x32_bf16 v[24:27], v[162:165], v[194:197], v[24:27]
	v_mfma_f32_16x16x32_bf16 v[12:15], v[154:157], v[202:205], v[12:15]
	v_mfma_f32_16x16x32_bf16 v[8:11], v[162:165], v[202:205], v[8:11]
	s_setprio 0
	s_barrier
; #define PG8_STAGE(bufoff, gbase, voff) do { _Pragma("unroll") for (int _i = 0; _i < 2; ++_i) \
;         __builtin_amdgcn_global_load_lds((const unsigned*)((const char*)(gbase) + (voff)[_i]), (LAS unsigned*)(lds + (bufoff) + ldsw + _i * 8192), 16, 0, 0); } while (0)
; #define PG8_LDA(dst, b, h) do { _Pragma("unroll") for (int m = 0; m < 4; ++m) _Pragma("unroll") for (int k = 0; k < 2; ++k) dst[m][k] = *(const LAS bf16x8*)(lds + PG8_SA(b, h) + aoff + m * 2048 + k * 1024); } while (0)
; #define PG8_LDB(dst, b, h) do { _Pragma("unroll") for (int n = 0; n < 2; ++n) _Pragma("unroll") for (int k = 0; k < 2; ++k) dst[n][k] = *(const LAS bf16x8*)(lds + PG8_SB(b, h) + boff + n * 2048 + k * 1024); } while (0)
; #define PG8_MMA(ai, bj, At, Bt) do { __builtin_amdgcn_s_setprio(1); _Pragma("unroll") for (int m = 0; m < 4; ++m) _Pragma("unroll") for (int n = 0; n < 2; ++n) _Pragma("unroll") for (int k = 0; k < 2; ++k) \
;         acc[ai][bj][m][n] = __builtin_amdgcn_mfma_f32_16x16x32_bf16(Bt[n][k], At[m][k], acc[ai][bj][m][n], 0, 0, 0); __builtin_amdgcn_s_setprio(0); } while (0)
; #define PG8_WAIT_V(n) asm volatile("s_waitcnt vmcnt(" #n ")" ::: "memory")
; #define PG8_WAIT_L(n) asm volatile("s_waitcnt lgkmcnt(" #n ")" ::: "memory")
; #define PG8_BAR __builtin_amdgcn_s_barrier()
; #define PG8_SCHED __builtin_amdgcn_sched_barrier(0)
; template <class Epi>
; __device__ __forceinline__ void gemm_phase(LAS unsigned char* lds, const Gemm g, const StaticOrder& S, const Epi& E) {
;     ...
;             PG8_STAGE(PG8_SB(0, 1), b2 + hstepB, voffB);
;             PG8_WAIT_V(6); PG8_BAR; PG8_MMA(1, 1, At, B1); PG8_BAR;
;             PG8_LDB(B0, 1, 0); PG8_SCHED; PG8_LDA(At, 1, 0); PG8_STAGE(PG8_SA(0, 1), a2 + hstepA, voffA);
;             PG8_WAIT_L(8); PG8_BAR; PG8_WAIT_L(0); PG8_MMA(0, 0, At, B0); PG8_BAR; PG8_SCHED;
;             PG8_LDB(B1, 1, 1); PG8_STAGE(PG8_SB(1, 0), b3, voffB);
	s_add_u32 s46, s22, 0x40000
	s_addc_u32 s47, s23, 0
	s_add_i32 s48, s38, s29
	v_lshl_add_u64 v[146:147], s[46:47], 0, v[130:131]
	s_mov_b32 m0, s48
	s_nop 0
	global_load_lds_dwordx4 v[146:147], off
	v_lshl_add_u64 v[146:147], s[46:47], 0, v[134:135]
	s_add_i32 m0, s48, 0x2000
	s_nop 0
	global_load_lds_dwordx4 v[146:147], off
	s_waitcnt vmcnt(6)
	s_barrier
	s_setprio 1
	v_mfma_f32_16x16x32_bf16 v[52:55], v[206:209], v[166:169], 0
	v_mfma_f32_16x16x32_bf16 v[48:51], v[214:217], v[166:169], 0
	v_mfma_f32_16x16x32_bf16 v[36:39], v[206:209], v[182:185], 0
	v_mfma_f32_16x16x32_bf16 v[32:35], v[214:217], v[182:185], 0
	v_mfma_f32_16x16x32_bf16 v[20:23], v[206:209], v[190:193], 0
	v_mfma_f32_16x16x32_bf16 v[16:19], v[214:217], v[190:193], 0
	v_mfma_f32_16x16x32_bf16 v[4:7], v[206:209], v[198:201], 0
	v_mfma_f32_16x16x32_bf16 v[0:3], v[214:217], v[198:201], 0
	v_mfma_f32_16x16x32_bf16 v[52:55], v[210:213], v[170:173], v[52:55]
	v_mfma_f32_16x16x32_bf16 v[48:51], v[218:221], v[170:173], v[48:51]
	v_mfma_f32_16x16x32_bf16 v[36:39], v[210:213], v[186:189], v[36:39]
	v_mfma_f32_16x16x32_bf16 v[32:35], v[218:221], v[186:189], v[32:35]
	v_mfma_f32_16x16x32_bf16 v[20:23], v[210:213], v[194:197], v[20:23]
	v_mfma_f32_16x16x32_bf16 v[16:19], v[218:221], v[194:197], v[16:19]
	v_mfma_f32_16x16x32_bf16 v[4:7], v[210:213], v[202:205], v[4:7]
	v_mfma_f32_16x16x32_bf16 v[0:3], v[218:221], v[202:205], v[0:3]
	s_setprio 0
	s_add_i32 s46, 0, 0x18000
	v_add_u32_e32 v162, s46, v175
	s_barrier
	ds_read_b128 v[146:149], v162
	ds_read_b128 v[154:157], v162 offset:1024
	ds_read_b128 v[158:161], v162 offset:2048
	ds_read_b128 v[162:165], v162 offset:3072
	s_add_u32 s24, s24, 0x40000
	s_addc_u32 s25, s25, 0
	s_mov_b32 m0, s31
	v_lshl_add_u64 v[206:207], s[24:25], 0, v[128:129]
	ds_read_b128 v[166:169], v178 offset:32768
	ds_read_b128 v[170:173], v178 offset:33792
	ds_read_b128 v[182:185], v178 offset:34816
	ds_read_b128 v[186:189], v178 offset:35840
	ds_read_b128 v[190:193], v178 offset:36864
	ds_read_b128 v[194:197], v178 offset:37888
	ds_read_b128 v[198:201], v178 offset:38912
	ds_read_b128 v[202:205], v178 offset:39936
	global_load_lds_dwordx4 v[206:207], off
	v_lshl_add_u64 v[206:207], s[24:25], 0, v[132:133]
	s_mov_b32 m0, s33
	s_nop 0
	global_load_lds_dwordx4 v[206:207], off
	s_waitcnt lgkmcnt(8)
	s_barrier
	s_waitcnt lgkmcnt(0)
	s_setprio 1
	s_waitcnt lgkmcnt(0)
	v_mfma_f32_16x16x32_bf16 v[124:127], v[146:149], v[166:169], v[124:127]
	v_mfma_f32_16x16x32_bf16 v[120:123], v[158:161], v[166:169], v[120:123]
	v_mfma_f32_16x16x32_bf16 v[108:111], v[146:149], v[182:185], v[108:111]
	v_mfma_f32_16x16x32_bf16 v[104:107], v[158:161], v[182:185], v[104:107]
	v_mfma_f32_16x16x32_bf16 v[92:95], v[146:149], v[190:193], v[92:95]
	v_mfma_f32_16x16x32_bf16 v[88:91], v[158:161], v[190:193], v[88:91]
	v_mfma_f32_16x16x32_bf16 v[76:79], v[146:149], v[198:201], v[76:79]
	v_mfma_f32_16x16x32_bf16 v[72:75], v[158:161], v[198:201], v[72:75]
	v_mfma_f32_16x16x32_bf16 v[124:127], v[154:157], v[170:173], v[124:127]
	v_mfma_f32_16x16x32_bf16 v[120:123], v[162:165], v[170:173], v[120:123]
	v_mfma_f32_16x16x32_bf16 v[108:111], v[154:157], v[186:189], v[108:111]
	v_mfma_f32_16x16x32_bf16 v[104:107], v[162:165], v[186:189], v[104:107]
	v_mfma_f32_16x16x32_bf16 v[92:95], v[154:157], v[194:197], v[92:95]
	v_mfma_f32_16x16x32_bf16 v[88:91], v[162:165], v[194:197], v[88:91]
	v_mfma_f32_16x16x32_bf16 v[76:79], v[154:157], v[202:205], v[76:79]
	v_mfma_f32_16x16x32_bf16 v[72:75], v[162:165], v[202:205], v[72:75]
	s_setprio 0
	s_barrier
	s_add_i32 s24, 0, 0x1c000
	s_add_i32 s25, s46, s29
	v_add_u32_e32 v181, s24, v175
	v_lshl_add_u64 v[150:151], v[150:151], 0, s[4:5]
	s_mov_b32 m0, s25
	ds_read_b128 v[206:209], v181
	ds_read_b128 v[210:213], v181 offset:1024
	ds_read_b128 v[214:217], v181 offset:2048
	ds_read_b128 v[218:221], v181 offset:3072
	global_load_lds_dwordx4 v[150:151], off
	v_lshl_add_u64 v[150:151], v[222:223], 0, s[4:5]
	s_add_i32 m0, s25, 0x2000
	s_nop 0
	global_load_lds_dwordx4 v[150:151], off
	s_barrier
; #define PG8_STAGE(bufoff, gbase, voff) do { _Pragma("unroll") for (int _i = 0; _i < 2; ++_i) \
;         __builtin_amdgcn_global_load_lds((const unsigned*)((const char*)(gbase) + (voff)[_i]), (LAS unsigned*)(lds + (bufoff) + ldsw + _i * 8192), 16, 0, 0); } while (0)
; #define PG8_LDA(dst, b, h) do { _Pragma("unroll") for (int m = 0; m < 4; ++m) _Pragma("unroll") for (int k = 0; k < 2; ++k) dst[m][k] = *(const LAS bf16x8*)(lds + PG8_SA(b, h) + aoff + m * 2048 + k * 1024); } while (0)
; #define PG8_MMA(ai, bj, At, Bt) do { __builtin_amdgcn_s_setprio(1); _Pragma("unroll") for (int m = 0; m < 4; ++m) _Pragma("unroll") for (int n = 0; n < 2; ++n) _Pragma("unroll") for (int k = 0; k < 2; ++k) \
;         acc[ai][bj][m][n] = __builtin_amdgcn_mfma_f32_16x16x32_bf16(Bt[n][k], At[m][k], acc[ai][bj][m][n], 0, 0, 0); __builtin_amdgcn_s_setprio(0); } while (0)
; #define PG8_WAIT_V(n) asm volatile("s_waitcnt vmcnt(" #n ")" ::: "memory")
; #define PG8_WAIT_L(n) asm volatile("s_waitcnt lgkmcnt(" #n ")" ::: "memory")
; #define PG8_BAR __builtin_amdgcn_s_barrier()
; #define PG8_SCHED __builtin_amdgcn_sched_barrier(0)
; template <class Epi>
; __device__ __forceinline__ void gemm_phase(LAS unsigned char* lds, const Gemm g, const StaticOrder& S, const Epi& E) {
;     ...
;             PG8_BAR; PG8_WAIT_L(0); PG8_MMA(0, 1, At, B1); PG8_BAR;
;             PG8_LDA(At, 1, 1); PG8_STAGE(PG8_SA(1, 0), a3, voffA);
;             PG8_BAR; PG8_WAIT_L(0); PG8_MMA(1, 0, At, B0); PG8_BAR; PG8_SCHED;
;             PG8_STAGE(PG8_SB(1, 1), b3 + hstepB, voffB);
;             PG8_WAIT_V(6); PG8_BAR; PG8_MMA(1, 1, At, B1); PG8_BAR;
	s_waitcnt lgkmcnt(0)
	s_setprio 1
	s_waitcnt lgkmcnt(0)
	v_mfma_f32_16x16x32_bf16 v[116:119], v[206:209], v[166:169], v[116:119]
	v_mfma_f32_16x16x32_bf16 v[112:115], v[214:217], v[166:169], v[112:115]
	v_mfma_f32_16x16x32_bf16 v[100:103], v[206:209], v[182:185], v[100:103]
	v_mfma_f32_16x16x32_bf16 v[96:99], v[214:217], v[182:185], v[96:99]
	v_mfma_f32_16x16x32_bf16 v[84:87], v[206:209], v[190:193], v[84:87]
	v_mfma_f32_16x16x32_bf16 v[80:83], v[214:217], v[190:193], v[80:83]
	v_mfma_f32_16x16x32_bf16 v[68:71], v[206:209], v[198:201], v[68:71]
	v_mfma_f32_16x16x32_bf16 v[64:67], v[214:217], v[198:201], v[64:67]
	v_mfma_f32_16x16x32_bf16 v[116:119], v[210:213], v[170:173], v[116:119]
	v_mfma_f32_16x16x32_bf16 v[112:115], v[218:221], v[170:173], v[112:115]
	v_mfma_f32_16x16x32_bf16 v[100:103], v[210:213], v[186:189], v[100:103]
	v_mfma_f32_16x16x32_bf16 v[96:99], v[218:221], v[186:189], v[96:99]
	v_mfma_f32_16x16x32_bf16 v[84:87], v[210:213], v[194:197], v[84:87]
	v_mfma_f32_16x16x32_bf16 v[80:83], v[218:221], v[194:197], v[80:83]
	v_mfma_f32_16x16x32_bf16 v[68:71], v[210:213], v[202:205], v[68:71]
	v_mfma_f32_16x16x32_bf16 v[64:67], v[218:221], v[202:205], v[64:67]
	s_setprio 0
	s_mov_b32 m0, s35
	v_lshl_add_u64 v[150:151], v[224:225], 0, s[4:5]
	s_barrier
	ds_read_b128 v[166:169], v178 offset:49152
	ds_read_b128 v[170:173], v178 offset:50176
	ds_read_b128 v[182:185], v178 offset:51200
	ds_read_b128 v[186:189], v178 offset:52224
	ds_read_b128 v[190:193], v178 offset:53248
	ds_read_b128 v[194:197], v178 offset:54272
	ds_read_b128 v[198:201], v178 offset:55296
	ds_read_b128 v[202:205], v178 offset:56320
	global_load_lds_dwordx4 v[150:151], off
	v_lshl_add_u64 v[150:151], v[226:227], 0, s[4:5]
	s_mov_b32 m0, s36
	s_nop 0
	global_load_lds_dwordx4 v[150:151], off
	s_barrier
	s_waitcnt lgkmcnt(0)
	s_setprio 1
	s_waitcnt lgkmcnt(0)
	v_mfma_f32_16x16x32_bf16 v[60:63], v[146:149], v[166:169], v[60:63]
	v_mfma_f32_16x16x32_bf16 v[56:59], v[158:161], v[166:169], v[56:59]
	v_mfma_f32_16x16x32_bf16 v[44:47], v[146:149], v[182:185], v[44:47]
	v_mfma_f32_16x16x32_bf16 v[40:43], v[158:161], v[182:185], v[40:43]
	v_mfma_f32_16x16x32_bf16 v[28:31], v[146:149], v[190:193], v[28:31]
	v_mfma_f32_16x16x32_bf16 v[24:27], v[158:161], v[190:193], v[24:27]
	v_mfma_f32_16x16x32_bf16 v[12:15], v[146:149], v[198:201], v[12:15]
	v_mfma_f32_16x16x32_bf16 v[8:11], v[158:161], v[198:201], v[8:11]
	v_mfma_f32_16x16x32_bf16 v[60:63], v[154:157], v[170:173], v[60:63]
	v_mfma_f32_16x16x32_bf16 v[56:59], v[162:165], v[170:173], v[56:59]
	v_mfma_f32_16x16x32_bf16 v[44:47], v[154:157], v[186:189], v[44:47]
	v_mfma_f32_16x16x32_bf16 v[40:43], v[162:165], v[186:189], v[40:43]
	v_mfma_f32_16x16x32_bf16 v[28:31], v[154:157], v[194:197], v[28:31]
	v_mfma_f32_16x16x32_bf16 v[24:27], v[162:165], v[194:197], v[24:27]
	v_mfma_f32_16x16x32_bf16 v[12:15], v[154:157], v[202:205], v[12:15]
	v_mfma_f32_16x16x32_bf16 v[8:11], v[162:165], v[202:205], v[8:11]
	s_setprio 0
	s_barrier
	s_add_u32 s22, s22, 0x40080
	s_addc_u32 s23, s23, 0
	s_add_i32 s24, s24, s29
	v_lshl_add_u64 v[146:147], s[22:23], 0, v[130:131]
	s_mov_b32 m0, s24
	s_nop 0
	global_load_lds_dwordx4 v[146:147], off
	v_lshl_add_u64 v[146:147], s[22:23], 0, v[134:135]
	s_add_i32 m0, s24, 0x2000
	s_nop 0
	global_load_lds_dwordx4 v[146:147], off
	s_waitcnt vmcnt(6)
	s_barrier
	s_setprio 1
	v_mfma_f32_16x16x32_bf16 v[52:55], v[206:209], v[166:169], v[52:55]
	v_mfma_f32_16x16x32_bf16 v[48:51], v[214:217], v[166:169], v[48:51]
	v_mfma_f32_16x16x32_bf16 v[36:39], v[206:209], v[182:185], v[36:39]
	v_mfma_f32_16x16x32_bf16 v[32:35], v[214:217], v[182:185], v[32:35]
	v_mfma_f32_16x16x32_bf16 v[20:23], v[206:209], v[190:193], v[20:23]
	v_mfma_f32_16x16x32_bf16 v[16:19], v[214:217], v[190:193], v[16:19]
	v_mfma_f32_16x16x32_bf16 v[4:7], v[206:209], v[198:201], v[4:7]
	v_mfma_f32_16x16x32_bf16 v[0:3], v[214:217], v[198:201], v[0:3]
	v_mfma_f32_16x16x32_bf16 v[52:55], v[210:213], v[170:173], v[52:55]
	v_mfma_f32_16x16x32_bf16 v[48:51], v[218:221], v[170:173], v[48:51]
	v_mfma_f32_16x16x32_bf16 v[36:39], v[210:213], v[186:189], v[36:39]
	v_mfma_f32_16x16x32_bf16 v[32:35], v[218:221], v[186:189], v[32:35]
	v_mfma_f32_16x16x32_bf16 v[20:23], v[210:213], v[194:197], v[20:23]
	v_mfma_f32_16x16x32_bf16 v[16:19], v[218:221], v[194:197], v[16:19]
	v_mfma_f32_16x16x32_bf16 v[4:7], v[210:213], v[202:205], v[4:7]
	v_mfma_f32_16x16x32_bf16 v[0:3], v[218:221], v[202:205], v[0:3]
	s_setprio 0
	s_add_i32 s45, s45, 2
	s_add_u32 s20, s20, 0x100
	s_addc_u32 s21, s21, 0
	s_add_u32 s43, s43, 0x100
	s_addc_u32 s44, s44, 0
	s_cmp_gt_u32 s45, 13
	s_barrier

; #define PG8_STAGE(bufoff, gbase, voff) do { _Pragma("unroll") for (int _i = 0; _i < 2; ++_i) \
;         __builtin_amdgcn_global_load_lds((const unsigned*)((const char*)(gbase) + (voff)[_i]), (LAS unsigned*)(lds + (bufoff) + ldsw + _i * 8192), 16, 0, 0); } while (0)
; #define PG8_LDA(dst, b, h) do { _Pragma("unroll") for (int m = 0; m < 4; ++m) _Pragma("unroll") for (int k = 0; k < 2; ++k) dst[m][k] = *(const LAS bf16x8*)(lds + PG8_SA(b, h) + aoff + m * 2048 + k * 1024); } while (0)
; #define PG8_LDB(dst, b, h) do { _Pragma("unroll") for (int n = 0; n < 2; ++n) _Pragma("unroll") for (int k = 0; k < 2; ++k) dst[n][k] = *(const LAS bf16x8*)(lds + PG8_SB(b, h) + boff + n * 2048 + k * 1024); } while (0)
; #define PG8_MMA(ai, bj, At, Bt) do { __builtin_amdgcn_s_setprio(1); _Pragma("unroll") for (int m = 0; m < 4; ++m) _Pragma("unroll") for (int n = 0; n < 2; ++n) _Pragma("unroll") for (int k = 0; k < 2; ++k) \
;         acc[ai][bj][m][n] = __builtin_amdgcn_mfma_f32_16x16x32_bf16(Bt[n][k], At[m][k], acc[ai][bj][m][n], 0, 0, 0); __builtin_amdgcn_s_setprio(0); } while (0)
; #define PG8_BAR __builtin_amdgcn_s_barrier()
; template <class Epi>
; __device__ __forceinline__ void gemm_phase(LAS unsigned char* lds, const Gemm g, const StaticOrder& S, const Epi& E) {
;     ...
;         const bool has_next = S.next(ui + 1, nxt);
;         const char* nA = has_next ? (const char*)g.A + (size_t)nxt.pm * tstepA : cA; const char* nB = has_next ? (const char*)g.Bt + (size_t)nxt.pn * tstepB : cB;
;         for (int t = 0; t < nt; t += 2) {
;             const bool last = (t == nt - 2);
;             const char* a1 = cA + (size_t)(t + 1) * kstep;
;             const char* a2 = last ? nA : cA + (size_t)(t + 2) * kstep; const char* b2 = last ? nB : cB + (size_t)(t + 2) * kstep;
;             const char* a3 = a2 + kstep; const char* b3 = b2 + kstep;
;             if (last) E.pre(cur, wr, fr, epre);
;             PG8_LDB(B0, 0, 0); PG8_SCHED; PG8_LDA(At, 0, 0); PG8_STAGE(PG8_SA(1, 1), a1 + hstepA, voffA);
;             PG8_WAIT_L(8); PG8_BAR; PG8_WAIT_L(0); PG8_MMA(0, 0, At, B0); PG8_BAR; PG8_SCHED;
;             PG8_LDB(B1, 0, 1); PG8_STAGE(PG8_SB(0, 0), b2, voffB);
;             PG8_BAR; PG8_WAIT_L(0); PG8_MMA(0, 1, At, B1); PG8_BAR;
;             PG8_LDA(At, 0, 1); PG8_STAGE(PG8_SA(0, 0), a2, voffA);
;             PG8_BAR; PG8_WAIT_L(0); PG8_MMA(1, 0, At, B0); PG8_BAR; PG8_SCHED;
.LBB0_843:
	s_ashr_i32 s17, s16, 31
	v_cmp_lt_i64_e32 vcc, s[18:19], v[166:167]
	s_lshl_b64 s[18:19], s[16:17], 21
	s_add_u32 s18, s96, s18
	s_addc_u32 s19, s97, s19
	s_and_b64 s[20:21], vcc, exec
	s_cselect_b32 s17, s19, s23
	s_cselect_b32 s44, s18, s22
	s_ashr_i32 s15, s14, 31
	s_lshl_b64 s[20:21], s[14:15], 21
	s_add_u32 s20, s29, s20
	s_addc_u32 s21, s30, s21
	s_and_b64 s[26:27], vcc, exec
	s_cselect_b32 s15, s21, s25
	s_cselect_b32 s45, s20, s24
	s_add_u32 s22, s22, 0x100080
	s_addc_u32 s23, s23, 0
	s_add_u32 s46, s24, 0x100
	s_addc_u32 s47, s25, 0
	s_mov_b32 s48, -2
	s_waitcnt lgkmcnt(0)
	ds_read_b128 v[128:131], v191
	ds_read_b128 v[132:135], v191 offset:1024
	ds_read_b128 v[136:139], v191 offset:2048
	ds_read_b128 v[140:143], v191 offset:3072
	s_add_u32 s24, s22, 0xfff00080
	s_addc_u32 s25, s23, -1
	s_cmp_eq_u32 s48, 60
	s_cselect_b32 s27, s17, s25
	s_cselect_b32 s26, s44, s24
	s_cselect_b32 s25, s15, s47
	s_cselect_b32 s24, s45, s46
	v_lshl_add_u64 v[186:187], s[22:23], 0, v[162:163]
	s_add_i32 m0, s7, 0xc000
	ds_read_b128 v[144:147], v192
	ds_read_b128 v[148:151], v192 offset:1024
	ds_read_b128 v[170:173], v192 offset:2048
	ds_read_b128 v[174:177], v192 offset:3072
	ds_read_b128 v[178:181], v192 offset:4096
	ds_read_b128 v[182:185], v192 offset:5120
	ds_read_b128 v[196:199], v192 offset:6144
	ds_read_b128 v[200:203], v192 offset:7168
	global_load_lds_dwordx4 v[186:187], off
	v_lshl_add_u64 v[186:187], s[22:23], 0, v[164:165]
	s_add_i32 m0, s7, 0xe000
	s_nop 0
	global_load_lds_dwordx4 v[186:187], off
	s_waitcnt lgkmcnt(8)
	s_barrier
	s_waitcnt lgkmcnt(0)
	s_setprio 1
	s_waitcnt lgkmcnt(0)
	v_mfma_f32_16x16x32_bf16 v[124:127], v[128:131], v[144:147], 0
	v_mfma_f32_16x16x32_bf16 v[120:123], v[136:139], v[144:147], 0
	v_mfma_f32_16x16x32_bf16 v[108:111], v[128:131], v[170:173], 0
	v_mfma_f32_16x16x32_bf16 v[104:107], v[136:139], v[170:173], 0
	v_mfma_f32_16x16x32_bf16 v[92:95], v[128:131], v[178:181], 0
	v_mfma_f32_16x16x32_bf16 v[88:91], v[136:139], v[178:181], 0
	v_mfma_f32_16x16x32_bf16 v[76:79], v[128:131], v[196:199], 0
	v_mfma_f32_16x16x32_bf16 v[72:75], v[136:139], v[196:199], 0
	v_mfma_f32_16x16x32_bf16 v[124:127], v[132:135], v[148:151], v[124:127]
	v_mfma_f32_16x16x32_bf16 v[120:123], v[140:143], v[148:151], v[120:123]
	v_mfma_f32_16x16x32_bf16 v[108:111], v[132:135], v[174:177], v[108:111]
	v_mfma_f32_16x16x32_bf16 v[104:107], v[140:143], v[174:177], v[104:107]
	v_mfma_f32_16x16x32_bf16 v[92:95], v[132:135], v[182:185], v[92:95]
	v_mfma_f32_16x16x32_bf16 v[88:91], v[140:143], v[182:185], v[88:91]
	v_mfma_f32_16x16x32_bf16 v[76:79], v[132:135], v[200:203], v[76:79]
	v_mfma_f32_16x16x32_bf16 v[72:75], v[140:143], v[200:203], v[72:75]
	s_setprio 0
	s_barrier
	s_add_i32 s49, s42, s31
	v_lshl_add_u64 v[186:187], s[24:25], 0, v[156:157]
	s_mov_b32 m0, s49
	ds_read_b128 v[204:207], v193
	ds_read_b128 v[208:211], v193 offset:1024
	ds_read_b128 v[212:215], v193 offset:2048
	ds_read_b128 v[216:219], v193 offset:3072
	global_load_lds_dwordx4 v[186:187], off
	v_lshl_add_u64 v[220:221], s[24:25], 0, v[160:161]
	s_add_i32 m0, s49, 0x2000
	s_nop 0
	global_load_lds_dwordx4 v[220:221], off
	s_barrier
	s_waitcnt lgkmcnt(0)
	s_setprio 1
	s_waitcnt lgkmcnt(0)
	v_mfma_f32_16x16x32_bf16 v[116:119], v[204:207], v[144:147], 0
	v_mfma_f32_16x16x32_bf16 v[112:115], v[212:215], v[144:147], 0
	v_mfma_f32_16x16x32_bf16 v[100:103], v[204:207], v[170:173], 0
	v_mfma_f32_16x16x32_bf16 v[96:99], v[212:215], v[170:173], 0
	v_mfma_f32_16x16x32_bf16 v[84:87], v[204:207], v[178:181], 0
	v_mfma_f32_16x16x32_bf16 v[80:83], v[212:215], v[178:181], 0
	v_mfma_f32_16x16x32_bf16 v[68:71], v[204:207], v[196:199], 0
	v_mfma_f32_16x16x32_bf16 v[64:67], v[212:215], v[196:199], 0
	v_mfma_f32_16x16x32_bf16 v[116:119], v[208:211], v[148:151], v[116:119]
	v_mfma_f32_16x16x32_bf16 v[112:115], v[216:219], v[148:151], v[112:115]
	v_mfma_f32_16x16x32_bf16 v[100:103], v[208:211], v[174:177], v[100:103]
	v_mfma_f32_16x16x32_bf16 v[96:99], v[216:219], v[174:177], v[96:99]
	v_mfma_f32_16x16x32_bf16 v[84:87], v[208:211], v[182:185], v[84:87]
	v_mfma_f32_16x16x32_bf16 v[80:83], v[216:219], v[182:185], v[80:83]
	v_mfma_f32_16x16x32_bf16 v[68:71], v[208:211], v[200:203], v[68:71]
	v_mfma_f32_16x16x32_bf16 v[64:67], v[216:219], v[200:203], v[64:67]
	s_setprio 0
	s_mov_b32 m0, s7
	v_lshl_add_u64 v[222:223], s[26:27], 0, v[154:155]
	s_barrier
	ds_read_b128 v[144:147], v192 offset:16384
	ds_read_b128 v[148:151], v192 offset:17408
	ds_read_b128 v[170:173], v192 offset:18432
	ds_read_b128 v[174:177], v192 offset:19456
	ds_read_b128 v[178:181], v192 offset:20480
	ds_read_b128 v[182:185], v192 offset:21504
	ds_read_b128 v[196:199], v192 offset:22528
	ds_read_b128 v[200:203], v192 offset:23552
	global_load_lds_dwordx4 v[222:223], off
	v_lshl_add_u64 v[224:225], s[26:27], 0, v[158:159]
	s_mov_b32 m0, s34
	s_nop 0
	global_load_lds_dwordx4 v[224:225], off
	s_barrier
	s_waitcnt lgkmcnt(0)
	s_setprio 1
	s_waitcnt lgkmcnt(0)
	v_mfma_f32_16x16x32_bf16 v[60:63], v[128:131], v[144:147], 0
	v_mfma_f32_16x16x32_bf16 v[56:59], v[136:139], v[144:147], 0
	v_mfma_f32_16x16x32_bf16 v[44:47], v[128:131], v[170:173], 0
	v_mfma_f32_16x16x32_bf16 v[40:43], v[136:139], v[170:173], 0
	v_mfma_f32_16x16x32_bf16 v[28:31], v[128:131], v[178:181], 0
	v_mfma_f32_16x16x32_bf16 v[24:27], v[136:139], v[178:181], 0
	v_mfma_f32_16x16x32_bf16 v[12:15], v[128:131], v[196:199], 0
	v_mfma_f32_16x16x32_bf16 v[8:11], v[136:139], v[196:199], 0
	v_mfma_f32_16x16x32_bf16 v[60:63], v[132:135], v[148:151], v[60:63]
	v_mfma_f32_16x16x32_bf16 v[56:59], v[140:143], v[148:151], v[56:59]
	v_mfma_f32_16x16x32_bf16 v[44:47], v[132:135], v[174:177], v[44:47]
	v_mfma_f32_16x16x32_bf16 v[40:43], v[140:143], v[174:177], v[40:43]
	v_mfma_f32_16x16x32_bf16 v[28:31], v[132:135], v[182:185], v[28:31]
	v_mfma_f32_16x16x32_bf16 v[24:27], v[140:143], v[182:185], v[24:27]
	v_mfma_f32_16x16x32_bf16 v[12:15], v[132:135], v[200:203], v[12:15]
	v_mfma_f32_16x16x32_bf16 v[8:11], v[140:143], v[200:203], v[8:11]
	s_setprio 0
	s_barrier
; #define PG8_STAGE(bufoff, gbase, voff) do { _Pragma("unroll") for (int _i = 0; _i < 2; ++_i) \
;         __builtin_amdgcn_global_load_lds((const unsigned*)((const char*)(gbase) + (voff)[_i]), (LAS unsigned*)(lds + (bufoff) + ldsw + _i * 8192), 16, 0, 0); } while (0)
; #define PG8_LDA(dst, b, h) do { _Pragma("unroll") for (int m = 0; m < 4; ++m) _Pragma("unroll") for (int k = 0; k < 2; ++k) dst[m][k] = *(const LAS bf16x8*)(lds + PG8_SA(b, h) + aoff + m * 2048 + k * 1024); } while (0)
; #define PG8_LDB(dst, b, h) do { _Pragma("unroll") for (int n = 0; n < 2; ++n) _Pragma("unroll") for (int k = 0; k < 2; ++k) dst[n][k] = *(const LAS bf16x8*)(lds + PG8_SB(b, h) + boff + n * 2048 + k * 1024); } while (0)
; #define PG8_MMA(ai, bj, At, Bt) do { __builtin_amdgcn_s_setprio(1); _Pragma("unroll") for (int m = 0; m < 4; ++m) _Pragma("unroll") for (int n = 0; n < 2; ++n) _Pragma("unroll") for (int k = 0; k < 2; ++k) \
;         acc[ai][bj][m][n] = __builtin_amdgcn_mfma_f32_16x16x32_bf16(Bt[n][k], At[m][k], acc[ai][bj][m][n], 0, 0, 0); __builtin_amdgcn_s_setprio(0); } while (0)
; #define PG8_WAIT_V(n) asm volatile("s_waitcnt vmcnt(" #n ")" ::: "memory")
; #define PG8_WAIT_L(n) asm volatile("s_waitcnt lgkmcnt(" #n ")" ::: "memory")
; #define PG8_BAR __builtin_amdgcn_s_barrier()
; #define PG8_SCHED __builtin_amdgcn_sched_barrier(0)
; template <class Epi>
; __device__ __forceinline__ void gemm_phase(LAS unsigned char* lds, const Gemm g, const StaticOrder& S, const Epi& E) {
;     ...
;             PG8_STAGE(PG8_SB(0, 1), b2 + hstepB, voffB);
;             PG8_WAIT_V(6); PG8_BAR; PG8_MMA(1, 1, At, B1); PG8_BAR;
;             PG8_LDB(B0, 1, 0); PG8_SCHED; PG8_LDA(At, 1, 0); PG8_STAGE(PG8_SA(0, 1), a2 + hstepA, voffA);
;             PG8_WAIT_L(8); PG8_BAR; PG8_WAIT_L(0); PG8_MMA(0, 0, At, B0); PG8_BAR; PG8_SCHED;
;             PG8_LDB(B1, 1, 1); PG8_STAGE(PG8_SB(1, 0), b3, voffB);
	s_add_u32 s50, s24, 0x100000
	s_addc_u32 s51, s25, 0
	s_add_i32 s49, s43, s31
	v_lshl_add_u64 v[128:129], s[50:51], 0, v[156:157]
	s_mov_b32 m0, s49
	s_nop 0
	global_load_lds_dwordx4 v[128:129], off
	v_lshl_add_u64 v[128:129], s[50:51], 0, v[160:161]
	s_add_i32 m0, s49, 0x2000
	s_nop 0
	global_load_lds_dwordx4 v[128:129], off
	s_waitcnt vmcnt(6)
	s_barrier
	s_setprio 1
	v_mfma_f32_16x16x32_bf16 v[52:55], v[204:207], v[144:147], 0
	v_mfma_f32_16x16x32_bf16 v[48:51], v[212:215], v[144:147], 0
	v_mfma_f32_16x16x32_bf16 v[36:39], v[204:207], v[170:173], 0
	v_mfma_f32_16x16x32_bf16 v[32:35], v[212:215], v[170:173], 0
	v_mfma_f32_16x16x32_bf16 v[20:23], v[204:207], v[178:181], 0
	v_mfma_f32_16x16x32_bf16 v[16:19], v[212:215], v[178:181], 0
	v_mfma_f32_16x16x32_bf16 v[4:7], v[204:207], v[196:199], 0
	v_mfma_f32_16x16x32_bf16 v[0:3], v[212:215], v[196:199], 0
	v_mfma_f32_16x16x32_bf16 v[52:55], v[208:211], v[148:151], v[52:55]
	v_mfma_f32_16x16x32_bf16 v[48:51], v[216:219], v[148:151], v[48:51]
	v_mfma_f32_16x16x32_bf16 v[36:39], v[208:211], v[174:177], v[36:39]
	v_mfma_f32_16x16x32_bf16 v[32:35], v[216:219], v[174:177], v[32:35]
	v_mfma_f32_16x16x32_bf16 v[20:23], v[208:211], v[182:185], v[20:23]
	v_mfma_f32_16x16x32_bf16 v[16:19], v[216:219], v[182:185], v[16:19]
	v_mfma_f32_16x16x32_bf16 v[4:7], v[208:211], v[200:203], v[4:7]
	v_mfma_f32_16x16x32_bf16 v[0:3], v[216:219], v[200:203], v[0:3]
	s_setprio 0
	s_add_i32 s49, 0, 0x18000
	v_add_u32_e32 v140, s49, v189
	s_barrier
	ds_read_b128 v[128:131], v140
	ds_read_b128 v[132:135], v140 offset:1024
	ds_read_b128 v[136:139], v140 offset:2048
	ds_read_b128 v[140:143], v140 offset:3072
	s_add_u32 s26, s26, 0x100000
	s_addc_u32 s27, s27, 0
	s_mov_b32 m0, s35
	v_lshl_add_u64 v[204:205], s[26:27], 0, v[154:155]
	ds_read_b128 v[144:147], v192 offset:32768
	ds_read_b128 v[148:151], v192 offset:33792
	ds_read_b128 v[170:173], v192 offset:34816
	ds_read_b128 v[174:177], v192 offset:35840
	ds_read_b128 v[178:181], v192 offset:36864
	ds_read_b128 v[182:185], v192 offset:37888
	ds_read_b128 v[196:199], v192 offset:38912
	ds_read_b128 v[200:203], v192 offset:39936
	global_load_lds_dwordx4 v[204:205], off
	v_lshl_add_u64 v[204:205], s[26:27], 0, v[158:159]
	s_mov_b32 m0, s36
	s_nop 0
	global_load_lds_dwordx4 v[204:205], off
	s_waitcnt lgkmcnt(8)
	s_barrier
	s_waitcnt lgkmcnt(0)
	s_setprio 1
	s_waitcnt lgkmcnt(0)
	v_mfma_f32_16x16x32_bf16 v[124:127], v[128:131], v[144:147], v[124:127]
	v_mfma_f32_16x16x32_bf16 v[120:123], v[136:139], v[144:147], v[120:123]
	v_mfma_f32_16x16x32_bf16 v[108:111], v[128:131], v[170:173], v[108:111]
	v_mfma_f32_16x16x32_bf16 v[104:107], v[136:139], v[170:173], v[104:107]
	v_mfma_f32_16x16x32_bf16 v[92:95], v[128:131], v[178:181], v[92:95]
	v_mfma_f32_16x16x32_bf16 v[88:91], v[136:139], v[178:181], v[88:91]
	v_mfma_f32_16x16x32_bf16 v[76:79], v[128:131], v[196:199], v[76:79]
	v_mfma_f32_16x16x32_bf16 v[72:75], v[136:139], v[196:199], v[72:75]
	v_mfma_f32_16x16x32_bf16 v[124:127], v[132:135], v[148:151], v[124:127]
	v_mfma_f32_16x16x32_bf16 v[120:123], v[140:143], v[148:151], v[120:123]
	v_mfma_f32_16x16x32_bf16 v[108:111], v[132:135], v[174:177], v[108:111]
	v_mfma_f32_16x16x32_bf16 v[104:107], v[140:143], v[174:177], v[104:107]
	v_mfma_f32_16x16x32_bf16 v[92:95], v[132:135], v[182:185], v[92:95]
	v_mfma_f32_16x16x32_bf16 v[88:91], v[140:143], v[182:185], v[88:91]
	v_mfma_f32_16x16x32_bf16 v[76:79], v[132:135], v[200:203], v[76:79]
	v_mfma_f32_16x16x32_bf16 v[72:75], v[140:143], v[200:203], v[72:75]
	s_setprio 0
	s_barrier
	s_add_i32 s26, 0, 0x1c000
	s_add_i32 s27, s49, s31
	v_add_u32_e32 v195, s26, v189
	v_lshl_add_u64 v[186:187], v[186:187], 0, s[12:13]
	s_mov_b32 m0, s27
	ds_read_b128 v[204:207], v195
	ds_read_b128 v[208:211], v195 offset:1024
	ds_read_b128 v[212:215], v195 offset:2048
	ds_read_b128 v[216:219], v195 offset:3072
	global_load_lds_dwordx4 v[186:187], off
	v_lshl_add_u64 v[186:187], v[220:221], 0, s[12:13]
	s_add_i32 m0, s27, 0x2000
	s_nop 0
	global_load_lds_dwordx4 v[186:187], off
	s_barrier
; #define PG8_STAGE(bufoff, gbase, voff) do { _Pragma("unroll") for (int _i = 0; _i < 2; ++_i) \
;         __builtin_amdgcn_global_load_lds((const unsigned*)((const char*)(gbase) + (voff)[_i]), (LAS unsigned*)(lds + (bufoff) + ldsw + _i * 8192), 16, 0, 0); } while (0)
; #define PG8_LDA(dst, b, h) do { _Pragma("unroll") for (int m = 0; m < 4; ++m) _Pragma("unroll") for (int k = 0; k < 2; ++k) dst[m][k] = *(const LAS bf16x8*)(lds + PG8_SA(b, h) + aoff + m * 2048 + k * 1024); } while (0)
; #define PG8_MMA(ai, bj, At, Bt) do { __builtin_amdgcn_s_setprio(1); _Pragma("unroll") for (int m = 0; m < 4; ++m) _Pragma("unroll") for (int n = 0; n < 2; ++n) _Pragma("unroll") for (int k = 0; k < 2; ++k) \
;         acc[ai][bj][m][n] = __builtin_amdgcn_mfma_f32_16x16x32_bf16(Bt[n][k], At[m][k], acc[ai][bj][m][n], 0, 0, 0); __builtin_amdgcn_s_setprio(0); } while (0)
; #define PG8_WAIT_V(n) asm volatile("s_waitcnt vmcnt(" #n ")" ::: "memory")
; #define PG8_WAIT_L(n) asm volatile("s_waitcnt lgkmcnt(" #n ")" ::: "memory")
; #define PG8_BAR __builtin_amdgcn_s_barrier()
; #define PG8_SCHED __builtin_amdgcn_sched_barrier(0)
; template <class Epi>
; __device__ __forceinline__ void gemm_phase(LAS unsigned char* lds, const Gemm g, const StaticOrder& S, const Epi& E) {
;     ...
;             PG8_BAR; PG8_WAIT_L(0); PG8_MMA(0, 1, At, B1); PG8_BAR;
;             PG8_LDA(At, 1, 1); PG8_STAGE(PG8_SA(1, 0), a3, voffA);
;             PG8_BAR; PG8_WAIT_L(0); PG8_MMA(1, 0, At, B0); PG8_BAR; PG8_SCHED;
;             PG8_STAGE(PG8_SB(1, 1), b3 + hstepB, voffB);
;             PG8_WAIT_V(6); PG8_BAR; PG8_MMA(1, 1, At, B1); PG8_BAR;
;         }
	s_waitcnt lgkmcnt(0)
	s_setprio 1
	s_waitcnt lgkmcnt(0)
	v_mfma_f32_16x16x32_bf16 v[116:119], v[204:207], v[144:147], v[116:119]
	v_mfma_f32_16x16x32_bf16 v[112:115], v[212:215], v[144:147], v[112:115]
	v_mfma_f32_16x16x32_bf16 v[100:103], v[204:207], v[170:173], v[100:103]
	v_mfma_f32_16x16x32_bf16 v[96:99], v[212:215], v[170:173], v[96:99]
	v_mfma_f32_16x16x32_bf16 v[84:87], v[204:207], v[178:181], v[84:87]
	v_mfma_f32_16x16x32_bf16 v[80:83], v[212:215], v[178:181], v[80:83]
	v_mfma_f32_16x16x32_bf16 v[68:71], v[204:207], v[196:199], v[68:71]
	v_mfma_f32_16x16x32_bf16 v[64:67], v[212:215], v[196:199], v[64:67]
	v_mfma_f32_16x16x32_bf16 v[116:119], v[208:211], v[148:151], v[116:119]
	v_mfma_f32_16x16x32_bf16 v[112:115], v[216:219], v[148:151], v[112:115]
	v_mfma_f32_16x16x32_bf16 v[100:103], v[208:211], v[174:177], v[100:103]
	v_mfma_f32_16x16x32_bf16 v[96:99], v[216:219], v[174:177], v[96:99]
	v_mfma_f32_16x16x32_bf16 v[84:87], v[208:211], v[182:185], v[84:87]
	v_mfma_f32_16x16x32_bf16 v[80:83], v[216:219], v[182:185], v[80:83]
	v_mfma_f32_16x16x32_bf16 v[68:71], v[208:211], v[200:203], v[68:71]
	v_mfma_f32_16x16x32_bf16 v[64:67], v[216:219], v[200:203], v[64:67]
	s_setprio 0
	s_mov_b32 m0, s38
	v_lshl_add_u64 v[186:187], v[222:223], 0, s[12:13]
	s_barrier
	ds_read_b128 v[144:147], v192 offset:49152
	ds_read_b128 v[148:151], v192 offset:50176
	ds_read_b128 v[170:173], v192 offset:51200
	ds_read_b128 v[174:177], v192 offset:52224
	ds_read_b128 v[178:181], v192 offset:53248
	ds_read_b128 v[182:185], v192 offset:54272
	ds_read_b128 v[196:199], v192 offset:55296
	ds_read_b128 v[200:203], v192 offset:56320
	global_load_lds_dwordx4 v[186:187], off
	v_lshl_add_u64 v[186:187], v[224:225], 0, s[12:13]
	s_mov_b32 m0, s39
	s_nop 0
	global_load_lds_dwordx4 v[186:187], off
	s_barrier
	s_waitcnt lgkmcnt(0)
	s_setprio 1
	s_waitcnt lgkmcnt(0)
	v_mfma_f32_16x16x32_bf16 v[60:63], v[128:131], v[144:147], v[60:63]
	v_mfma_f32_16x16x32_bf16 v[56:59], v[136:139], v[144:147], v[56:59]
	v_mfma_f32_16x16x32_bf16 v[44:47], v[128:131], v[170:173], v[44:47]
	v_mfma_f32_16x16x32_bf16 v[40:43], v[136:139], v[170:173], v[40:43]
	v_mfma_f32_16x16x32_bf16 v[28:31], v[128:131], v[178:181], v[28:31]
	v_mfma_f32_16x16x32_bf16 v[24:27], v[136:139], v[178:181], v[24:27]
	v_mfma_f32_16x16x32_bf16 v[12:15], v[128:131], v[196:199], v[12:15]
	v_mfma_f32_16x16x32_bf16 v[8:11], v[136:139], v[196:199], v[8:11]
	v_mfma_f32_16x16x32_bf16 v[60:63], v[132:135], v[148:151], v[60:63]
	v_mfma_f32_16x16x32_bf16 v[56:59], v[140:143], v[148:151], v[56:59]
	v_mfma_f32_16x16x32_bf16 v[44:47], v[132:135], v[174:177], v[44:47]
	v_mfma_f32_16x16x32_bf16 v[40:43], v[140:143], v[174:177], v[40:43]
	v_mfma_f32_16x16x32_bf16 v[28:31], v[132:135], v[182:185], v[28:31]
	v_mfma_f32_16x16x32_bf16 v[24:27], v[140:143], v[182:185], v[24:27]
	v_mfma_f32_16x16x32_bf16 v[12:15], v[132:135], v[200:203], v[12:15]
	v_mfma_f32_16x16x32_bf16 v[8:11], v[140:143], v[200:203], v[8:11]
	s_setprio 0
	s_barrier
	s_add_u32 s24, s24, 0x100080
	s_addc_u32 s25, s25, 0
	s_add_i32 s26, s26, s31
	v_lshl_add_u64 v[128:129], s[24:25], 0, v[156:157]
	s_mov_b32 m0, s26
	s_nop 0
	global_load_lds_dwordx4 v[128:129], off
	v_lshl_add_u64 v[128:129], s[24:25], 0, v[160:161]
	s_add_i32 m0, s26, 0x2000
	s_nop 0
	global_load_lds_dwordx4 v[128:129], off
	s_waitcnt vmcnt(6)
	s_barrier
	s_setprio 1
	v_mfma_f32_16x16x32_bf16 v[52:55], v[204:207], v[144:147], v[52:55]
	v_mfma_f32_16x16x32_bf16 v[48:51], v[212:215], v[144:147], v[48:51]
	v_mfma_f32_16x16x32_bf16 v[36:39], v[204:207], v[170:173], v[36:39]
	v_mfma_f32_16x16x32_bf16 v[32:35], v[212:215], v[170:173], v[32:35]
	v_mfma_f32_16x16x32_bf16 v[20:23], v[204:207], v[178:181], v[20:23]
	v_mfma_f32_16x16x32_bf16 v[16:19], v[212:215], v[178:181], v[16:19]
	v_mfma_f32_16x16x32_bf16 v[4:7], v[204:207], v[196:199], v[4:7]
	v_mfma_f32_16x16x32_bf16 v[0:3], v[212:215], v[196:199], v[0:3]
	v_mfma_f32_16x16x32_bf16 v[52:55], v[208:211], v[148:151], v[52:55]
	v_mfma_f32_16x16x32_bf16 v[48:51], v[216:219], v[148:151], v[48:51]
	v_mfma_f32_16x16x32_bf16 v[36:39], v[208:211], v[174:177], v[36:39]
	v_mfma_f32_16x16x32_bf16 v[32:35], v[216:219], v[174:177], v[32:35]
	v_mfma_f32_16x16x32_bf16 v[20:23], v[208:211], v[182:185], v[20:23]
	v_mfma_f32_16x16x32_bf16 v[16:19], v[216:219], v[182:185], v[16:19]
	v_mfma_f32_16x16x32_bf16 v[4:7], v[208:211], v[200:203], v[4:7]
	v_mfma_f32_16x16x32_bf16 v[0:3], v[216:219], v[200:203], v[0:3]
	s_setprio 0
	s_add_i32 s48, s48, 2
	s_add_u32 s22, s22, 0x100
	s_addc_u32 s23, s23, 0
	s_add_u32 s46, s46, 0x100
	s_addc_u32 s47, s47, 0
	s_cmp_gt_u32 s48, 61
	s_barrier

; #define PG8_STAGE(bufoff, gbase, voff) do { _Pragma("unroll") for (int _i = 0; _i < 2; ++_i) \
;         __builtin_amdgcn_global_load_lds((const unsigned*)((const char*)(gbase) + (voff)[_i]), (LAS unsigned*)(lds + (bufoff) + ldsw + _i * 8192), 16, 0, 0); } while (0)
; #define PG8_LDA(dst, b, h) do { _Pragma("unroll") for (int m = 0; m < 4; ++m) _Pragma("unroll") for (int k = 0; k < 2; ++k) dst[m][k] = *(const LAS bf16x8*)(lds + PG8_SA(b, h) + aoff + m * 2048 + k * 1024); } while (0)
; #define PG8_LDB(dst, b, h) do { _Pragma("unroll") for (int n = 0; n < 2; ++n) _Pragma("unroll") for (int k = 0; k < 2; ++k) dst[n][k] = *(const LAS bf16x8*)(lds + PG8_SB(b, h) + boff + n * 2048 + k * 1024); } while (0)
; #define PG8_MMA(ai, bj, At, Bt) do { __builtin_amdgcn_s_setprio(1); _Pragma("unroll") for (int m = 0; m < 4; ++m) _Pragma("unroll") for (int n = 0; n < 2; ++n) _Pragma("unroll") for (int k = 0; k < 2; ++k) \
;         acc[ai][bj][m][n] = __builtin_amdgcn_mfma_f32_16x16x32_bf16(Bt[n][k], At[m][k], acc[ai][bj][m][n], 0, 0, 0); __builtin_amdgcn_s_setprio(0); } while (0)
; #define PG8_BAR __builtin_amdgcn_s_barrier()
; template <class Epi>
; __device__ __forceinline__ void gemm_phase(LAS unsigned char* lds, const Gemm g, const StaticOrder& S, const Epi& E) {
;     ...
;         const bool has_next = S.next(ui + 1, nxt);
;         const char* nA = has_next ? (const char*)g.A + (size_t)nxt.pm * tstepA : cA; const char* nB = has_next ? (const char*)g.Bt + (size_t)nxt.pn * tstepB : cB;
;         for (int t = 0; t < nt; t += 2) {
;             const bool last = (t == nt - 2);
;             const char* a1 = cA + (size_t)(t + 1) * kstep;
;             const char* a2 = last ? nA : cA + (size_t)(t + 2) * kstep; const char* b2 = last ? nB : cB + (size_t)(t + 2) * kstep;
;             const char* a3 = a2 + kstep; const char* b3 = b2 + kstep;
;             if (last) E.pre(cur, wr, fr, epre);
;             PG8_LDB(B0, 0, 0); PG8_SCHED; PG8_LDA(At, 0, 0); PG8_STAGE(PG8_SA(1, 1), a1 + hstepA, voffA);
;             PG8_WAIT_L(8); PG8_BAR; PG8_WAIT_L(0); PG8_MMA(0, 0, At, B0); PG8_BAR; PG8_SCHED;
;             PG8_LDB(B1, 0, 1); PG8_STAGE(PG8_SB(0, 0), b2, voffB);
;             PG8_BAR; PG8_WAIT_L(0); PG8_MMA(0, 1, At, B1); PG8_BAR;
;             PG8_LDA(At, 0, 1); PG8_STAGE(PG8_SA(0, 0), a2, voffA);
;             PG8_BAR; PG8_WAIT_L(0); PG8_MMA(1, 0, At, B0); PG8_BAR; PG8_SCHED;
.LBB0_921:
	s_ashr_i32 s13, s12, 31
	v_cmp_lt_i64_e32 vcc, s[14:15], v[142:143]
	s_lshl_b64 s[14:15], s[12:13], 19
	s_add_u32 s14, s76, s14
	s_addc_u32 s15, s77, s15
	s_and_b64 s[16:17], vcc, exec
	s_cselect_b32 s13, s15, s21
	s_cselect_b32 s43, s14, s20
	s_ashr_i32 s11, s10, 31
	s_lshl_b64 s[16:17], s[10:11], 19
	s_add_u32 s16, s9, s16
	s_addc_u32 s17, s26, s17
	s_and_b64 s[24:25], vcc, exec
	s_cselect_b32 s11, s17, s23
	s_cselect_b32 s44, s16, s22
	s_add_u32 s20, s20, 0x40080
	s_addc_u32 s21, s21, 0
	s_add_u32 s45, s22, 0x100
	s_addc_u32 s46, s23, 0
	s_mov_b32 s47, -2
	ds_read_b128 v[146:149], v173
	ds_read_b128 v[154:157], v173 offset:1024
	ds_read_b128 v[158:161], v173 offset:2048
	ds_read_b128 v[162:165], v173 offset:3072
	s_add_u32 s22, s20, 0xfffc0080
	s_addc_u32 s23, s21, -1
	s_cmp_eq_u32 s47, 12
	s_cselect_b32 s25, s13, s23
	s_cselect_b32 s24, s43, s22
	s_cselect_b32 s23, s11, s46
	s_cselect_b32 s22, s44, s45
	v_lshl_add_u64 v[150:151], s[20:21], 0, v[138:139]
	s_add_i32 m0, s19, 0xc000
	ds_read_b128 v[166:169], v174
	ds_read_b128 v[178:181], v174 offset:1024
	ds_read_b128 v[182:185], v174 offset:2048
	ds_read_b128 v[186:189], v174 offset:3072
	ds_read_b128 v[190:193], v174 offset:4096
	ds_read_b128 v[194:197], v174 offset:5120
	ds_read_b128 v[198:201], v174 offset:6144
	ds_read_b128 v[202:205], v174 offset:7168
	global_load_lds_dwordx4 v[150:151], off
	v_lshl_add_u64 v[150:151], s[20:21], 0, v[140:141]
	s_add_i32 m0, s19, 0xe000
	s_nop 0
	global_load_lds_dwordx4 v[150:151], off
	s_waitcnt lgkmcnt(8)
	s_barrier
	s_waitcnt lgkmcnt(0)
	s_setprio 1
	s_waitcnt lgkmcnt(0)
	v_mfma_f32_16x16x32_bf16 v[124:127], v[146:149], v[166:169], 0
	v_mfma_f32_16x16x32_bf16 v[120:123], v[158:161], v[166:169], 0
	v_mfma_f32_16x16x32_bf16 v[112:115], v[146:149], v[182:185], 0
	v_mfma_f32_16x16x32_bf16 v[104:107], v[158:161], v[182:185], 0
	v_mfma_f32_16x16x32_bf16 v[92:95], v[146:149], v[190:193], 0
	v_mfma_f32_16x16x32_bf16 v[88:91], v[158:161], v[190:193], 0
	v_mfma_f32_16x16x32_bf16 v[80:83], v[146:149], v[198:201], 0
	v_mfma_f32_16x16x32_bf16 v[72:75], v[158:161], v[198:201], 0
	v_mfma_f32_16x16x32_bf16 v[124:127], v[154:157], v[178:181], v[124:127]
	v_mfma_f32_16x16x32_bf16 v[120:123], v[162:165], v[178:181], v[120:123]
	v_mfma_f32_16x16x32_bf16 v[112:115], v[154:157], v[186:189], v[112:115]
	v_mfma_f32_16x16x32_bf16 v[104:107], v[162:165], v[186:189], v[104:107]
	v_mfma_f32_16x16x32_bf16 v[92:95], v[154:157], v[194:197], v[92:95]
	v_mfma_f32_16x16x32_bf16 v[88:91], v[162:165], v[194:197], v[88:91]
	v_mfma_f32_16x16x32_bf16 v[80:83], v[154:157], v[202:205], v[80:83]
	v_mfma_f32_16x16x32_bf16 v[72:75], v[162:165], v[202:205], v[72:75]
	s_setprio 0
	s_barrier
	s_add_i32 s48, s38, s27
	v_lshl_add_u64 v[150:151], s[22:23], 0, v[132:133]
	s_mov_b32 m0, s48
	ds_read_b128 v[206:209], v175
	ds_read_b128 v[210:213], v175 offset:1024
	ds_read_b128 v[214:217], v175 offset:2048
	ds_read_b128 v[218:221], v175 offset:3072
	global_load_lds_dwordx4 v[150:151], off
	v_lshl_add_u64 v[222:223], s[22:23], 0, v[128:129]
	s_add_i32 m0, s48, 0x2000
	s_nop 0
	global_load_lds_dwordx4 v[222:223], off
	s_barrier
	s_waitcnt lgkmcnt(0)
	s_setprio 1
	s_waitcnt lgkmcnt(0)
	v_mfma_f32_16x16x32_bf16 v[116:119], v[206:209], v[166:169], 0
	v_mfma_f32_16x16x32_bf16 v[108:111], v[214:217], v[166:169], 0
	v_mfma_f32_16x16x32_bf16 v[100:103], v[206:209], v[182:185], 0
	v_mfma_f32_16x16x32_bf16 v[96:99], v[214:217], v[182:185], 0
	v_mfma_f32_16x16x32_bf16 v[84:87], v[206:209], v[190:193], 0
	v_mfma_f32_16x16x32_bf16 v[76:79], v[214:217], v[190:193], 0
	v_mfma_f32_16x16x32_bf16 v[68:71], v[206:209], v[198:201], 0
	v_mfma_f32_16x16x32_bf16 v[64:67], v[214:217], v[198:201], 0
	v_mfma_f32_16x16x32_bf16 v[116:119], v[210:213], v[178:181], v[116:119]
	v_mfma_f32_16x16x32_bf16 v[108:111], v[218:221], v[178:181], v[108:111]
	v_mfma_f32_16x16x32_bf16 v[100:103], v[210:213], v[186:189], v[100:103]
	v_mfma_f32_16x16x32_bf16 v[96:99], v[218:221], v[186:189], v[96:99]
	v_mfma_f32_16x16x32_bf16 v[84:87], v[210:213], v[194:197], v[84:87]
	v_mfma_f32_16x16x32_bf16 v[76:79], v[218:221], v[194:197], v[76:79]
	v_mfma_f32_16x16x32_bf16 v[68:71], v[210:213], v[202:205], v[68:71]
	v_mfma_f32_16x16x32_bf16 v[64:67], v[218:221], v[202:205], v[64:67]
	s_setprio 0
	s_mov_b32 m0, s19
	v_lshl_add_u64 v[224:225], s[24:25], 0, v[134:135]
	s_barrier
	ds_read_b128 v[166:169], v174 offset:16384
	ds_read_b128 v[178:181], v174 offset:17408
	ds_read_b128 v[182:185], v174 offset:18432
	ds_read_b128 v[186:189], v174 offset:19456
	ds_read_b128 v[190:193], v174 offset:20480
	ds_read_b128 v[194:197], v174 offset:21504
	ds_read_b128 v[198:201], v174 offset:22528
	ds_read_b128 v[202:205], v174 offset:23552
	global_load_lds_dwordx4 v[224:225], off
	v_lshl_add_u64 v[226:227], s[24:25], 0, v[130:131]
	s_mov_b32 m0, s30
	s_nop 0
	global_load_lds_dwordx4 v[226:227], off
	s_barrier
	s_waitcnt lgkmcnt(0)
	s_setprio 1
	s_waitcnt lgkmcnt(0)
	v_mfma_f32_16x16x32_bf16 v[60:63], v[146:149], v[166:169], 0
	v_mfma_f32_16x16x32_bf16 v[56:59], v[158:161], v[166:169], 0
	v_mfma_f32_16x16x32_bf16 v[48:51], v[146:149], v[182:185], 0
	v_mfma_f32_16x16x32_bf16 v[40:43], v[158:161], v[182:185], 0
	v_mfma_f32_16x16x32_bf16 v[32:35], v[146:149], v[190:193], 0
	v_mfma_f32_16x16x32_bf16 v[24:27], v[158:161], v[190:193], 0
	v_mfma_f32_16x16x32_bf16 v[16:19], v[146:149], v[198:201], 0
	v_mfma_f32_16x16x32_bf16 v[8:11], v[158:161], v[198:201], 0
	v_mfma_f32_16x16x32_bf16 v[60:63], v[154:157], v[178:181], v[60:63]
	v_mfma_f32_16x16x32_bf16 v[56:59], v[162:165], v[178:181], v[56:59]
	v_mfma_f32_16x16x32_bf16 v[48:51], v[154:157], v[186:189], v[48:51]
	v_mfma_f32_16x16x32_bf16 v[40:43], v[162:165], v[186:189], v[40:43]
	v_mfma_f32_16x16x32_bf16 v[32:35], v[154:157], v[194:197], v[32:35]
	v_mfma_f32_16x16x32_bf16 v[24:27], v[162:165], v[194:197], v[24:27]
	v_mfma_f32_16x16x32_bf16 v[16:19], v[154:157], v[202:205], v[16:19]
	v_mfma_f32_16x16x32_bf16 v[8:11], v[162:165], v[202:205], v[8:11]
	s_setprio 0
	s_barrier
; #define PG8_STAGE(bufoff, gbase, voff) do { _Pragma("unroll") for (int _i = 0; _i < 2; ++_i) \
;         __builtin_amdgcn_global_load_lds((const unsigned*)((const char*)(gbase) + (voff)[_i]), (LAS unsigned*)(lds + (bufoff) + ldsw + _i * 8192), 16, 0, 0); } while (0)
; #define PG8_LDA(dst, b, h) do { _Pragma("unroll") for (int m = 0; m < 4; ++m) _Pragma("unroll") for (int k = 0; k < 2; ++k) dst[m][k] = *(const LAS bf16x8*)(lds + PG8_SA(b, h) + aoff + m * 2048 + k * 1024); } while (0)
; #define PG8_LDB(dst, b, h) do { _Pragma("unroll") for (int n = 0; n < 2; ++n) _Pragma("unroll") for (int k = 0; k < 2; ++k) dst[n][k] = *(const LAS bf16x8*)(lds + PG8_SB(b, h) + boff + n * 2048 + k * 1024); } while (0)
; #define PG8_MMA(ai, bj, At, Bt) do { __builtin_amdgcn_s_setprio(1); _Pragma("unroll") for (int m = 0; m < 4; ++m) _Pragma("unroll") for (int n = 0; n < 2; ++n) _Pragma("unroll") for (int k = 0; k < 2; ++k) \
;         acc[ai][bj][m][n] = __builtin_amdgcn_mfma_f32_16x16x32_bf16(Bt[n][k], At[m][k], acc[ai][bj][m][n], 0, 0, 0); __builtin_amdgcn_s_setprio(0); } while (0)
; #define PG8_WAIT_V(n) asm volatile("s_waitcnt vmcnt(" #n ")" ::: "memory")
; #define PG8_WAIT_L(n) asm volatile("s_waitcnt lgkmcnt(" #n ")" ::: "memory")
; #define PG8_BAR __builtin_amdgcn_s_barrier()
; #define PG8_SCHED __builtin_amdgcn_sched_barrier(0)
; template <class Epi>
; __device__ __forceinline__ void gemm_phase(LAS unsigned char* lds, const Gemm g, const StaticOrder& S, const Epi& E) {
;     ...
;             PG8_STAGE(PG8_SB(0, 1), b2 + hstepB, voffB);
;             PG8_WAIT_V(6); PG8_BAR; PG8_MMA(1, 1, At, B1); PG8_BAR;
;             PG8_LDB(B0, 1, 0); PG8_SCHED; PG8_LDA(At, 1, 0); PG8_STAGE(PG8_SA(0, 1), a2 + hstepA, voffA);
;             PG8_WAIT_L(8); PG8_BAR; PG8_WAIT_L(0); PG8_MMA(0, 0, At, B0); PG8_BAR; PG8_SCHED;
;             PG8_LDB(B1, 1, 1); PG8_STAGE(PG8_SB(1, 0), b3, voffB);
;             PG8_BAR; PG8_WAIT_L(0); PG8_MMA(0, 1, At, B1); PG8_BAR;
;             PG8_LDA(At, 1, 1); PG8_STAGE(PG8_SA(1, 0), a3, voffA);
	s_add_u32 s48, s22, 0x40000
	s_addc_u32 s49, s23, 0
	s_add_i32 s50, s39, s27
	v_lshl_add_u64 v[146:147], s[48:49], 0, v[132:133]
	s_mov_b32 m0, s50
	s_nop 0
	global_load_lds_dwordx4 v[146:147], off
	v_lshl_add_u64 v[146:147], s[48:49], 0, v[128:129]
	s_add_i32 m0, s50, 0x2000
	s_nop 0
	global_load_lds_dwordx4 v[146:147], off
	s_waitcnt vmcnt(6)
	s_barrier
	s_setprio 1
	v_mfma_f32_16x16x32_bf16 v[52:55], v[206:209], v[166:169], 0
	v_mfma_f32_16x16x32_bf16 v[44:47], v[214:217], v[166:169], 0
	v_mfma_f32_16x16x32_bf16 v[36:39], v[206:209], v[182:185], 0
	v_mfma_f32_16x16x32_bf16 v[28:31], v[214:217], v[182:185], 0
	v_mfma_f32_16x16x32_bf16 v[20:23], v[206:209], v[190:193], 0
	v_mfma_f32_16x16x32_bf16 v[12:15], v[214:217], v[190:193], 0
	v_mfma_f32_16x16x32_bf16 v[4:7], v[206:209], v[198:201], 0
	v_mfma_f32_16x16x32_bf16 v[0:3], v[214:217], v[198:201], 0
	v_mfma_f32_16x16x32_bf16 v[52:55], v[210:213], v[178:181], v[52:55]
	v_mfma_f32_16x16x32_bf16 v[44:47], v[218:221], v[178:181], v[44:47]
	v_mfma_f32_16x16x32_bf16 v[36:39], v[210:213], v[186:189], v[36:39]
	v_mfma_f32_16x16x32_bf16 v[28:31], v[218:221], v[186:189], v[28:31]
	v_mfma_f32_16x16x32_bf16 v[20:23], v[210:213], v[194:197], v[20:23]
	v_mfma_f32_16x16x32_bf16 v[12:15], v[218:221], v[194:197], v[12:15]
	v_mfma_f32_16x16x32_bf16 v[4:7], v[210:213], v[202:205], v[4:7]
	v_mfma_f32_16x16x32_bf16 v[0:3], v[218:221], v[202:205], v[0:3]
	s_setprio 0
	s_add_i32 s48, 0, 0x18000
	v_add_u32_e32 v162, s48, v171
	s_barrier
	ds_read_b128 v[146:149], v162
	ds_read_b128 v[154:157], v162 offset:1024
	ds_read_b128 v[158:161], v162 offset:2048
	ds_read_b128 v[162:165], v162 offset:3072
	s_add_u32 s24, s24, 0x40000
	s_addc_u32 s25, s25, 0
	s_mov_b32 m0, s31
	v_lshl_add_u64 v[206:207], s[24:25], 0, v[134:135]
	ds_read_b128 v[166:169], v174 offset:32768
	ds_read_b128 v[178:181], v174 offset:33792
	ds_read_b128 v[182:185], v174 offset:34816
	ds_read_b128 v[186:189], v174 offset:35840
	ds_read_b128 v[190:193], v174 offset:36864
	ds_read_b128 v[194:197], v174 offset:37888
	ds_read_b128 v[198:201], v174 offset:38912
	ds_read_b128 v[202:205], v174 offset:39936
	global_load_lds_dwordx4 v[206:207], off
	v_lshl_add_u64 v[206:207], s[24:25], 0, v[130:131]
	s_mov_b32 m0, s33
	s_nop 0
	global_load_lds_dwordx4 v[206:207], off
	s_waitcnt lgkmcnt(8)
	s_barrier
	s_waitcnt lgkmcnt(0)
	s_setprio 1
	s_waitcnt lgkmcnt(0)
	v_mfma_f32_16x16x32_bf16 v[124:127], v[146:149], v[166:169], v[124:127]
	v_mfma_f32_16x16x32_bf16 v[120:123], v[158:161], v[166:169], v[120:123]
	v_mfma_f32_16x16x32_bf16 v[112:115], v[146:149], v[182:185], v[112:115]
	v_mfma_f32_16x16x32_bf16 v[104:107], v[158:161], v[182:185], v[104:107]
	v_mfma_f32_16x16x32_bf16 v[92:95], v[146:149], v[190:193], v[92:95]
	v_mfma_f32_16x16x32_bf16 v[88:91], v[158:161], v[190:193], v[88:91]
	v_mfma_f32_16x16x32_bf16 v[80:83], v[146:149], v[198:201], v[80:83]
	v_mfma_f32_16x16x32_bf16 v[72:75], v[158:161], v[198:201], v[72:75]
	v_mfma_f32_16x16x32_bf16 v[124:127], v[154:157], v[178:181], v[124:127]
	v_mfma_f32_16x16x32_bf16 v[120:123], v[162:165], v[178:181], v[120:123]
	v_mfma_f32_16x16x32_bf16 v[112:115], v[154:157], v[186:189], v[112:115]
	v_mfma_f32_16x16x32_bf16 v[104:107], v[162:165], v[186:189], v[104:107]
	v_mfma_f32_16x16x32_bf16 v[92:95], v[154:157], v[194:197], v[92:95]
	v_mfma_f32_16x16x32_bf16 v[88:91], v[162:165], v[194:197], v[88:91]
	v_mfma_f32_16x16x32_bf16 v[80:83], v[154:157], v[202:205], v[80:83]
	v_mfma_f32_16x16x32_bf16 v[72:75], v[162:165], v[202:205], v[72:75]
	s_setprio 0
	s_barrier
	s_add_i32 s24, 0, 0x1c000
	s_add_i32 s25, s48, s27
	v_add_u32_e32 v177, s24, v171
	v_lshl_add_u64 v[150:151], v[150:151], 0, s[4:5]
	s_mov_b32 m0, s25
	ds_read_b128 v[206:209], v177
	ds_read_b128 v[210:213], v177 offset:1024
	ds_read_b128 v[214:217], v177 offset:2048
	ds_read_b128 v[218:221], v177 offset:3072
	global_load_lds_dwordx4 v[150:151], off
	v_lshl_add_u64 v[150:151], v[222:223], 0, s[4:5]
	s_add_i32 m0, s25, 0x2000
	s_nop 0
	global_load_lds_dwordx4 v[150:151], off
	s_barrier
; #define PG8_STAGE(bufoff, gbase, voff) do { _Pragma("unroll") for (int _i = 0; _i < 2; ++_i) \
;         __builtin_amdgcn_global_load_lds((const unsigned*)((const char*)(gbase) + (voff)[_i]), (LAS unsigned*)(lds + (bufoff) + ldsw + _i * 8192), 16, 0, 0); } while (0)
; #define PG8_LDA(dst, b, h) do { _Pragma("unroll") for (int m = 0; m < 4; ++m) _Pragma("unroll") for (int k = 0; k < 2; ++k) dst[m][k] = *(const LAS bf16x8*)(lds + PG8_SA(b, h) + aoff + m * 2048 + k * 1024); } while (0)
; #define PG8_MMA(ai, bj, At, Bt) do { __builtin_amdgcn_s_setprio(1); _Pragma("unroll") for (int m = 0; m < 4; ++m) _Pragma("unroll") for (int n = 0; n < 2; ++n) _Pragma("unroll") for (int k = 0; k < 2; ++k) \
;         acc[ai][bj][m][n] = __builtin_amdgcn_mfma_f32_16x16x32_bf16(Bt[n][k], At[m][k], acc[ai][bj][m][n], 0, 0, 0); __builtin_amdgcn_s_setprio(0); } while (0)
; #define PG8_WAIT_V(n) asm volatile("s_waitcnt vmcnt(" #n ")" ::: "memory")
; #define PG8_WAIT_L(n) asm volatile("s_waitcnt lgkmcnt(" #n ")" ::: "memory")
; #define PG8_BAR __builtin_amdgcn_s_barrier()
; #define PG8_SCHED __builtin_amdgcn_sched_barrier(0)
; template <class Epi>
; __device__ __forceinline__ void gemm_phase(LAS unsigned char* lds, const Gemm g, const StaticOrder& S, const Epi& E) {
;     ...
;             PG8_BAR; PG8_WAIT_L(0); PG8_MMA(0, 1, At, B1); PG8_BAR;
;             PG8_LDA(At, 1, 1); PG8_STAGE(PG8_SA(1, 0), a3, voffA);
;             PG8_BAR; PG8_WAIT_L(0); PG8_MMA(1, 0, At, B0); PG8_BAR; PG8_SCHED;
;             PG8_STAGE(PG8_SB(1, 1), b3 + hstepB, voffB);
;             PG8_WAIT_V(6); PG8_BAR; PG8_MMA(1, 1, At, B1); PG8_BAR;
;         }
	s_waitcnt lgkmcnt(0)
	s_setprio 1
	s_waitcnt lgkmcnt(0)
	v_mfma_f32_16x16x32_bf16 v[116:119], v[206:209], v[166:169], v[116:119]
	v_mfma_f32_16x16x32_bf16 v[108:111], v[214:217], v[166:169], v[108:111]
	v_mfma_f32_16x16x32_bf16 v[100:103], v[206:209], v[182:185], v[100:103]
	v_mfma_f32_16x16x32_bf16 v[96:99], v[214:217], v[182:185], v[96:99]
	v_mfma_f32_16x16x32_bf16 v[84:87], v[206:209], v[190:193], v[84:87]
	v_mfma_f32_16x16x32_bf16 v[76:79], v[214:217], v[190:193], v[76:79]
	v_mfma_f32_16x16x32_bf16 v[68:71], v[206:209], v[198:201], v[68:71]
	v_mfma_f32_16x16x32_bf16 v[64:67], v[214:217], v[198:201], v[64:67]
	v_mfma_f32_16x16x32_bf16 v[116:119], v[210:213], v[178:181], v[116:119]
	v_mfma_f32_16x16x32_bf16 v[108:111], v[218:221], v[178:181], v[108:111]
	v_mfma_f32_16x16x32_bf16 v[100:103], v[210:213], v[186:189], v[100:103]
	v_mfma_f32_16x16x32_bf16 v[96:99], v[218:221], v[186:189], v[96:99]
	v_mfma_f32_16x16x32_bf16 v[84:87], v[210:213], v[194:197], v[84:87]
	v_mfma_f32_16x16x32_bf16 v[76:79], v[218:221], v[194:197], v[76:79]
	v_mfma_f32_16x16x32_bf16 v[68:71], v[210:213], v[202:205], v[68:71]
	v_mfma_f32_16x16x32_bf16 v[64:67], v[218:221], v[202:205], v[64:67]
	s_setprio 0
	s_mov_b32 m0, s35
	v_lshl_add_u64 v[150:151], v[224:225], 0, s[4:5]
	s_barrier
	ds_read_b128 v[166:169], v174 offset:49152
	ds_read_b128 v[178:181], v174 offset:50176
	ds_read_b128 v[182:185], v174 offset:51200
	ds_read_b128 v[186:189], v174 offset:52224
	ds_read_b128 v[190:193], v174 offset:53248
	ds_read_b128 v[194:197], v174 offset:54272
	ds_read_b128 v[198:201], v174 offset:55296
	ds_read_b128 v[202:205], v174 offset:56320
	global_load_lds_dwordx4 v[150:151], off
	v_lshl_add_u64 v[150:151], v[226:227], 0, s[4:5]
	s_mov_b32 m0, s36
	s_nop 0
	global_load_lds_dwordx4 v[150:151], off
	s_barrier
	s_waitcnt lgkmcnt(0)
	s_setprio 1
	s_waitcnt lgkmcnt(0)
	v_mfma_f32_16x16x32_bf16 v[60:63], v[146:149], v[166:169], v[60:63]
	v_mfma_f32_16x16x32_bf16 v[56:59], v[158:161], v[166:169], v[56:59]
	v_mfma_f32_16x16x32_bf16 v[48:51], v[146:149], v[182:185], v[48:51]
	v_mfma_f32_16x16x32_bf16 v[40:43], v[158:161], v[182:185], v[40:43]
	v_mfma_f32_16x16x32_bf16 v[32:35], v[146:149], v[190:193], v[32:35]
	v_mfma_f32_16x16x32_bf16 v[24:27], v[158:161], v[190:193], v[24:27]
	v_mfma_f32_16x16x32_bf16 v[16:19], v[146:149], v[198:201], v[16:19]
	v_mfma_f32_16x16x32_bf16 v[8:11], v[158:161], v[198:201], v[8:11]
	v_mfma_f32_16x16x32_bf16 v[60:63], v[154:157], v[178:181], v[60:63]
	v_mfma_f32_16x16x32_bf16 v[56:59], v[162:165], v[178:181], v[56:59]
	v_mfma_f32_16x16x32_bf16 v[48:51], v[154:157], v[186:189], v[48:51]
	v_mfma_f32_16x16x32_bf16 v[40:43], v[162:165], v[186:189], v[40:43]
	v_mfma_f32_16x16x32_bf16 v[32:35], v[154:157], v[194:197], v[32:35]
	v_mfma_f32_16x16x32_bf16 v[24:27], v[162:165], v[194:197], v[24:27]
	v_mfma_f32_16x16x32_bf16 v[16:19], v[154:157], v[202:205], v[16:19]
	v_mfma_f32_16x16x32_bf16 v[8:11], v[162:165], v[202:205], v[8:11]
	s_setprio 0
	s_barrier
	s_add_u32 s22, s22, 0x40080
	s_addc_u32 s23, s23, 0
	s_add_i32 s24, s24, s27
	v_lshl_add_u64 v[146:147], s[22:23], 0, v[132:133]
	s_mov_b32 m0, s24
	s_nop 0
	global_load_lds_dwordx4 v[146:147], off
	v_lshl_add_u64 v[146:147], s[22:23], 0, v[128:129]
	s_add_i32 m0, s24, 0x2000
	s_nop 0
	global_load_lds_dwordx4 v[146:147], off
	s_waitcnt vmcnt(6)
	s_barrier
	s_setprio 1
	v_mfma_f32_16x16x32_bf16 v[52:55], v[206:209], v[166:169], v[52:55]
	v_mfma_f32_16x16x32_bf16 v[44:47], v[214:217], v[166:169], v[44:47]
	v_mfma_f32_16x16x32_bf16 v[36:39], v[206:209], v[182:185], v[36:39]
	v_mfma_f32_16x16x32_bf16 v[28:31], v[214:217], v[182:185], v[28:31]
	v_mfma_f32_16x16x32_bf16 v[20:23], v[206:209], v[190:193], v[20:23]
	v_mfma_f32_16x16x32_bf16 v[12:15], v[214:217], v[190:193], v[12:15]
	v_mfma_f32_16x16x32_bf16 v[4:7], v[206:209], v[198:201], v[4:7]
	v_mfma_f32_16x16x32_bf16 v[0:3], v[214:217], v[198:201], v[0:3]
	v_mfma_f32_16x16x32_bf16 v[52:55], v[210:213], v[178:181], v[52:55]
	v_mfma_f32_16x16x32_bf16 v[44:47], v[218:221], v[178:181], v[44:47]
	v_mfma_f32_16x16x32_bf16 v[36:39], v[210:213], v[186:189], v[36:39]
	v_mfma_f32_16x16x32_bf16 v[28:31], v[218:221], v[186:189], v[28:31]
	v_mfma_f32_16x16x32_bf16 v[20:23], v[210:213], v[194:197], v[20:23]
	v_mfma_f32_16x16x32_bf16 v[12:15], v[218:221], v[194:197], v[12:15]
	v_mfma_f32_16x16x32_bf16 v[4:7], v[210:213], v[202:205], v[4:7]
	v_mfma_f32_16x16x32_bf16 v[0:3], v[218:221], v[202:205], v[0:3]
	s_setprio 0
	s_add_i32 s47, s47, 2
	s_add_u32 s20, s20, 0x100
	s_addc_u32 s21, s21, 0
	s_add_u32 s45, s45, 0x100
	s_addc_u32 s46, s46, 0
	s_cmp_gt_u32 s47, 13
	s_barrier

; #define PG8_STAGE(bufoff, gbase, voff) do { _Pragma("unroll") for (int _i = 0; _i < 2; ++_i) \
;         __builtin_amdgcn_global_load_lds((const unsigned*)((const char*)(gbase) + (voff)[_i]), (LAS unsigned*)(lds + (bufoff) + ldsw + _i * 8192), 16, 0, 0); } while (0)
; #define PG8_LDA(dst, b, h) do { _Pragma("unroll") for (int m = 0; m < 4; ++m) _Pragma("unroll") for (int k = 0; k < 2; ++k) dst[m][k] = *(const LAS bf16x8*)(lds + PG8_SA(b, h) + aoff + m * 2048 + k * 1024); } while (0)
; #define PG8_LDB(dst, b, h) do { _Pragma("unroll") for (int n = 0; n < 2; ++n) _Pragma("unroll") for (int k = 0; k < 2; ++k) dst[n][k] = *(const LAS bf16x8*)(lds + PG8_SB(b, h) + boff + n * 2048 + k * 1024); } while (0)
; #define PG8_MMA(ai, bj, At, Bt) do { __builtin_amdgcn_s_setprio(1); _Pragma("unroll") for (int m = 0; m < 4; ++m) _Pragma("unroll") for (int n = 0; n < 2; ++n) _Pragma("unroll") for (int k = 0; k < 2; ++k) \
;         acc[ai][bj][m][n] = __builtin_amdgcn_mfma_f32_16x16x32_bf16(Bt[n][k], At[m][k], acc[ai][bj][m][n], 0, 0, 0); __builtin_amdgcn_s_setprio(0); } while (0)
; #define PG8_BAR __builtin_amdgcn_s_barrier()
; template <class Epi>
; __device__ __forceinline__ void gemm_phase(LAS unsigned char* lds, const Gemm g, const StaticOrder& S, const Epi& E) {
;     ...
;         const bool has_next = S.next(ui + 1, nxt);
;         const char* nA = has_next ? (const char*)g.A + (size_t)nxt.pm * tstepA : cA; const char* nB = has_next ? (const char*)g.Bt + (size_t)nxt.pn * tstepB : cB;
;         for (int t = 0; t < nt; t += 2) {
;             const bool last = (t == nt - 2);
;             const char* a1 = cA + (size_t)(t + 1) * kstep;
;             const char* a2 = last ? nA : cA + (size_t)(t + 2) * kstep; const char* b2 = last ? nB : cB + (size_t)(t + 2) * kstep;
;             const char* a3 = a2 + kstep; const char* b3 = b2 + kstep;
;             if (last) E.pre(cur, wr, fr, epre);
;             PG8_LDB(B0, 0, 0); PG8_SCHED; PG8_LDA(At, 0, 0); PG8_STAGE(PG8_SA(1, 1), a1 + hstepA, voffA);
;             PG8_WAIT_L(8); PG8_BAR; PG8_WAIT_L(0); PG8_MMA(0, 0, At, B0); PG8_BAR; PG8_SCHED;
;             PG8_LDB(B1, 0, 1); PG8_STAGE(PG8_SB(0, 0), b2, voffB);
;             PG8_BAR; PG8_WAIT_L(0); PG8_MMA(0, 1, At, B1); PG8_BAR;
;             PG8_LDA(At, 0, 1); PG8_STAGE(PG8_SA(0, 0), a2, voffA);
;             PG8_BAR; PG8_WAIT_L(0); PG8_MMA(1, 0, At, B0); PG8_BAR; PG8_SCHED;
.LBB0_1117:
	s_ashr_i32 s17, s16, 31
	s_lshl_b64 s[20:21], s[16:17], 19
	s_add_u32 s20, s27, s20
	s_addc_u32 s21, s28, s21
	s_and_b64 s[4:5], s[4:5], exec
	s_cselect_b32 s17, s21, s23
	s_cselect_b32 s43, s20, s22
	s_add_u32 s4, s24, 0x140080
	s_addc_u32 s5, s25, 0
	s_add_u32 s44, s22, 0x100
	s_addc_u32 s45, s23, 0
	s_mov_b32 s46, -2
	s_waitcnt lgkmcnt(0)
	ds_read_b128 v[128:131], v190
	ds_read_b128 v[132:135], v190 offset:1024
	ds_read_b128 v[136:139], v190 offset:2048
	ds_read_b128 v[140:143], v190 offset:3072
	s_add_u32 s22, s4, 0xffec0080
	s_addc_u32 s23, s5, -1
	s_cmp_eq_u32 s46, 12
	s_cselect_b32 s25, s19, s23
	s_cselect_b32 s24, s18, s22
	s_cselect_b32 s23, s17, s45
	s_cselect_b32 s22, s43, s44
	v_lshl_add_u64 v[186:187], s[4:5], 0, v[162:163]
	s_add_i32 m0, s9, 0xc000
	ds_read_b128 v[144:147], v191
	ds_read_b128 v[148:151], v191 offset:1024
	ds_read_b128 v[170:173], v191 offset:2048
	ds_read_b128 v[174:177], v191 offset:3072
	ds_read_b128 v[178:181], v191 offset:4096
	ds_read_b128 v[182:185], v191 offset:5120
	ds_read_b128 v[194:197], v191 offset:6144
	ds_read_b128 v[198:201], v191 offset:7168
	global_load_lds_dwordx4 v[186:187], off
	v_lshl_add_u64 v[186:187], s[4:5], 0, v[164:165]
	s_add_i32 m0, s9, 0xe000
	s_nop 0
	global_load_lds_dwordx4 v[186:187], off
	s_waitcnt lgkmcnt(8)
	s_barrier
	s_waitcnt lgkmcnt(0)
	s_setprio 1
	s_waitcnt lgkmcnt(0)
	v_mfma_f32_16x16x32_bf16 v[124:127], v[128:131], v[144:147], 0
	v_mfma_f32_16x16x32_bf16 v[120:123], v[136:139], v[144:147], 0
	v_mfma_f32_16x16x32_bf16 v[108:111], v[128:131], v[170:173], 0
	v_mfma_f32_16x16x32_bf16 v[104:107], v[136:139], v[170:173], 0
	v_mfma_f32_16x16x32_bf16 v[92:95], v[128:131], v[178:181], 0
	v_mfma_f32_16x16x32_bf16 v[88:91], v[136:139], v[178:181], 0
	v_mfma_f32_16x16x32_bf16 v[76:79], v[128:131], v[194:197], 0
	v_mfma_f32_16x16x32_bf16 v[72:75], v[136:139], v[194:197], 0
	v_mfma_f32_16x16x32_bf16 v[124:127], v[132:135], v[148:151], v[124:127]
	v_mfma_f32_16x16x32_bf16 v[120:123], v[140:143], v[148:151], v[120:123]
	v_mfma_f32_16x16x32_bf16 v[108:111], v[132:135], v[174:177], v[108:111]
	v_mfma_f32_16x16x32_bf16 v[104:107], v[140:143], v[174:177], v[104:107]
	v_mfma_f32_16x16x32_bf16 v[92:95], v[132:135], v[182:185], v[92:95]
	v_mfma_f32_16x16x32_bf16 v[88:91], v[140:143], v[182:185], v[88:91]
	v_mfma_f32_16x16x32_bf16 v[76:79], v[132:135], v[198:201], v[76:79]
	v_mfma_f32_16x16x32_bf16 v[72:75], v[140:143], v[198:201], v[72:75]
	s_setprio 0
	s_barrier
	s_add_i32 s47, s40, s29
	v_lshl_add_u64 v[186:187], s[22:23], 0, v[156:157]
	s_mov_b32 m0, s47
	ds_read_b128 v[202:205], v192
	ds_read_b128 v[206:209], v192 offset:1024
	ds_read_b128 v[210:213], v192 offset:2048
	ds_read_b128 v[214:217], v192 offset:3072
	global_load_lds_dwordx4 v[186:187], off
	v_lshl_add_u64 v[218:219], s[22:23], 0, v[160:161]
	s_add_i32 m0, s47, 0x2000
	s_nop 0
	global_load_lds_dwordx4 v[218:219], off
	s_barrier
	s_waitcnt lgkmcnt(0)
	s_setprio 1
	s_waitcnt lgkmcnt(0)
	v_mfma_f32_16x16x32_bf16 v[116:119], v[202:205], v[144:147], 0
	v_mfma_f32_16x16x32_bf16 v[112:115], v[210:213], v[144:147], 0
	v_mfma_f32_16x16x32_bf16 v[100:103], v[202:205], v[170:173], 0
	v_mfma_f32_16x16x32_bf16 v[96:99], v[210:213], v[170:173], 0
	v_mfma_f32_16x16x32_bf16 v[84:87], v[202:205], v[178:181], 0
	v_mfma_f32_16x16x32_bf16 v[80:83], v[210:213], v[178:181], 0
	v_mfma_f32_16x16x32_bf16 v[68:71], v[202:205], v[194:197], 0
	v_mfma_f32_16x16x32_bf16 v[64:67], v[210:213], v[194:197], 0
	v_mfma_f32_16x16x32_bf16 v[116:119], v[206:209], v[148:151], v[116:119]
	v_mfma_f32_16x16x32_bf16 v[112:115], v[214:217], v[148:151], v[112:115]
	v_mfma_f32_16x16x32_bf16 v[100:103], v[206:209], v[174:177], v[100:103]
	v_mfma_f32_16x16x32_bf16 v[96:99], v[214:217], v[174:177], v[96:99]
	v_mfma_f32_16x16x32_bf16 v[84:87], v[206:209], v[182:185], v[84:87]
	v_mfma_f32_16x16x32_bf16 v[80:83], v[214:217], v[182:185], v[80:83]
	v_mfma_f32_16x16x32_bf16 v[68:71], v[206:209], v[198:201], v[68:71]
	v_mfma_f32_16x16x32_bf16 v[64:67], v[214:217], v[198:201], v[64:67]
	s_setprio 0
	s_mov_b32 m0, s9
	v_lshl_add_u64 v[220:221], s[24:25], 0, v[154:155]
	s_barrier
	ds_read_b128 v[144:147], v191 offset:16384
	ds_read_b128 v[148:151], v191 offset:17408
	ds_read_b128 v[170:173], v191 offset:18432
	ds_read_b128 v[174:177], v191 offset:19456
	ds_read_b128 v[178:181], v191 offset:20480
	ds_read_b128 v[182:185], v191 offset:21504
	ds_read_b128 v[194:197], v191 offset:22528
	ds_read_b128 v[198:201], v191 offset:23552
	global_load_lds_dwordx4 v[220:221], off
	v_lshl_add_u64 v[222:223], s[24:25], 0, v[158:159]
	s_mov_b32 m0, s30
	s_nop 0
	global_load_lds_dwordx4 v[222:223], off
	s_barrier
	s_waitcnt lgkmcnt(0)
	s_setprio 1
	s_waitcnt lgkmcnt(0)
	v_mfma_f32_16x16x32_bf16 v[60:63], v[128:131], v[144:147], 0
	v_mfma_f32_16x16x32_bf16 v[56:59], v[136:139], v[144:147], 0
	v_mfma_f32_16x16x32_bf16 v[44:47], v[128:131], v[170:173], 0
	v_mfma_f32_16x16x32_bf16 v[40:43], v[136:139], v[170:173], 0
	v_mfma_f32_16x16x32_bf16 v[28:31], v[128:131], v[178:181], 0
	v_mfma_f32_16x16x32_bf16 v[24:27], v[136:139], v[178:181], 0
	v_mfma_f32_16x16x32_bf16 v[12:15], v[128:131], v[194:197], 0
	v_mfma_f32_16x16x32_bf16 v[8:11], v[136:139], v[194:197], 0
	v_mfma_f32_16x16x32_bf16 v[60:63], v[132:135], v[148:151], v[60:63]
	v_mfma_f32_16x16x32_bf16 v[56:59], v[140:143], v[148:151], v[56:59]
	v_mfma_f32_16x16x32_bf16 v[44:47], v[132:135], v[174:177], v[44:47]
	v_mfma_f32_16x16x32_bf16 v[40:43], v[140:143], v[174:177], v[40:43]
	v_mfma_f32_16x16x32_bf16 v[28:31], v[132:135], v[182:185], v[28:31]
	v_mfma_f32_16x16x32_bf16 v[24:27], v[140:143], v[182:185], v[24:27]
	v_mfma_f32_16x16x32_bf16 v[12:15], v[132:135], v[198:201], v[12:15]
	v_mfma_f32_16x16x32_bf16 v[8:11], v[140:143], v[198:201], v[8:11]
	s_setprio 0
	s_barrier
; #define PG8_STAGE(bufoff, gbase, voff) do { _Pragma("unroll") for (int _i = 0; _i < 2; ++_i) \
;         __builtin_amdgcn_global_load_lds((const unsigned*)((const char*)(gbase) + (voff)[_i]), (LAS unsigned*)(lds + (bufoff) + ldsw + _i * 8192), 16, 0, 0); } while (0)
; #define PG8_LDA(dst, b, h) do { _Pragma("unroll") for (int m = 0; m < 4; ++m) _Pragma("unroll") for (int k = 0; k < 2; ++k) dst[m][k] = *(const LAS bf16x8*)(lds + PG8_SA(b, h) + aoff + m * 2048 + k * 1024); } while (0)
; #define PG8_LDB(dst, b, h) do { _Pragma("unroll") for (int n = 0; n < 2; ++n) _Pragma("unroll") for (int k = 0; k < 2; ++k) dst[n][k] = *(const LAS bf16x8*)(lds + PG8_SB(b, h) + boff + n * 2048 + k * 1024); } while (0)
; #define PG8_MMA(ai, bj, At, Bt) do { __builtin_amdgcn_s_setprio(1); _Pragma("unroll") for (int m = 0; m < 4; ++m) _Pragma("unroll") for (int n = 0; n < 2; ++n) _Pragma("unroll") for (int k = 0; k < 2; ++k) \
;         acc[ai][bj][m][n] = __builtin_amdgcn_mfma_f32_16x16x32_bf16(Bt[n][k], At[m][k], acc[ai][bj][m][n], 0, 0, 0); __builtin_amdgcn_s_setprio(0); } while (0)
; #define PG8_WAIT_V(n) asm volatile("s_waitcnt vmcnt(" #n ")" ::: "memory")
; #define PG8_WAIT_L(n) asm volatile("s_waitcnt lgkmcnt(" #n ")" ::: "memory")
; #define PG8_BAR __builtin_amdgcn_s_barrier()
; #define PG8_SCHED __builtin_amdgcn_sched_barrier(0)
; template <class Epi>
; __device__ __forceinline__ void gemm_phase(LAS unsigned char* lds, const Gemm g, const StaticOrder& S, const Epi& E) {
;     ...
;             PG8_STAGE(PG8_SB(0, 1), b2 + hstepB, voffB);
;             PG8_WAIT_V(6); PG8_BAR; PG8_MMA(1, 1, At, B1); PG8_BAR;
;             PG8_LDB(B0, 1, 0); PG8_SCHED; PG8_LDA(At, 1, 0); PG8_STAGE(PG8_SA(0, 1), a2 + hstepA, voffA);
;             PG8_WAIT_L(8); PG8_BAR; PG8_WAIT_L(0); PG8_MMA(0, 0, At, B0); PG8_BAR; PG8_SCHED;
;             PG8_LDB(B1, 1, 1); PG8_STAGE(PG8_SB(1, 0), b3, voffB);
;             PG8_BAR; PG8_WAIT_L(0); PG8_MMA(0, 1, At, B1); PG8_BAR;
;             PG8_LDA(At, 1, 1); PG8_STAGE(PG8_SA(1, 0), a3, voffA);
	s_add_u32 s48, s22, 0x40000
	s_addc_u32 s49, s23, 0
	s_add_i32 s47, s41, s29
	v_lshl_add_u64 v[128:129], s[48:49], 0, v[156:157]
	s_mov_b32 m0, s47
	s_nop 0
	global_load_lds_dwordx4 v[128:129], off
	v_lshl_add_u64 v[128:129], s[48:49], 0, v[160:161]
	s_add_i32 m0, s47, 0x2000
	s_nop 0
	global_load_lds_dwordx4 v[128:129], off
	s_waitcnt vmcnt(6)
	s_barrier
	s_setprio 1
	v_mfma_f32_16x16x32_bf16 v[52:55], v[202:205], v[144:147], 0
	v_mfma_f32_16x16x32_bf16 v[48:51], v[210:213], v[144:147], 0
	v_mfma_f32_16x16x32_bf16 v[36:39], v[202:205], v[170:173], 0
	v_mfma_f32_16x16x32_bf16 v[32:35], v[210:213], v[170:173], 0
	v_mfma_f32_16x16x32_bf16 v[20:23], v[202:205], v[178:181], 0
	v_mfma_f32_16x16x32_bf16 v[16:19], v[210:213], v[178:181], 0
	v_mfma_f32_16x16x32_bf16 v[4:7], v[202:205], v[194:197], 0
	v_mfma_f32_16x16x32_bf16 v[0:3], v[210:213], v[194:197], 0
	v_mfma_f32_16x16x32_bf16 v[52:55], v[206:209], v[148:151], v[52:55]
	v_mfma_f32_16x16x32_bf16 v[48:51], v[214:217], v[148:151], v[48:51]
	v_mfma_f32_16x16x32_bf16 v[36:39], v[206:209], v[174:177], v[36:39]
	v_mfma_f32_16x16x32_bf16 v[32:35], v[214:217], v[174:177], v[32:35]
	v_mfma_f32_16x16x32_bf16 v[20:23], v[206:209], v[182:185], v[20:23]
	v_mfma_f32_16x16x32_bf16 v[16:19], v[214:217], v[182:185], v[16:19]
	v_mfma_f32_16x16x32_bf16 v[4:7], v[206:209], v[198:201], v[4:7]
	v_mfma_f32_16x16x32_bf16 v[0:3], v[214:217], v[198:201], v[0:3]
	s_setprio 0
	s_add_i32 s47, 0, 0x18000
	v_add_u32_e32 v140, s47, v188
	s_barrier
	ds_read_b128 v[128:131], v140
	ds_read_b128 v[132:135], v140 offset:1024
	ds_read_b128 v[136:139], v140 offset:2048
	ds_read_b128 v[140:143], v140 offset:3072
	s_add_u32 s24, s24, 0x140000
	s_addc_u32 s25, s25, 0
	s_mov_b32 m0, s31
	v_lshl_add_u64 v[202:203], s[24:25], 0, v[154:155]
	ds_read_b128 v[144:147], v191 offset:32768
	ds_read_b128 v[148:151], v191 offset:33792
	ds_read_b128 v[170:173], v191 offset:34816
	ds_read_b128 v[174:177], v191 offset:35840
	ds_read_b128 v[178:181], v191 offset:36864
	ds_read_b128 v[182:185], v191 offset:37888
	ds_read_b128 v[194:197], v191 offset:38912
	ds_read_b128 v[198:201], v191 offset:39936
	global_load_lds_dwordx4 v[202:203], off
	v_lshl_add_u64 v[202:203], s[24:25], 0, v[158:159]
	s_mov_b32 m0, s34
	s_nop 0
	global_load_lds_dwordx4 v[202:203], off
	s_waitcnt lgkmcnt(8)
	s_barrier
	s_waitcnt lgkmcnt(0)
	s_setprio 1
	s_waitcnt lgkmcnt(0)
	v_mfma_f32_16x16x32_bf16 v[124:127], v[128:131], v[144:147], v[124:127]
	v_mfma_f32_16x16x32_bf16 v[120:123], v[136:139], v[144:147], v[120:123]
	v_mfma_f32_16x16x32_bf16 v[108:111], v[128:131], v[170:173], v[108:111]
	v_mfma_f32_16x16x32_bf16 v[104:107], v[136:139], v[170:173], v[104:107]
	v_mfma_f32_16x16x32_bf16 v[92:95], v[128:131], v[178:181], v[92:95]
	v_mfma_f32_16x16x32_bf16 v[88:91], v[136:139], v[178:181], v[88:91]
	v_mfma_f32_16x16x32_bf16 v[76:79], v[128:131], v[194:197], v[76:79]
	v_mfma_f32_16x16x32_bf16 v[72:75], v[136:139], v[194:197], v[72:75]
	v_mfma_f32_16x16x32_bf16 v[124:127], v[132:135], v[148:151], v[124:127]
	v_mfma_f32_16x16x32_bf16 v[120:123], v[140:143], v[148:151], v[120:123]
	v_mfma_f32_16x16x32_bf16 v[108:111], v[132:135], v[174:177], v[108:111]
	v_mfma_f32_16x16x32_bf16 v[104:107], v[140:143], v[174:177], v[104:107]
	v_mfma_f32_16x16x32_bf16 v[92:95], v[132:135], v[182:185], v[92:95]
	v_mfma_f32_16x16x32_bf16 v[88:91], v[140:143], v[182:185], v[88:91]
	v_mfma_f32_16x16x32_bf16 v[76:79], v[132:135], v[198:201], v[76:79]
	v_mfma_f32_16x16x32_bf16 v[72:75], v[140:143], v[198:201], v[72:75]
	s_setprio 0
	s_barrier
	s_add_i32 s24, 0, 0x1c000
	s_add_i32 s25, s47, s29
	v_add_u32_e32 v214, s24, v188
	v_lshl_add_u64 v[186:187], v[186:187], 0, s[14:15]
	s_mov_b32 m0, s25
	ds_read_b128 v[202:205], v214
	ds_read_b128 v[206:209], v214 offset:1024
	ds_read_b128 v[210:213], v214 offset:2048
	ds_read_b128 v[214:217], v214 offset:3072
	global_load_lds_dwordx4 v[186:187], off
	v_lshl_add_u64 v[186:187], v[218:219], 0, s[14:15]
	s_add_i32 m0, s25, 0x2000
	s_nop 0
	global_load_lds_dwordx4 v[186:187], off
	s_barrier
; #define PG8_STAGE(bufoff, gbase, voff) do { _Pragma("unroll") for (int _i = 0; _i < 2; ++_i) \
;         __builtin_amdgcn_global_load_lds((const unsigned*)((const char*)(gbase) + (voff)[_i]), (LAS unsigned*)(lds + (bufoff) + ldsw + _i * 8192), 16, 0, 0); } while (0)
; #define PG8_LDA(dst, b, h) do { _Pragma("unroll") for (int m = 0; m < 4; ++m) _Pragma("unroll") for (int k = 0; k < 2; ++k) dst[m][k] = *(const LAS bf16x8*)(lds + PG8_SA(b, h) + aoff + m * 2048 + k * 1024); } while (0)
; #define PG8_MMA(ai, bj, At, Bt) do { __builtin_amdgcn_s_setprio(1); _Pragma("unroll") for (int m = 0; m < 4; ++m) _Pragma("unroll") for (int n = 0; n < 2; ++n) _Pragma("unroll") for (int k = 0; k < 2; ++k) \
;         acc[ai][bj][m][n] = __builtin_amdgcn_mfma_f32_16x16x32_bf16(Bt[n][k], At[m][k], acc[ai][bj][m][n], 0, 0, 0); __builtin_amdgcn_s_setprio(0); } while (0)
; #define PG8_WAIT_V(n) asm volatile("s_waitcnt vmcnt(" #n ")" ::: "memory")
; #define PG8_WAIT_L(n) asm volatile("s_waitcnt lgkmcnt(" #n ")" ::: "memory")
; #define PG8_BAR __builtin_amdgcn_s_barrier()
; #define PG8_SCHED __builtin_amdgcn_sched_barrier(0)
; template <class Epi>
; __device__ __forceinline__ void gemm_phase(LAS unsigned char* lds, const Gemm g, const StaticOrder& S, const Epi& E) {
;     ...
;             PG8_BAR; PG8_WAIT_L(0); PG8_MMA(0, 1, At, B1); PG8_BAR;
;             PG8_LDA(At, 1, 1); PG8_STAGE(PG8_SA(1, 0), a3, voffA);
;             PG8_BAR; PG8_WAIT_L(0); PG8_MMA(1, 0, At, B0); PG8_BAR; PG8_SCHED;
;             PG8_STAGE(PG8_SB(1, 1), b3 + hstepB, voffB);
;             PG8_WAIT_V(6); PG8_BAR; PG8_MMA(1, 1, At, B1); PG8_BAR;
;         }
	s_waitcnt lgkmcnt(0)
	s_setprio 1
	s_waitcnt lgkmcnt(0)
	v_mfma_f32_16x16x32_bf16 v[116:119], v[202:205], v[144:147], v[116:119]
	v_mfma_f32_16x16x32_bf16 v[112:115], v[210:213], v[144:147], v[112:115]
	v_mfma_f32_16x16x32_bf16 v[100:103], v[202:205], v[170:173], v[100:103]
	v_mfma_f32_16x16x32_bf16 v[96:99], v[210:213], v[170:173], v[96:99]
	v_mfma_f32_16x16x32_bf16 v[84:87], v[202:205], v[178:181], v[84:87]
	v_mfma_f32_16x16x32_bf16 v[80:83], v[210:213], v[178:181], v[80:83]
	v_mfma_f32_16x16x32_bf16 v[68:71], v[202:205], v[194:197], v[68:71]
	v_mfma_f32_16x16x32_bf16 v[64:67], v[210:213], v[194:197], v[64:67]
	v_mfma_f32_16x16x32_bf16 v[116:119], v[206:209], v[148:151], v[116:119]
	v_mfma_f32_16x16x32_bf16 v[112:115], v[214:217], v[148:151], v[112:115]
	v_mfma_f32_16x16x32_bf16 v[100:103], v[206:209], v[174:177], v[100:103]
	v_mfma_f32_16x16x32_bf16 v[96:99], v[214:217], v[174:177], v[96:99]
	v_mfma_f32_16x16x32_bf16 v[84:87], v[206:209], v[182:185], v[84:87]
	v_mfma_f32_16x16x32_bf16 v[80:83], v[214:217], v[182:185], v[80:83]
	v_mfma_f32_16x16x32_bf16 v[68:71], v[206:209], v[198:201], v[68:71]
	v_mfma_f32_16x16x32_bf16 v[64:67], v[214:217], v[198:201], v[64:67]
	s_setprio 0
	s_mov_b32 m0, s36
	v_lshl_add_u64 v[186:187], v[220:221], 0, s[14:15]
	s_barrier
	ds_read_b128 v[144:147], v191 offset:49152
	ds_read_b128 v[148:151], v191 offset:50176
	ds_read_b128 v[170:173], v191 offset:51200
	ds_read_b128 v[174:177], v191 offset:52224
	ds_read_b128 v[178:181], v191 offset:53248
	ds_read_b128 v[182:185], v191 offset:54272
	ds_read_b128 v[194:197], v191 offset:55296
	ds_read_b128 v[198:201], v191 offset:56320
	global_load_lds_dwordx4 v[186:187], off
	v_lshl_add_u64 v[186:187], v[222:223], 0, s[14:15]
	s_mov_b32 m0, s37
	s_nop 0
	global_load_lds_dwordx4 v[186:187], off
	s_barrier
	s_waitcnt lgkmcnt(0)
	s_setprio 1
	s_waitcnt lgkmcnt(0)
	v_mfma_f32_16x16x32_bf16 v[60:63], v[128:131], v[144:147], v[60:63]
	v_mfma_f32_16x16x32_bf16 v[56:59], v[136:139], v[144:147], v[56:59]
	v_mfma_f32_16x16x32_bf16 v[44:47], v[128:131], v[170:173], v[44:47]
	v_mfma_f32_16x16x32_bf16 v[40:43], v[136:139], v[170:173], v[40:43]
	v_mfma_f32_16x16x32_bf16 v[28:31], v[128:131], v[178:181], v[28:31]
	v_mfma_f32_16x16x32_bf16 v[24:27], v[136:139], v[178:181], v[24:27]
	v_mfma_f32_16x16x32_bf16 v[12:15], v[128:131], v[194:197], v[12:15]
	v_mfma_f32_16x16x32_bf16 v[8:11], v[136:139], v[194:197], v[8:11]
	v_mfma_f32_16x16x32_bf16 v[60:63], v[132:135], v[148:151], v[60:63]
	v_mfma_f32_16x16x32_bf16 v[56:59], v[140:143], v[148:151], v[56:59]
	v_mfma_f32_16x16x32_bf16 v[44:47], v[132:135], v[174:177], v[44:47]
	v_mfma_f32_16x16x32_bf16 v[40:43], v[140:143], v[174:177], v[40:43]
	v_mfma_f32_16x16x32_bf16 v[28:31], v[132:135], v[182:185], v[28:31]
	v_mfma_f32_16x16x32_bf16 v[24:27], v[140:143], v[182:185], v[24:27]
	v_mfma_f32_16x16x32_bf16 v[12:15], v[132:135], v[198:201], v[12:15]
	v_mfma_f32_16x16x32_bf16 v[8:11], v[140:143], v[198:201], v[8:11]
	s_setprio 0
	s_barrier
	s_add_u32 s22, s22, 0x40080
	s_addc_u32 s23, s23, 0
	s_add_i32 s24, s24, s29
	v_lshl_add_u64 v[128:129], s[22:23], 0, v[156:157]
	s_mov_b32 m0, s24
	s_nop 0
	global_load_lds_dwordx4 v[128:129], off
	v_lshl_add_u64 v[128:129], s[22:23], 0, v[160:161]
	s_add_i32 m0, s24, 0x2000
	s_nop 0
	global_load_lds_dwordx4 v[128:129], off
	s_waitcnt vmcnt(6)
	s_barrier
	s_setprio 1
	v_mfma_f32_16x16x32_bf16 v[52:55], v[202:205], v[144:147], v[52:55]
	v_mfma_f32_16x16x32_bf16 v[48:51], v[210:213], v[144:147], v[48:51]
	v_mfma_f32_16x16x32_bf16 v[36:39], v[202:205], v[170:173], v[36:39]
	v_mfma_f32_16x16x32_bf16 v[32:35], v[210:213], v[170:173], v[32:35]
	v_mfma_f32_16x16x32_bf16 v[20:23], v[202:205], v[178:181], v[20:23]
	v_mfma_f32_16x16x32_bf16 v[16:19], v[210:213], v[178:181], v[16:19]
	v_mfma_f32_16x16x32_bf16 v[4:7], v[202:205], v[194:197], v[4:7]
	v_mfma_f32_16x16x32_bf16 v[0:3], v[210:213], v[194:197], v[0:3]
	v_mfma_f32_16x16x32_bf16 v[52:55], v[206:209], v[148:151], v[52:55]
	v_mfma_f32_16x16x32_bf16 v[48:51], v[214:217], v[148:151], v[48:51]
	v_mfma_f32_16x16x32_bf16 v[36:39], v[206:209], v[174:177], v[36:39]
	v_mfma_f32_16x16x32_bf16 v[32:35], v[214:217], v[174:177], v[32:35]
	v_mfma_f32_16x16x32_bf16 v[20:23], v[206:209], v[182:185], v[20:23]
	v_mfma_f32_16x16x32_bf16 v[16:19], v[214:217], v[182:185], v[16:19]
	v_mfma_f32_16x16x32_bf16 v[4:7], v[206:209], v[198:201], v[4:7]
	v_mfma_f32_16x16x32_bf16 v[0:3], v[214:217], v[198:201], v[0:3]
	s_setprio 0
	s_add_i32 s46, s46, 2
	s_add_u32 s4, s4, 0x100
	s_addc_u32 s5, s5, 0
	s_add_u32 s44, s44, 0x100
	s_addc_u32 s45, s45, 0
	s_cmp_gt_u32 s46, 13
	s_barrier

; #define PG8_STAGE(bufoff, gbase, voff) do { _Pragma("unroll") for (int _i = 0; _i < 2; ++_i) \
;         __builtin_amdgcn_global_load_lds((const unsigned*)((const char*)(gbase) + (voff)[_i]), (LAS unsigned*)(lds + (bufoff) + ldsw + _i * 8192), 16, 0, 0); } while (0)
; #define PG8_LDA(dst, b, h) do { _Pragma("unroll") for (int m = 0; m < 4; ++m) _Pragma("unroll") for (int k = 0; k < 2; ++k) dst[m][k] = *(const LAS bf16x8*)(lds + PG8_SA(b, h) + aoff + m * 2048 + k * 1024); } while (0)
; #define PG8_LDB(dst, b, h) do { _Pragma("unroll") for (int n = 0; n < 2; ++n) _Pragma("unroll") for (int k = 0; k < 2; ++k) dst[n][k] = *(const LAS bf16x8*)(lds + PG8_SB(b, h) + boff + n * 2048 + k * 1024); } while (0)
; #define PG8_MMA(ai, bj, At, Bt) do { __builtin_amdgcn_s_setprio(1); _Pragma("unroll") for (int m = 0; m < 4; ++m) _Pragma("unroll") for (int n = 0; n < 2; ++n) _Pragma("unroll") for (int k = 0; k < 2; ++k) \
;         acc[ai][bj][m][n] = __builtin_amdgcn_mfma_f32_16x16x32_bf16(Bt[n][k], At[m][k], acc[ai][bj][m][n], 0, 0, 0); __builtin_amdgcn_s_setprio(0); } while (0)
; #define PG8_BAR __builtin_amdgcn_s_barrier()
; template <class Epi>
; __device__ __forceinline__ void gemm_phase(LAS unsigned char* lds, const Gemm g, const StaticOrder& S, const Epi& E) {
;     ...
;         const bool has_next = S.next(ui + 1, nxt);
;         const char* nA = has_next ? (const char*)g.A + (size_t)nxt.pm * tstepA : cA; const char* nB = has_next ? (const char*)g.Bt + (size_t)nxt.pn * tstepB : cB;
;         for (int t = 0; t < nt; t += 2) {
;             const bool last = (t == nt - 2);
;             const char* a1 = cA + (size_t)(t + 1) * kstep;
;             const char* a2 = last ? nA : cA + (size_t)(t + 2) * kstep; const char* b2 = last ? nB : cB + (size_t)(t + 2) * kstep;
;             const char* a3 = a2 + kstep; const char* b3 = b2 + kstep;
;             if (last) E.pre(cur, wr, fr, epre);
;             PG8_LDB(B0, 0, 0); PG8_SCHED; PG8_LDA(At, 0, 0); PG8_STAGE(PG8_SA(1, 1), a1 + hstepA, voffA);
;             PG8_WAIT_L(8); PG8_BAR; PG8_WAIT_L(0); PG8_MMA(0, 0, At, B0); PG8_BAR; PG8_SCHED;
;             PG8_LDB(B1, 0, 1); PG8_STAGE(PG8_SB(0, 0), b2, voffB);
;             PG8_BAR; PG8_WAIT_L(0); PG8_MMA(0, 1, At, B1); PG8_BAR;
;             PG8_LDA(At, 0, 1); PG8_STAGE(PG8_SA(0, 0), a2, voffA);
;             PG8_BAR; PG8_WAIT_L(0); PG8_MMA(1, 0, At, B0); PG8_BAR; PG8_SCHED;
.LBB0_1203:
	s_ashr_i32 s13, s12, 31
	v_cmp_lt_i64_e32 vcc, s[14:15], v[142:143]
	s_lshl_b64 s[14:15], s[12:13], 19
	s_add_u32 s14, s76, s14
	s_addc_u32 s15, s77, s15
	s_and_b64 s[16:17], vcc, exec
	s_cselect_b32 s13, s15, s21
	s_cselect_b32 s41, s14, s20
	s_ashr_i32 s11, s10, 31
	s_lshl_b64 s[16:17], s[10:11], 19
	s_add_u32 s16, s26, s16
	s_addc_u32 s17, s27, s17
	s_and_b64 s[24:25], vcc, exec
	s_cselect_b32 s11, s17, s23
	s_cselect_b32 s42, s16, s22
	s_add_u32 s20, s20, 0x40080
	s_addc_u32 s21, s21, 0
	s_add_u32 s43, s22, 0x100
	s_addc_u32 s44, s23, 0
	s_mov_b32 s45, -2
	ds_read_b128 v[146:149], v176
	ds_read_b128 v[154:157], v176 offset:1024
	ds_read_b128 v[158:161], v176 offset:2048
	ds_read_b128 v[162:165], v176 offset:3072
	s_add_u32 s22, s20, 0xfffc0080
	s_addc_u32 s23, s21, -1
	s_cmp_eq_u32 s45, 12
	s_cselect_b32 s25, s13, s23
	s_cselect_b32 s24, s41, s22
	s_cselect_b32 s23, s11, s44
	s_cselect_b32 s22, s42, s43
	v_lshl_add_u64 v[150:151], s[20:21], 0, v[138:139]
	s_add_i32 m0, s19, 0xc000
	ds_read_b128 v[166:169], v177
	ds_read_b128 v[170:173], v177 offset:1024
	ds_read_b128 v[180:183], v177 offset:2048
	ds_read_b128 v[184:187], v177 offset:3072
	ds_read_b128 v[188:191], v177 offset:4096
	ds_read_b128 v[192:195], v177 offset:5120
	ds_read_b128 v[196:199], v177 offset:6144
	ds_read_b128 v[200:203], v177 offset:7168
	global_load_lds_dwordx4 v[150:151], off
	v_lshl_add_u64 v[150:151], s[20:21], 0, v[140:141]
	s_add_i32 m0, s19, 0xe000
	s_nop 0
	global_load_lds_dwordx4 v[150:151], off
	s_waitcnt lgkmcnt(8)
	s_barrier
	s_waitcnt lgkmcnt(0)
	s_setprio 1
	s_waitcnt lgkmcnt(0)
	v_mfma_f32_16x16x32_bf16 v[124:127], v[146:149], v[166:169], 0
	v_mfma_f32_16x16x32_bf16 v[120:123], v[158:161], v[166:169], 0
	v_mfma_f32_16x16x32_bf16 v[108:111], v[146:149], v[180:183], 0
	v_mfma_f32_16x16x32_bf16 v[104:107], v[158:161], v[180:183], 0
	v_mfma_f32_16x16x32_bf16 v[92:95], v[146:149], v[188:191], 0
	v_mfma_f32_16x16x32_bf16 v[88:91], v[158:161], v[188:191], 0
	v_mfma_f32_16x16x32_bf16 v[76:79], v[146:149], v[196:199], 0
	v_mfma_f32_16x16x32_bf16 v[72:75], v[158:161], v[196:199], 0
	v_mfma_f32_16x16x32_bf16 v[124:127], v[154:157], v[170:173], v[124:127]
	v_mfma_f32_16x16x32_bf16 v[120:123], v[162:165], v[170:173], v[120:123]
	v_mfma_f32_16x16x32_bf16 v[108:111], v[154:157], v[184:187], v[108:111]
	v_mfma_f32_16x16x32_bf16 v[104:107], v[162:165], v[184:187], v[104:107]
	v_mfma_f32_16x16x32_bf16 v[92:95], v[154:157], v[192:195], v[92:95]
	v_mfma_f32_16x16x32_bf16 v[88:91], v[162:165], v[192:195], v[88:91]
	v_mfma_f32_16x16x32_bf16 v[76:79], v[154:157], v[200:203], v[76:79]
	v_mfma_f32_16x16x32_bf16 v[72:75], v[162:165], v[200:203], v[72:75]
	s_setprio 0
	s_barrier
	s_add_i32 s46, s37, s28
	v_lshl_add_u64 v[150:151], s[22:23], 0, v[130:131]
	s_mov_b32 m0, s46
	ds_read_b128 v[204:207], v178
	ds_read_b128 v[208:211], v178 offset:1024
	ds_read_b128 v[212:215], v178 offset:2048
	ds_read_b128 v[216:219], v178 offset:3072
	global_load_lds_dwordx4 v[150:151], off
	v_lshl_add_u64 v[220:221], s[22:23], 0, v[134:135]
	s_add_i32 m0, s46, 0x2000
	s_nop 0
	global_load_lds_dwordx4 v[220:221], off
	s_barrier
	s_waitcnt lgkmcnt(0)
	s_setprio 1
	s_waitcnt lgkmcnt(0)
	v_mfma_f32_16x16x32_bf16 v[116:119], v[204:207], v[166:169], 0
	v_mfma_f32_16x16x32_bf16 v[112:115], v[212:215], v[166:169], 0
	v_mfma_f32_16x16x32_bf16 v[100:103], v[204:207], v[180:183], 0
	v_mfma_f32_16x16x32_bf16 v[96:99], v[212:215], v[180:183], 0
	v_mfma_f32_16x16x32_bf16 v[84:87], v[204:207], v[188:191], 0
	v_mfma_f32_16x16x32_bf16 v[80:83], v[212:215], v[188:191], 0
	v_mfma_f32_16x16x32_bf16 v[68:71], v[204:207], v[196:199], 0
	v_mfma_f32_16x16x32_bf16 v[64:67], v[212:215], v[196:199], 0
	v_mfma_f32_16x16x32_bf16 v[116:119], v[208:211], v[170:173], v[116:119]
	v_mfma_f32_16x16x32_bf16 v[112:115], v[216:219], v[170:173], v[112:115]
	v_mfma_f32_16x16x32_bf16 v[100:103], v[208:211], v[184:187], v[100:103]
	v_mfma_f32_16x16x32_bf16 v[96:99], v[216:219], v[184:187], v[96:99]
	v_mfma_f32_16x16x32_bf16 v[84:87], v[208:211], v[192:195], v[84:87]
	v_mfma_f32_16x16x32_bf16 v[80:83], v[216:219], v[192:195], v[80:83]
	v_mfma_f32_16x16x32_bf16 v[68:71], v[208:211], v[200:203], v[68:71]
	v_mfma_f32_16x16x32_bf16 v[64:67], v[216:219], v[200:203], v[64:67]
	s_setprio 0
	s_mov_b32 m0, s19
	v_lshl_add_u64 v[222:223], s[24:25], 0, v[128:129]
	s_barrier
	ds_read_b128 v[166:169], v177 offset:16384
	ds_read_b128 v[170:173], v177 offset:17408
	ds_read_b128 v[180:183], v177 offset:18432
	ds_read_b128 v[184:187], v177 offset:19456
	ds_read_b128 v[188:191], v177 offset:20480
	ds_read_b128 v[192:195], v177 offset:21504
	ds_read_b128 v[196:199], v177 offset:22528
	ds_read_b128 v[200:203], v177 offset:23552
	global_load_lds_dwordx4 v[222:223], off
	v_lshl_add_u64 v[224:225], s[24:25], 0, v[132:133]
	s_mov_b32 m0, s29
	s_nop 0
	global_load_lds_dwordx4 v[224:225], off
	s_barrier
	s_waitcnt lgkmcnt(0)
	s_setprio 1
	s_waitcnt lgkmcnt(0)
	v_mfma_f32_16x16x32_bf16 v[60:63], v[146:149], v[166:169], 0
	v_mfma_f32_16x16x32_bf16 v[56:59], v[158:161], v[166:169], 0
	v_mfma_f32_16x16x32_bf16 v[44:47], v[146:149], v[180:183], 0
	v_mfma_f32_16x16x32_bf16 v[40:43], v[158:161], v[180:183], 0
	v_mfma_f32_16x16x32_bf16 v[28:31], v[146:149], v[188:191], 0
	v_mfma_f32_16x16x32_bf16 v[24:27], v[158:161], v[188:191], 0
	v_mfma_f32_16x16x32_bf16 v[12:15], v[146:149], v[196:199], 0
	v_mfma_f32_16x16x32_bf16 v[8:11], v[158:161], v[196:199], 0
	v_mfma_f32_16x16x32_bf16 v[60:63], v[154:157], v[170:173], v[60:63]
	v_mfma_f32_16x16x32_bf16 v[56:59], v[162:165], v[170:173], v[56:59]
	v_mfma_f32_16x16x32_bf16 v[44:47], v[154:157], v[184:187], v[44:47]
	v_mfma_f32_16x16x32_bf16 v[40:43], v[162:165], v[184:187], v[40:43]
	v_mfma_f32_16x16x32_bf16 v[28:31], v[154:157], v[192:195], v[28:31]
	v_mfma_f32_16x16x32_bf16 v[24:27], v[162:165], v[192:195], v[24:27]
	v_mfma_f32_16x16x32_bf16 v[12:15], v[154:157], v[200:203], v[12:15]
	v_mfma_f32_16x16x32_bf16 v[8:11], v[162:165], v[200:203], v[8:11]
	s_setprio 0
	s_barrier
; #define PG8_STAGE(bufoff, gbase, voff) do { _Pragma("unroll") for (int _i = 0; _i < 2; ++_i) \
;         __builtin_amdgcn_global_load_lds((const unsigned*)((const char*)(gbase) + (voff)[_i]), (LAS unsigned*)(lds + (bufoff) + ldsw + _i * 8192), 16, 0, 0); } while (0)
; #define PG8_LDA(dst, b, h) do { _Pragma("unroll") for (int m = 0; m < 4; ++m) _Pragma("unroll") for (int k = 0; k < 2; ++k) dst[m][k] = *(const LAS bf16x8*)(lds + PG8_SA(b, h) + aoff + m * 2048 + k * 1024); } while (0)
; #define PG8_LDB(dst, b, h) do { _Pragma("unroll") for (int n = 0; n < 2; ++n) _Pragma("unroll") for (int k = 0; k < 2; ++k) dst[n][k] = *(const LAS bf16x8*)(lds + PG8_SB(b, h) + boff + n * 2048 + k * 1024); } while (0)
; #define PG8_MMA(ai, bj, At, Bt) do { __builtin_amdgcn_s_setprio(1); _Pragma("unroll") for (int m = 0; m < 4; ++m) _Pragma("unroll") for (int n = 0; n < 2; ++n) _Pragma("unroll") for (int k = 0; k < 2; ++k) \
;         acc[ai][bj][m][n] = __builtin_amdgcn_mfma_f32_16x16x32_bf16(Bt[n][k], At[m][k], acc[ai][bj][m][n], 0, 0, 0); __builtin_amdgcn_s_setprio(0); } while (0)
; #define PG8_WAIT_V(n) asm volatile("s_waitcnt vmcnt(" #n ")" ::: "memory")
; #define PG8_WAIT_L(n) asm volatile("s_waitcnt lgkmcnt(" #n ")" ::: "memory")
; #define PG8_BAR __builtin_amdgcn_s_barrier()
; #define PG8_SCHED __builtin_amdgcn_sched_barrier(0)
; template <class Epi>
; __device__ __forceinline__ void gemm_phase(LAS unsigned char* lds, const Gemm g, const StaticOrder& S, const Epi& E) {
;     ...
;             PG8_STAGE(PG8_SB(0, 1), b2 + hstepB, voffB);
;             PG8_WAIT_V(6); PG8_BAR; PG8_MMA(1, 1, At, B1); PG8_BAR;
;             PG8_LDB(B0, 1, 0); PG8_SCHED; PG8_LDA(At, 1, 0); PG8_STAGE(PG8_SA(0, 1), a2 + hstepA, voffA);
;             PG8_WAIT_L(8); PG8_BAR; PG8_WAIT_L(0); PG8_MMA(0, 0, At, B0); PG8_BAR; PG8_SCHED;
;             PG8_LDB(B1, 1, 1); PG8_STAGE(PG8_SB(1, 0), b3, voffB);
;             PG8_BAR; PG8_WAIT_L(0); PG8_MMA(0, 1, At, B1); PG8_BAR;
;             PG8_LDA(At, 1, 1); PG8_STAGE(PG8_SA(1, 0), a3, voffA);
	s_add_u32 s46, s22, 0x40000
	s_addc_u32 s47, s23, 0
	s_add_i32 s48, s38, s28
	v_lshl_add_u64 v[146:147], s[46:47], 0, v[130:131]
	s_mov_b32 m0, s48
	s_nop 0
	global_load_lds_dwordx4 v[146:147], off
	v_lshl_add_u64 v[146:147], s[46:47], 0, v[134:135]
	s_add_i32 m0, s48, 0x2000
	s_nop 0
	global_load_lds_dwordx4 v[146:147], off
	s_waitcnt vmcnt(6)
	s_barrier
	s_setprio 1
	v_mfma_f32_16x16x32_bf16 v[52:55], v[204:207], v[166:169], 0
	v_mfma_f32_16x16x32_bf16 v[48:51], v[212:215], v[166:169], 0
	v_mfma_f32_16x16x32_bf16 v[36:39], v[204:207], v[180:183], 0
	v_mfma_f32_16x16x32_bf16 v[32:35], v[212:215], v[180:183], 0
	v_mfma_f32_16x16x32_bf16 v[20:23], v[204:207], v[188:191], 0
	v_mfma_f32_16x16x32_bf16 v[16:19], v[212:215], v[188:191], 0
	v_mfma_f32_16x16x32_bf16 v[4:7], v[204:207], v[196:199], 0
	v_mfma_f32_16x16x32_bf16 v[0:3], v[212:215], v[196:199], 0
	v_mfma_f32_16x16x32_bf16 v[52:55], v[208:211], v[170:173], v[52:55]
	v_mfma_f32_16x16x32_bf16 v[48:51], v[216:219], v[170:173], v[48:51]
	v_mfma_f32_16x16x32_bf16 v[36:39], v[208:211], v[184:187], v[36:39]
	v_mfma_f32_16x16x32_bf16 v[32:35], v[216:219], v[184:187], v[32:35]
	v_mfma_f32_16x16x32_bf16 v[20:23], v[208:211], v[192:195], v[20:23]
	v_mfma_f32_16x16x32_bf16 v[16:19], v[216:219], v[192:195], v[16:19]
	v_mfma_f32_16x16x32_bf16 v[4:7], v[208:211], v[200:203], v[4:7]
	v_mfma_f32_16x16x32_bf16 v[0:3], v[216:219], v[200:203], v[0:3]
	s_setprio 0
	s_add_i32 s46, 0, 0x18000
	v_add_u32_e32 v162, s46, v174
	s_barrier
	ds_read_b128 v[146:149], v162
	ds_read_b128 v[154:157], v162 offset:1024
	ds_read_b128 v[158:161], v162 offset:2048
	ds_read_b128 v[162:165], v162 offset:3072
	s_add_u32 s24, s24, 0x40000
	s_addc_u32 s25, s25, 0
	s_mov_b32 m0, s30
	v_lshl_add_u64 v[204:205], s[24:25], 0, v[128:129]
	ds_read_b128 v[166:169], v177 offset:32768
	ds_read_b128 v[170:173], v177 offset:33792
	ds_read_b128 v[180:183], v177 offset:34816
	ds_read_b128 v[184:187], v177 offset:35840
	ds_read_b128 v[188:191], v177 offset:36864
	ds_read_b128 v[192:195], v177 offset:37888
	ds_read_b128 v[196:199], v177 offset:38912
	ds_read_b128 v[200:203], v177 offset:39936
	global_load_lds_dwordx4 v[204:205], off
	v_lshl_add_u64 v[204:205], s[24:25], 0, v[132:133]
	s_mov_b32 m0, s31
	s_nop 0
	global_load_lds_dwordx4 v[204:205], off
	s_waitcnt lgkmcnt(8)
	s_barrier
	s_waitcnt lgkmcnt(0)
	s_setprio 1
	s_waitcnt lgkmcnt(0)
	v_mfma_f32_16x16x32_bf16 v[124:127], v[146:149], v[166:169], v[124:127]
	v_mfma_f32_16x16x32_bf16 v[120:123], v[158:161], v[166:169], v[120:123]
	v_mfma_f32_16x16x32_bf16 v[108:111], v[146:149], v[180:183], v[108:111]
	v_mfma_f32_16x16x32_bf16 v[104:107], v[158:161], v[180:183], v[104:107]
	v_mfma_f32_16x16x32_bf16 v[92:95], v[146:149], v[188:191], v[92:95]
	v_mfma_f32_16x16x32_bf16 v[88:91], v[158:161], v[188:191], v[88:91]
	v_mfma_f32_16x16x32_bf16 v[76:79], v[146:149], v[196:199], v[76:79]
	v_mfma_f32_16x16x32_bf16 v[72:75], v[158:161], v[196:199], v[72:75]
	v_mfma_f32_16x16x32_bf16 v[124:127], v[154:157], v[170:173], v[124:127]
	v_mfma_f32_16x16x32_bf16 v[120:123], v[162:165], v[170:173], v[120:123]
	v_mfma_f32_16x16x32_bf16 v[108:111], v[154:157], v[184:187], v[108:111]
	v_mfma_f32_16x16x32_bf16 v[104:107], v[162:165], v[184:187], v[104:107]
	v_mfma_f32_16x16x32_bf16 v[92:95], v[154:157], v[192:195], v[92:95]
	v_mfma_f32_16x16x32_bf16 v[88:91], v[162:165], v[192:195], v[88:91]
	v_mfma_f32_16x16x32_bf16 v[76:79], v[154:157], v[200:203], v[76:79]
	v_mfma_f32_16x16x32_bf16 v[72:75], v[162:165], v[200:203], v[72:75]
	s_setprio 0
	s_barrier
	s_add_i32 s24, 0, 0x1c000
	s_add_i32 s25, s46, s28
	v_add_u32_e32 v216, s24, v174
	v_lshl_add_u64 v[150:151], v[150:151], 0, s[4:5]
	s_mov_b32 m0, s25
	ds_read_b128 v[204:207], v216
	ds_read_b128 v[208:211], v216 offset:1024
	ds_read_b128 v[212:215], v216 offset:2048
	ds_read_b128 v[216:219], v216 offset:3072
	global_load_lds_dwordx4 v[150:151], off
	v_lshl_add_u64 v[150:151], v[220:221], 0, s[4:5]
	s_add_i32 m0, s25, 0x2000
	s_nop 0
	global_load_lds_dwordx4 v[150:151], off
	s_barrier
; #define PG8_STAGE(bufoff, gbase, voff) do { _Pragma("unroll") for (int _i = 0; _i < 2; ++_i) \
;         __builtin_amdgcn_global_load_lds((const unsigned*)((const char*)(gbase) + (voff)[_i]), (LAS unsigned*)(lds + (bufoff) + ldsw + _i * 8192), 16, 0, 0); } while (0)
; #define PG8_LDA(dst, b, h) do { _Pragma("unroll") for (int m = 0; m < 4; ++m) _Pragma("unroll") for (int k = 0; k < 2; ++k) dst[m][k] = *(const LAS bf16x8*)(lds + PG8_SA(b, h) + aoff + m * 2048 + k * 1024); } while (0)
; #define PG8_MMA(ai, bj, At, Bt) do { __builtin_amdgcn_s_setprio(1); _Pragma("unroll") for (int m = 0; m < 4; ++m) _Pragma("unroll") for (int n = 0; n < 2; ++n) _Pragma("unroll") for (int k = 0; k < 2; ++k) \
;         acc[ai][bj][m][n] = __builtin_amdgcn_mfma_f32_16x16x32_bf16(Bt[n][k], At[m][k], acc[ai][bj][m][n], 0, 0, 0); __builtin_amdgcn_s_setprio(0); } while (0)
; #define PG8_WAIT_V(n) asm volatile("s_waitcnt vmcnt(" #n ")" ::: "memory")
; #define PG8_WAIT_L(n) asm volatile("s_waitcnt lgkmcnt(" #n ")" ::: "memory")
; #define PG8_BAR __builtin_amdgcn_s_barrier()
; #define PG8_SCHED __builtin_amdgcn_sched_barrier(0)
; template <class Epi>
; __device__ __forceinline__ void gemm_phase(LAS unsigned char* lds, const Gemm g, const StaticOrder& S, const Epi& E) {
;     ...
;             PG8_BAR; PG8_WAIT_L(0); PG8_MMA(0, 1, At, B1); PG8_BAR;
;             PG8_LDA(At, 1, 1); PG8_STAGE(PG8_SA(1, 0), a3, voffA);
;             PG8_BAR; PG8_WAIT_L(0); PG8_MMA(1, 0, At, B0); PG8_BAR; PG8_SCHED;
;             PG8_STAGE(PG8_SB(1, 1), b3 + hstepB, voffB);
;             PG8_WAIT_V(6); PG8_BAR; PG8_MMA(1, 1, At, B1); PG8_BAR;
;         }
	s_waitcnt lgkmcnt(0)
	s_setprio 1
	s_waitcnt lgkmcnt(0)
	v_mfma_f32_16x16x32_bf16 v[116:119], v[204:207], v[166:169], v[116:119]
	v_mfma_f32_16x16x32_bf16 v[112:115], v[212:215], v[166:169], v[112:115]
	v_mfma_f32_16x16x32_bf16 v[100:103], v[204:207], v[180:183], v[100:103]
	v_mfma_f32_16x16x32_bf16 v[96:99], v[212:215], v[180:183], v[96:99]
	v_mfma_f32_16x16x32_bf16 v[84:87], v[204:207], v[188:191], v[84:87]
	v_mfma_f32_16x16x32_bf16 v[80:83], v[212:215], v[188:191], v[80:83]
	v_mfma_f32_16x16x32_bf16 v[68:71], v[204:207], v[196:199], v[68:71]
	v_mfma_f32_16x16x32_bf16 v[64:67], v[212:215], v[196:199], v[64:67]
	v_mfma_f32_16x16x32_bf16 v[116:119], v[208:211], v[170:173], v[116:119]
	v_mfma_f32_16x16x32_bf16 v[112:115], v[216:219], v[170:173], v[112:115]
	v_mfma_f32_16x16x32_bf16 v[100:103], v[208:211], v[184:187], v[100:103]
	v_mfma_f32_16x16x32_bf16 v[96:99], v[216:219], v[184:187], v[96:99]
	v_mfma_f32_16x16x32_bf16 v[84:87], v[208:211], v[192:195], v[84:87]
	v_mfma_f32_16x16x32_bf16 v[80:83], v[216:219], v[192:195], v[80:83]
	v_mfma_f32_16x16x32_bf16 v[68:71], v[208:211], v[200:203], v[68:71]
	v_mfma_f32_16x16x32_bf16 v[64:67], v[216:219], v[200:203], v[64:67]
	s_setprio 0
	s_mov_b32 m0, s34
	v_lshl_add_u64 v[150:151], v[222:223], 0, s[4:5]
	s_barrier
	ds_read_b128 v[166:169], v177 offset:49152
	ds_read_b128 v[170:173], v177 offset:50176
	ds_read_b128 v[180:183], v177 offset:51200
	ds_read_b128 v[184:187], v177 offset:52224
	ds_read_b128 v[188:191], v177 offset:53248
	ds_read_b128 v[192:195], v177 offset:54272
	ds_read_b128 v[196:199], v177 offset:55296
	ds_read_b128 v[200:203], v177 offset:56320
	global_load_lds_dwordx4 v[150:151], off
	v_lshl_add_u64 v[150:151], v[224:225], 0, s[4:5]
	s_mov_b32 m0, s35
	s_nop 0
	global_load_lds_dwordx4 v[150:151], off
	s_barrier
	s_waitcnt lgkmcnt(0)
	s_setprio 1
	s_waitcnt lgkmcnt(0)
	v_mfma_f32_16x16x32_bf16 v[60:63], v[146:149], v[166:169], v[60:63]
	v_mfma_f32_16x16x32_bf16 v[56:59], v[158:161], v[166:169], v[56:59]
	v_mfma_f32_16x16x32_bf16 v[44:47], v[146:149], v[180:183], v[44:47]
	v_mfma_f32_16x16x32_bf16 v[40:43], v[158:161], v[180:183], v[40:43]
	v_mfma_f32_16x16x32_bf16 v[28:31], v[146:149], v[188:191], v[28:31]
	v_mfma_f32_16x16x32_bf16 v[24:27], v[158:161], v[188:191], v[24:27]
	v_mfma_f32_16x16x32_bf16 v[12:15], v[146:149], v[196:199], v[12:15]
	v_mfma_f32_16x16x32_bf16 v[8:11], v[158:161], v[196:199], v[8:11]
	v_mfma_f32_16x16x32_bf16 v[60:63], v[154:157], v[170:173], v[60:63]
	v_mfma_f32_16x16x32_bf16 v[56:59], v[162:165], v[170:173], v[56:59]
	v_mfma_f32_16x16x32_bf16 v[44:47], v[154:157], v[184:187], v[44:47]
	v_mfma_f32_16x16x32_bf16 v[40:43], v[162:165], v[184:187], v[40:43]
	v_mfma_f32_16x16x32_bf16 v[28:31], v[154:157], v[192:195], v[28:31]
	v_mfma_f32_16x16x32_bf16 v[24:27], v[162:165], v[192:195], v[24:27]
	v_mfma_f32_16x16x32_bf16 v[12:15], v[154:157], v[200:203], v[12:15]
	v_mfma_f32_16x16x32_bf16 v[8:11], v[162:165], v[200:203], v[8:11]
	s_setprio 0
	s_barrier
	s_add_u32 s22, s22, 0x40080
	s_addc_u32 s23, s23, 0
	s_add_i32 s24, s24, s28
	v_lshl_add_u64 v[146:147], s[22:23], 0, v[130:131]
	s_mov_b32 m0, s24
	s_nop 0
	global_load_lds_dwordx4 v[146:147], off
	v_lshl_add_u64 v[146:147], s[22:23], 0, v[134:135]
	s_add_i32 m0, s24, 0x2000
	s_nop 0
	global_load_lds_dwordx4 v[146:147], off
	s_waitcnt vmcnt(6)
	s_barrier
	s_setprio 1
	v_mfma_f32_16x16x32_bf16 v[52:55], v[204:207], v[166:169], v[52:55]
	v_mfma_f32_16x16x32_bf16 v[48:51], v[212:215], v[166:169], v[48:51]
	v_mfma_f32_16x16x32_bf16 v[36:39], v[204:207], v[180:183], v[36:39]
	v_mfma_f32_16x16x32_bf16 v[32:35], v[212:215], v[180:183], v[32:35]
	v_mfma_f32_16x16x32_bf16 v[20:23], v[204:207], v[188:191], v[20:23]
	v_mfma_f32_16x16x32_bf16 v[16:19], v[212:215], v[188:191], v[16:19]
	v_mfma_f32_16x16x32_bf16 v[4:7], v[204:207], v[196:199], v[4:7]
	v_mfma_f32_16x16x32_bf16 v[0:3], v[212:215], v[196:199], v[0:3]
	v_mfma_f32_16x16x32_bf16 v[52:55], v[208:211], v[170:173], v[52:55]
	v_mfma_f32_16x16x32_bf16 v[48:51], v[216:219], v[170:173], v[48:51]
	v_mfma_f32_16x16x32_bf16 v[36:39], v[208:211], v[184:187], v[36:39]
	v_mfma_f32_16x16x32_bf16 v[32:35], v[216:219], v[184:187], v[32:35]
	v_mfma_f32_16x16x32_bf16 v[20:23], v[208:211], v[192:195], v[20:23]
	v_mfma_f32_16x16x32_bf16 v[16:19], v[216:219], v[192:195], v[16:19]
	v_mfma_f32_16x16x32_bf16 v[4:7], v[208:211], v[200:203], v[4:7]
	v_mfma_f32_16x16x32_bf16 v[0:3], v[216:219], v[200:203], v[0:3]
	s_setprio 0
	s_add_i32 s45, s45, 2
	s_add_u32 s20, s20, 0x100
	s_addc_u32 s21, s21, 0
	s_add_u32 s43, s43, 0x100
	s_addc_u32 s44, s44, 0
	s_cmp_gt_u32 s45, 13
	s_barrier

; #define PG8_STAGE(bufoff, gbase, voff) do { _Pragma("unroll") for (int _i = 0; _i < 2; ++_i) \
;         __builtin_amdgcn_global_load_lds((const unsigned*)((const char*)(gbase) + (voff)[_i]), (LAS unsigned*)(lds + (bufoff) + ldsw + _i * 8192), 16, 0, 0); } while (0)
; #define PG8_LDA(dst, b, h) do { _Pragma("unroll") for (int m = 0; m < 4; ++m) _Pragma("unroll") for (int k = 0; k < 2; ++k) dst[m][k] = *(const LAS bf16x8*)(lds + PG8_SA(b, h) + aoff + m * 2048 + k * 1024); } while (0)
; #define PG8_LDB(dst, b, h) do { _Pragma("unroll") for (int n = 0; n < 2; ++n) _Pragma("unroll") for (int k = 0; k < 2; ++k) dst[n][k] = *(const LAS bf16x8*)(lds + PG8_SB(b, h) + boff + n * 2048 + k * 1024); } while (0)
; #define PG8_MMA(ai, bj, At, Bt) do { __builtin_amdgcn_s_setprio(1); _Pragma("unroll") for (int m = 0; m < 4; ++m) _Pragma("unroll") for (int n = 0; n < 2; ++n) _Pragma("unroll") for (int k = 0; k < 2; ++k) \
;         acc[ai][bj][m][n] = __builtin_amdgcn_mfma_f32_16x16x32_bf16(Bt[n][k], At[m][k], acc[ai][bj][m][n], 0, 0, 0); __builtin_amdgcn_s_setprio(0); } while (0)
; #define PG8_BAR __builtin_amdgcn_s_barrier()
; template <class Epi>
; __device__ __forceinline__ void gemm_phase(LAS unsigned char* lds, const Gemm g, const StaticOrder& S, const Epi& E) {
;     ...
;         const bool has_next = S.next(ui + 1, nxt);
;         const char* nA = has_next ? (const char*)g.A + (size_t)nxt.pm * tstepA : cA; const char* nB = has_next ? (const char*)g.Bt + (size_t)nxt.pn * tstepB : cB;
;         for (int t = 0; t < nt; t += 2) {
;             const bool last = (t == nt - 2);
;             const char* a1 = cA + (size_t)(t + 1) * kstep;
;             const char* a2 = last ? nA : cA + (size_t)(t + 2) * kstep; const char* b2 = last ? nB : cB + (size_t)(t + 2) * kstep;
;             const char* a3 = a2 + kstep; const char* b3 = b2 + kstep;
;             if (last) E.pre(cur, wr, fr, epre);
;             PG8_LDB(B0, 0, 0); PG8_SCHED; PG8_LDA(At, 0, 0); PG8_STAGE(PG8_SA(1, 1), a1 + hstepA, voffA);
;             PG8_WAIT_L(8); PG8_BAR; PG8_WAIT_L(0); PG8_MMA(0, 0, At, B0); PG8_BAR; PG8_SCHED;
;             PG8_LDB(B1, 0, 1); PG8_STAGE(PG8_SB(0, 0), b2, voffB);
;             PG8_BAR; PG8_WAIT_L(0); PG8_MMA(0, 1, At, B1); PG8_BAR;
;             PG8_LDA(At, 0, 1); PG8_STAGE(PG8_SA(0, 0), a2, voffA);
;             PG8_BAR; PG8_WAIT_L(0); PG8_MMA(1, 0, At, B0); PG8_BAR; PG8_SCHED;
.LBB0_1277:
	s_ashr_i32 s17, s16, 31
	v_cmp_lt_i64_e32 vcc, s[18:19], v[166:167]
	s_lshl_b64 s[18:19], s[16:17], 21
	s_add_u32 s18, s96, s18
	s_addc_u32 s19, s97, s19
	s_and_b64 s[20:21], vcc, exec
	s_cselect_b32 s17, s19, s23
	s_cselect_b32 s44, s18, s22
	s_ashr_i32 s15, s14, 31
	s_lshl_b64 s[20:21], s[14:15], 21
	s_add_u32 s20, s29, s20
	s_addc_u32 s21, s30, s21
	s_and_b64 s[26:27], vcc, exec
	s_cselect_b32 s15, s21, s25
	s_cselect_b32 s45, s20, s24
	s_add_u32 s22, s22, 0x100080
	s_addc_u32 s23, s23, 0
	s_add_u32 s46, s24, 0x100
	s_addc_u32 s47, s25, 0
	s_mov_b32 s48, -2
	s_waitcnt lgkmcnt(0)
	ds_read_b128 v[128:131], v190
	ds_read_b128 v[132:135], v190 offset:1024
	ds_read_b128 v[136:139], v190 offset:2048
	ds_read_b128 v[140:143], v190 offset:3072
	s_add_u32 s24, s22, 0xfff00080
	s_addc_u32 s25, s23, -1
	s_cmp_eq_u32 s48, 60
	s_cselect_b32 s27, s17, s25
	s_cselect_b32 s26, s44, s24
	s_cselect_b32 s25, s15, s47
	s_cselect_b32 s24, s45, s46
	v_lshl_add_u64 v[186:187], s[22:23], 0, v[162:163]
	s_add_i32 m0, s7, 0xc000
	ds_read_b128 v[144:147], v191
	ds_read_b128 v[148:151], v191 offset:1024
	ds_read_b128 v[170:173], v191 offset:2048
	ds_read_b128 v[174:177], v191 offset:3072
	ds_read_b128 v[178:181], v191 offset:4096
	ds_read_b128 v[182:185], v191 offset:5120
	ds_read_b128 v[194:197], v191 offset:6144
	ds_read_b128 v[198:201], v191 offset:7168
	global_load_lds_dwordx4 v[186:187], off
	v_lshl_add_u64 v[186:187], s[22:23], 0, v[164:165]
	s_add_i32 m0, s7, 0xe000
	s_nop 0
	global_load_lds_dwordx4 v[186:187], off
	s_waitcnt lgkmcnt(8)
	s_barrier
	s_waitcnt lgkmcnt(0)
	s_setprio 1
	s_waitcnt lgkmcnt(0)
	v_mfma_f32_16x16x32_bf16 v[124:127], v[128:131], v[144:147], 0
	v_mfma_f32_16x16x32_bf16 v[120:123], v[136:139], v[144:147], 0
	v_mfma_f32_16x16x32_bf16 v[108:111], v[128:131], v[170:173], 0
	v_mfma_f32_16x16x32_bf16 v[104:107], v[136:139], v[170:173], 0
	v_mfma_f32_16x16x32_bf16 v[92:95], v[128:131], v[178:181], 0
	v_mfma_f32_16x16x32_bf16 v[88:91], v[136:139], v[178:181], 0
	v_mfma_f32_16x16x32_bf16 v[76:79], v[128:131], v[194:197], 0
	v_mfma_f32_16x16x32_bf16 v[72:75], v[136:139], v[194:197], 0
	v_mfma_f32_16x16x32_bf16 v[124:127], v[132:135], v[148:151], v[124:127]
	v_mfma_f32_16x16x32_bf16 v[120:123], v[140:143], v[148:151], v[120:123]
	v_mfma_f32_16x16x32_bf16 v[108:111], v[132:135], v[174:177], v[108:111]
	v_mfma_f32_16x16x32_bf16 v[104:107], v[140:143], v[174:177], v[104:107]
	v_mfma_f32_16x16x32_bf16 v[92:95], v[132:135], v[182:185], v[92:95]
	v_mfma_f32_16x16x32_bf16 v[88:91], v[140:143], v[182:185], v[88:91]
	v_mfma_f32_16x16x32_bf16 v[76:79], v[132:135], v[198:201], v[76:79]
	v_mfma_f32_16x16x32_bf16 v[72:75], v[140:143], v[198:201], v[72:75]
	s_setprio 0
	s_barrier
	s_add_i32 s49, s42, s31
	v_lshl_add_u64 v[186:187], s[24:25], 0, v[156:157]
	s_mov_b32 m0, s49
	ds_read_b128 v[202:205], v192
	ds_read_b128 v[206:209], v192 offset:1024
	ds_read_b128 v[210:213], v192 offset:2048
	ds_read_b128 v[214:217], v192 offset:3072
	global_load_lds_dwordx4 v[186:187], off
	v_lshl_add_u64 v[218:219], s[24:25], 0, v[160:161]
	s_add_i32 m0, s49, 0x2000
	s_nop 0
	global_load_lds_dwordx4 v[218:219], off
	s_barrier
	s_waitcnt lgkmcnt(0)
	s_setprio 1
	s_waitcnt lgkmcnt(0)
	v_mfma_f32_16x16x32_bf16 v[116:119], v[202:205], v[144:147], 0
	v_mfma_f32_16x16x32_bf16 v[112:115], v[210:213], v[144:147], 0
	v_mfma_f32_16x16x32_bf16 v[100:103], v[202:205], v[170:173], 0
	v_mfma_f32_16x16x32_bf16 v[96:99], v[210:213], v[170:173], 0
	v_mfma_f32_16x16x32_bf16 v[84:87], v[202:205], v[178:181], 0
	v_mfma_f32_16x16x32_bf16 v[80:83], v[210:213], v[178:181], 0
	v_mfma_f32_16x16x32_bf16 v[68:71], v[202:205], v[194:197], 0
	v_mfma_f32_16x16x32_bf16 v[64:67], v[210:213], v[194:197], 0
	v_mfma_f32_16x16x32_bf16 v[116:119], v[206:209], v[148:151], v[116:119]
	v_mfma_f32_16x16x32_bf16 v[112:115], v[214:217], v[148:151], v[112:115]
	v_mfma_f32_16x16x32_bf16 v[100:103], v[206:209], v[174:177], v[100:103]
	v_mfma_f32_16x16x32_bf16 v[96:99], v[214:217], v[174:177], v[96:99]
	v_mfma_f32_16x16x32_bf16 v[84:87], v[206:209], v[182:185], v[84:87]
	v_mfma_f32_16x16x32_bf16 v[80:83], v[214:217], v[182:185], v[80:83]
	v_mfma_f32_16x16x32_bf16 v[68:71], v[206:209], v[198:201], v[68:71]
	v_mfma_f32_16x16x32_bf16 v[64:67], v[214:217], v[198:201], v[64:67]
	s_setprio 0
	s_mov_b32 m0, s7
	v_lshl_add_u64 v[220:221], s[26:27], 0, v[154:155]
	s_barrier
	ds_read_b128 v[144:147], v191 offset:16384
	ds_read_b128 v[148:151], v191 offset:17408
	ds_read_b128 v[170:173], v191 offset:18432
	ds_read_b128 v[174:177], v191 offset:19456
	ds_read_b128 v[178:181], v191 offset:20480
	ds_read_b128 v[182:185], v191 offset:21504
	ds_read_b128 v[194:197], v191 offset:22528
	ds_read_b128 v[198:201], v191 offset:23552
	global_load_lds_dwordx4 v[220:221], off
	v_lshl_add_u64 v[222:223], s[26:27], 0, v[158:159]
	s_mov_b32 m0, s34
	s_nop 0
	global_load_lds_dwordx4 v[222:223], off
	s_barrier
	s_waitcnt lgkmcnt(0)
	s_setprio 1
	s_waitcnt lgkmcnt(0)
	v_mfma_f32_16x16x32_bf16 v[60:63], v[128:131], v[144:147], 0
	v_mfma_f32_16x16x32_bf16 v[56:59], v[136:139], v[144:147], 0
	v_mfma_f32_16x16x32_bf16 v[44:47], v[128:131], v[170:173], 0
	v_mfma_f32_16x16x32_bf16 v[40:43], v[136:139], v[170:173], 0
	v_mfma_f32_16x16x32_bf16 v[28:31], v[128:131], v[178:181], 0
	v_mfma_f32_16x16x32_bf16 v[24:27], v[136:139], v[178:181], 0
	v_mfma_f32_16x16x32_bf16 v[12:15], v[128:131], v[194:197], 0
	v_mfma_f32_16x16x32_bf16 v[8:11], v[136:139], v[194:197], 0
	v_mfma_f32_16x16x32_bf16 v[60:63], v[132:135], v[148:151], v[60:63]
	v_mfma_f32_16x16x32_bf16 v[56:59], v[140:143], v[148:151], v[56:59]
	v_mfma_f32_16x16x32_bf16 v[44:47], v[132:135], v[174:177], v[44:47]
	v_mfma_f32_16x16x32_bf16 v[40:43], v[140:143], v[174:177], v[40:43]
	v_mfma_f32_16x16x32_bf16 v[28:31], v[132:135], v[182:185], v[28:31]
	v_mfma_f32_16x16x32_bf16 v[24:27], v[140:143], v[182:185], v[24:27]
	v_mfma_f32_16x16x32_bf16 v[12:15], v[132:135], v[198:201], v[12:15]
	v_mfma_f32_16x16x32_bf16 v[8:11], v[140:143], v[198:201], v[8:11]
	s_setprio 0
	s_barrier
; #define PG8_STAGE(bufoff, gbase, voff) do { _Pragma("unroll") for (int _i = 0; _i < 2; ++_i) \
;         __builtin_amdgcn_global_load_lds((const unsigned*)((const char*)(gbase) + (voff)[_i]), (LAS unsigned*)(lds + (bufoff) + ldsw + _i * 8192), 16, 0, 0); } while (0)
; #define PG8_LDA(dst, b, h) do { _Pragma("unroll") for (int m = 0; m < 4; ++m) _Pragma("unroll") for (int k = 0; k < 2; ++k) dst[m][k] = *(const LAS bf16x8*)(lds + PG8_SA(b, h) + aoff + m * 2048 + k * 1024); } while (0)
; #define PG8_LDB(dst, b, h) do { _Pragma("unroll") for (int n = 0; n < 2; ++n) _Pragma("unroll") for (int k = 0; k < 2; ++k) dst[n][k] = *(const LAS bf16x8*)(lds + PG8_SB(b, h) + boff + n * 2048 + k * 1024); } while (0)
; #define PG8_MMA(ai, bj, At, Bt) do { __builtin_amdgcn_s_setprio(1); _Pragma("unroll") for (int m = 0; m < 4; ++m) _Pragma("unroll") for (int n = 0; n < 2; ++n) _Pragma("unroll") for (int k = 0; k < 2; ++k) \
;         acc[ai][bj][m][n] = __builtin_amdgcn_mfma_f32_16x16x32_bf16(Bt[n][k], At[m][k], acc[ai][bj][m][n], 0, 0, 0); __builtin_amdgcn_s_setprio(0); } while (0)
; #define PG8_WAIT_V(n) asm volatile("s_waitcnt vmcnt(" #n ")" ::: "memory")
; #define PG8_WAIT_L(n) asm volatile("s_waitcnt lgkmcnt(" #n ")" ::: "memory")
; #define PG8_BAR __builtin_amdgcn_s_barrier()
; #define PG8_SCHED __builtin_amdgcn_sched_barrier(0)
; template <class Epi>
; __device__ __forceinline__ void gemm_phase(LAS unsigned char* lds, const Gemm g, const StaticOrder& S, const Epi& E) {
;     ...
;             PG8_STAGE(PG8_SB(0, 1), b2 + hstepB, voffB);
;             PG8_WAIT_V(6); PG8_BAR; PG8_MMA(1, 1, At, B1); PG8_BAR;
;             PG8_LDB(B0, 1, 0); PG8_SCHED; PG8_LDA(At, 1, 0); PG8_STAGE(PG8_SA(0, 1), a2 + hstepA, voffA);
;             PG8_WAIT_L(8); PG8_BAR; PG8_WAIT_L(0); PG8_MMA(0, 0, At, B0); PG8_BAR; PG8_SCHED;
;             PG8_LDB(B1, 1, 1); PG8_STAGE(PG8_SB(1, 0), b3, voffB);
;             PG8_BAR; PG8_WAIT_L(0); PG8_MMA(0, 1, At, B1); PG8_BAR;
;             PG8_LDA(At, 1, 1); PG8_STAGE(PG8_SA(1, 0), a3, voffA);
	s_add_u32 s50, s24, 0x100000
	s_addc_u32 s51, s25, 0
	s_add_i32 s49, s43, s31
	v_lshl_add_u64 v[128:129], s[50:51], 0, v[156:157]
	s_mov_b32 m0, s49
	s_nop 0
	global_load_lds_dwordx4 v[128:129], off
	v_lshl_add_u64 v[128:129], s[50:51], 0, v[160:161]
	s_add_i32 m0, s49, 0x2000
	s_nop 0
	global_load_lds_dwordx4 v[128:129], off
	s_waitcnt vmcnt(6)
	s_barrier
	s_setprio 1
	v_mfma_f32_16x16x32_bf16 v[52:55], v[202:205], v[144:147], 0
	v_mfma_f32_16x16x32_bf16 v[48:51], v[210:213], v[144:147], 0
	v_mfma_f32_16x16x32_bf16 v[36:39], v[202:205], v[170:173], 0
	v_mfma_f32_16x16x32_bf16 v[32:35], v[210:213], v[170:173], 0
	v_mfma_f32_16x16x32_bf16 v[20:23], v[202:205], v[178:181], 0
	v_mfma_f32_16x16x32_bf16 v[16:19], v[210:213], v[178:181], 0
	v_mfma_f32_16x16x32_bf16 v[4:7], v[202:205], v[194:197], 0
	v_mfma_f32_16x16x32_bf16 v[0:3], v[210:213], v[194:197], 0
	v_mfma_f32_16x16x32_bf16 v[52:55], v[206:209], v[148:151], v[52:55]
	v_mfma_f32_16x16x32_bf16 v[48:51], v[214:217], v[148:151], v[48:51]
	v_mfma_f32_16x16x32_bf16 v[36:39], v[206:209], v[174:177], v[36:39]
	v_mfma_f32_16x16x32_bf16 v[32:35], v[214:217], v[174:177], v[32:35]
	v_mfma_f32_16x16x32_bf16 v[20:23], v[206:209], v[182:185], v[20:23]
	v_mfma_f32_16x16x32_bf16 v[16:19], v[214:217], v[182:185], v[16:19]
	v_mfma_f32_16x16x32_bf16 v[4:7], v[206:209], v[198:201], v[4:7]
	v_mfma_f32_16x16x32_bf16 v[0:3], v[214:217], v[198:201], v[0:3]
	s_setprio 0
	s_add_i32 s49, 0, 0x18000
	v_add_u32_e32 v140, s49, v188
	s_barrier
	ds_read_b128 v[128:131], v140
	ds_read_b128 v[132:135], v140 offset:1024
	ds_read_b128 v[136:139], v140 offset:2048
	ds_read_b128 v[140:143], v140 offset:3072
	s_add_u32 s26, s26, 0x100000
	s_addc_u32 s27, s27, 0
	s_mov_b32 m0, s35
	v_lshl_add_u64 v[202:203], s[26:27], 0, v[154:155]
	ds_read_b128 v[144:147], v191 offset:32768
	ds_read_b128 v[148:151], v191 offset:33792
	ds_read_b128 v[170:173], v191 offset:34816
	ds_read_b128 v[174:177], v191 offset:35840
	ds_read_b128 v[178:181], v191 offset:36864
	ds_read_b128 v[182:185], v191 offset:37888
	ds_read_b128 v[194:197], v191 offset:38912
	ds_read_b128 v[198:201], v191 offset:39936
	global_load_lds_dwordx4 v[202:203], off
	v_lshl_add_u64 v[202:203], s[26:27], 0, v[158:159]
	s_mov_b32 m0, s36
	s_nop 0
	global_load_lds_dwordx4 v[202:203], off
	s_waitcnt lgkmcnt(8)
	s_barrier
	s_waitcnt lgkmcnt(0)
	s_setprio 1
	s_waitcnt lgkmcnt(0)
	v_mfma_f32_16x16x32_bf16 v[124:127], v[128:131], v[144:147], v[124:127]
	v_mfma_f32_16x16x32_bf16 v[120:123], v[136:139], v[144:147], v[120:123]
	v_mfma_f32_16x16x32_bf16 v[108:111], v[128:131], v[170:173], v[108:111]
	v_mfma_f32_16x16x32_bf16 v[104:107], v[136:139], v[170:173], v[104:107]
	v_mfma_f32_16x16x32_bf16 v[92:95], v[128:131], v[178:181], v[92:95]
	v_mfma_f32_16x16x32_bf16 v[88:91], v[136:139], v[178:181], v[88:91]
	v_mfma_f32_16x16x32_bf16 v[76:79], v[128:131], v[194:197], v[76:79]
	v_mfma_f32_16x16x32_bf16 v[72:75], v[136:139], v[194:197], v[72:75]
	v_mfma_f32_16x16x32_bf16 v[124:127], v[132:135], v[148:151], v[124:127]
	v_mfma_f32_16x16x32_bf16 v[120:123], v[140:143], v[148:151], v[120:123]
	v_mfma_f32_16x16x32_bf16 v[108:111], v[132:135], v[174:177], v[108:111]
	v_mfma_f32_16x16x32_bf16 v[104:107], v[140:143], v[174:177], v[104:107]
	v_mfma_f32_16x16x32_bf16 v[92:95], v[132:135], v[182:185], v[92:95]
	v_mfma_f32_16x16x32_bf16 v[88:91], v[140:143], v[182:185], v[88:91]
	v_mfma_f32_16x16x32_bf16 v[76:79], v[132:135], v[198:201], v[76:79]
	v_mfma_f32_16x16x32_bf16 v[72:75], v[140:143], v[198:201], v[72:75]
	s_setprio 0
	s_barrier
	s_add_i32 s26, 0, 0x1c000
	s_add_i32 s27, s49, s31
	v_add_u32_e32 v214, s26, v188
	v_lshl_add_u64 v[186:187], v[186:187], 0, s[12:13]
	s_mov_b32 m0, s27
	ds_read_b128 v[202:205], v214
	ds_read_b128 v[206:209], v214 offset:1024
	ds_read_b128 v[210:213], v214 offset:2048
	ds_read_b128 v[214:217], v214 offset:3072
	global_load_lds_dwordx4 v[186:187], off
	v_lshl_add_u64 v[186:187], v[218:219], 0, s[12:13]
	s_add_i32 m0, s27, 0x2000
	s_nop 0
	global_load_lds_dwordx4 v[186:187], off
	s_barrier
; #define PG8_STAGE(bufoff, gbase, voff) do { _Pragma("unroll") for (int _i = 0; _i < 2; ++_i) \
;         __builtin_amdgcn_global_load_lds((const unsigned*)((const char*)(gbase) + (voff)[_i]), (LAS unsigned*)(lds + (bufoff) + ldsw + _i * 8192), 16, 0, 0); } while (0)
; #define PG8_LDA(dst, b, h) do { _Pragma("unroll") for (int m = 0; m < 4; ++m) _Pragma("unroll") for (int k = 0; k < 2; ++k) dst[m][k] = *(const LAS bf16x8*)(lds + PG8_SA(b, h) + aoff + m * 2048 + k * 1024); } while (0)
; #define PG8_MMA(ai, bj, At, Bt) do { __builtin_amdgcn_s_setprio(1); _Pragma("unroll") for (int m = 0; m < 4; ++m) _Pragma("unroll") for (int n = 0; n < 2; ++n) _Pragma("unroll") for (int k = 0; k < 2; ++k) \
;         acc[ai][bj][m][n] = __builtin_amdgcn_mfma_f32_16x16x32_bf16(Bt[n][k], At[m][k], acc[ai][bj][m][n], 0, 0, 0); __builtin_amdgcn_s_setprio(0); } while (0)
; #define PG8_WAIT_V(n) asm volatile("s_waitcnt vmcnt(" #n ")" ::: "memory")
; #define PG8_WAIT_L(n) asm volatile("s_waitcnt lgkmcnt(" #n ")" ::: "memory")
; #define PG8_BAR __builtin_amdgcn_s_barrier()
; #define PG8_SCHED __builtin_amdgcn_sched_barrier(0)
; template <class Epi>
; __device__ __forceinline__ void gemm_phase(LAS unsigned char* lds, const Gemm g, const StaticOrder& S, const Epi& E) {
;     ...
;             PG8_BAR; PG8_WAIT_L(0); PG8_MMA(0, 1, At, B1); PG8_BAR;
;             PG8_LDA(At, 1, 1); PG8_STAGE(PG8_SA(1, 0), a3, voffA);
;             PG8_BAR; PG8_WAIT_L(0); PG8_MMA(1, 0, At, B0); PG8_BAR; PG8_SCHED;
;             PG8_STAGE(PG8_SB(1, 1), b3 + hstepB, voffB);
;             PG8_WAIT_V(6); PG8_BAR; PG8_MMA(1, 1, At, B1); PG8_BAR;
;         }
	s_waitcnt lgkmcnt(0)
	s_setprio 1
	s_waitcnt lgkmcnt(0)
	v_mfma_f32_16x16x32_bf16 v[116:119], v[202:205], v[144:147], v[116:119]
	v_mfma_f32_16x16x32_bf16 v[112:115], v[210:213], v[144:147], v[112:115]
	v_mfma_f32_16x16x32_bf16 v[100:103], v[202:205], v[170:173], v[100:103]
	v_mfma_f32_16x16x32_bf16 v[96:99], v[210:213], v[170:173], v[96:99]
	v_mfma_f32_16x16x32_bf16 v[84:87], v[202:205], v[178:181], v[84:87]
	v_mfma_f32_16x16x32_bf16 v[80:83], v[210:213], v[178:181], v[80:83]
	v_mfma_f32_16x16x32_bf16 v[68:71], v[202:205], v[194:197], v[68:71]
	v_mfma_f32_16x16x32_bf16 v[64:67], v[210:213], v[194:197], v[64:67]
	v_mfma_f32_16x16x32_bf16 v[116:119], v[206:209], v[148:151], v[116:119]
	v_mfma_f32_16x16x32_bf16 v[112:115], v[214:217], v[148:151], v[112:115]
	v_mfma_f32_16x16x32_bf16 v[100:103], v[206:209], v[174:177], v[100:103]
	v_mfma_f32_16x16x32_bf16 v[96:99], v[214:217], v[174:177], v[96:99]
	v_mfma_f32_16x16x32_bf16 v[84:87], v[206:209], v[182:185], v[84:87]
	v_mfma_f32_16x16x32_bf16 v[80:83], v[214:217], v[182:185], v[80:83]
	v_mfma_f32_16x16x32_bf16 v[68:71], v[206:209], v[198:201], v[68:71]
	v_mfma_f32_16x16x32_bf16 v[64:67], v[214:217], v[198:201], v[64:67]
	s_setprio 0
	s_mov_b32 m0, s38
	v_lshl_add_u64 v[186:187], v[220:221], 0, s[12:13]
	s_barrier
	ds_read_b128 v[144:147], v191 offset:49152
	ds_read_b128 v[148:151], v191 offset:50176
	ds_read_b128 v[170:173], v191 offset:51200
	ds_read_b128 v[174:177], v191 offset:52224
	ds_read_b128 v[178:181], v191 offset:53248
	ds_read_b128 v[182:185], v191 offset:54272
	ds_read_b128 v[194:197], v191 offset:55296
	ds_read_b128 v[198:201], v191 offset:56320
	global_load_lds_dwordx4 v[186:187], off
	v_lshl_add_u64 v[186:187], v[222:223], 0, s[12:13]
	s_mov_b32 m0, s39
	s_nop 0
	global_load_lds_dwordx4 v[186:187], off
	s_barrier
	s_waitcnt lgkmcnt(0)
	s_setprio 1
	s_waitcnt lgkmcnt(0)
	v_mfma_f32_16x16x32_bf16 v[60:63], v[128:131], v[144:147], v[60:63]
	v_mfma_f32_16x16x32_bf16 v[56:59], v[136:139], v[144:147], v[56:59]
	v_mfma_f32_16x16x32_bf16 v[44:47], v[128:131], v[170:173], v[44:47]
	v_mfma_f32_16x16x32_bf16 v[40:43], v[136:139], v[170:173], v[40:43]
	v_mfma_f32_16x16x32_bf16 v[28:31], v[128:131], v[178:181], v[28:31]
	v_mfma_f32_16x16x32_bf16 v[24:27], v[136:139], v[178:181], v[24:27]
	v_mfma_f32_16x16x32_bf16 v[12:15], v[128:131], v[194:197], v[12:15]
	v_mfma_f32_16x16x32_bf16 v[8:11], v[136:139], v[194:197], v[8:11]
	v_mfma_f32_16x16x32_bf16 v[60:63], v[132:135], v[148:151], v[60:63]
	v_mfma_f32_16x16x32_bf16 v[56:59], v[140:143], v[148:151], v[56:59]
	v_mfma_f32_16x16x32_bf16 v[44:47], v[132:135], v[174:177], v[44:47]
	v_mfma_f32_16x16x32_bf16 v[40:43], v[140:143], v[174:177], v[40:43]
	v_mfma_f32_16x16x32_bf16 v[28:31], v[132:135], v[182:185], v[28:31]
	v_mfma_f32_16x16x32_bf16 v[24:27], v[140:143], v[182:185], v[24:27]
	v_mfma_f32_16x16x32_bf16 v[12:15], v[132:135], v[198:201], v[12:15]
	v_mfma_f32_16x16x32_bf16 v[8:11], v[140:143], v[198:201], v[8:11]
	s_setprio 0
	s_barrier
	s_add_u32 s24, s24, 0x100080
	s_addc_u32 s25, s25, 0
	s_add_i32 s26, s26, s31
	v_lshl_add_u64 v[128:129], s[24:25], 0, v[156:157]
	s_mov_b32 m0, s26
	s_nop 0
	global_load_lds_dwordx4 v[128:129], off
	v_lshl_add_u64 v[128:129], s[24:25], 0, v[160:161]
	s_add_i32 m0, s26, 0x2000
	s_nop 0
	global_load_lds_dwordx4 v[128:129], off
	s_waitcnt vmcnt(6)
	s_barrier
	s_setprio 1
	v_mfma_f32_16x16x32_bf16 v[52:55], v[202:205], v[144:147], v[52:55]
	v_mfma_f32_16x16x32_bf16 v[48:51], v[210:213], v[144:147], v[48:51]
	v_mfma_f32_16x16x32_bf16 v[36:39], v[202:205], v[170:173], v[36:39]
	v_mfma_f32_16x16x32_bf16 v[32:35], v[210:213], v[170:173], v[32:35]
	v_mfma_f32_16x16x32_bf16 v[20:23], v[202:205], v[178:181], v[20:23]
	v_mfma_f32_16x16x32_bf16 v[16:19], v[210:213], v[178:181], v[16:19]
	v_mfma_f32_16x16x32_bf16 v[4:7], v[202:205], v[194:197], v[4:7]
	v_mfma_f32_16x16x32_bf16 v[0:3], v[210:213], v[194:197], v[0:3]
	v_mfma_f32_16x16x32_bf16 v[52:55], v[206:209], v[148:151], v[52:55]
	v_mfma_f32_16x16x32_bf16 v[48:51], v[214:217], v[148:151], v[48:51]
	v_mfma_f32_16x16x32_bf16 v[36:39], v[206:209], v[174:177], v[36:39]
	v_mfma_f32_16x16x32_bf16 v[32:35], v[214:217], v[174:177], v[32:35]
	v_mfma_f32_16x16x32_bf16 v[20:23], v[206:209], v[182:185], v[20:23]
	v_mfma_f32_16x16x32_bf16 v[16:19], v[214:217], v[182:185], v[16:19]
	v_mfma_f32_16x16x32_bf16 v[4:7], v[206:209], v[198:201], v[4:7]
	v_mfma_f32_16x16x32_bf16 v[0:3], v[214:217], v[198:201], v[0:3]
	s_setprio 0
	s_add_i32 s48, s48, 2
	s_add_u32 s22, s22, 0x100
	s_addc_u32 s23, s23, 0
	s_add_u32 s46, s46, 0x100
	s_addc_u32 s47, s47, 0
	s_cmp_gt_u32 s48, 61
	s_barrier
